# v028 + loader-side vmcnt(8) and lgkmcnt(0) asm waits merged into one s_waitcnt in the GEMM K-loops
# baseline (speedup 1.0000x reference)
; #define PG8_STAGE(bufoff, gbase, voff) do { _Pragma("unroll") for (int _i = 0; _i < 2; ++_i) \
;         __builtin_amdgcn_global_load_lds((const unsigned*)((const char*)(gbase) + (voff)[_i]), (LAS unsigned*)(lds + (bufoff) + ldsw + _i * 8192), 16, 0, 0); } while (0)
; #define PG8_LDA(dst, b, h) do { _Pragma("unroll") for (int m = 0; m < 4; ++m) _Pragma("unroll") for (int k = 0; k < 2; ++k) dst[m][k] = *(const LAS bf16x8*)(lds + PG8_SA(b, h) + aoff + m * 2048 + k * 1024); } while (0)
; #define PG8_LDB(dst, b, h) do { _Pragma("unroll") for (int n = 0; n < 2; ++n) _Pragma("unroll") for (int k = 0; k < 2; ++k) dst[n][k] = *(const LAS bf16x8*)(lds + PG8_SB(b, h) + boff + n * 2048 + k * 1024); } while (0)
; #define PG8_MMA(ai, bj, At, Bt) do { __builtin_amdgcn_s_setprio(1); _Pragma("unroll") for (int m = 0; m < 4; ++m) _Pragma("unroll") for (int n = 0; n < 2; ++n) _Pragma("unroll") for (int k = 0; k < 2; ++k) \
;         acc[ai][bj][m][n] = __builtin_amdgcn_mfma_f32_16x16x32_bf16(Bt[n][k], At[m][k], acc[ai][bj][m][n], 0, 0, 0); __builtin_amdgcn_s_setprio(0); } while (0)
; #define PG8_WAIT_V(n) asm volatile("s_waitcnt vmcnt(" #n ")" ::: "memory")
; #define PG8_WAIT_L(n) asm volatile("s_waitcnt lgkmcnt(" #n ")" ::: "memory")
; #define PG8_BAR __builtin_amdgcn_s_barrier()
; #define PG8_SCHED __builtin_amdgcn_sched_barrier(0)
; template <class Epi, class Sched>
; DI void gemm_phase(LAS unsigned char* lds, const Gemm g, const Sched& S, const Epi& E) {
;     ...
;             const bool last = (t == nt - 2);
;             const char* a1 = cA + (size_t)(t + 1) * kstep;
;             const char* a2 = last ? nA : cA + (size_t)(t + 2) * kstep; const char* b2 = last ? nB : cB + (size_t)(t + 2) * kstep;
;             const char* a3 = a2 + kstep; const char* b3 = b2 + kstep;
;             PG8_LDB(B0, 0, 0); PG8_LDB(B1, 0, 1); PG8_SCHED; PG8_LDA(At, 0, 0); PG8_STAGE(PG8_SA(1, 1), a1 + hstepA, voffA);
;             PG8_WAIT_V(8); PG8_WAIT_L(0); PG8_BAR; PG8_MMA(0, 0, At, B0); PG8_MMA(0, 1, At, B1); PG8_BAR; PG8_SCHED;
;             PG8_LDA(At, 0, 1); PG8_STAGE(PG8_SB(0, 0), b2, voffB); PG8_STAGE(PG8_SB(0, 1), b2 + hstepB, voffB); PG8_STAGE(PG8_SA(0, 0), a2, voffA);
;             PG8_WAIT_V(8); PG8_WAIT_L(0); PG8_BAR; PG8_MMA(1, 0, At, B0); PG8_MMA(1, 1, At, B1); PG8_BAR; PG8_SCHED;
.LBB0_179:
	ds_read_b128 v[168:171], v162
	ds_read_b128 v[172:175], v162 offset:1024
	ds_read_b128 v[176:179], v162 offset:2048
	ds_read_b128 v[180:183], v162 offset:3072
	ds_read_b128 v[186:189], v163
	ds_read_b128 v[190:193], v163 offset:1024
	ds_read_b128 v[194:197], v163 offset:2048
	ds_read_b128 v[198:201], v163 offset:3072
	s_add_u32 s42, s40, 0xfffc0080
	s_addc_u32 s43, s41, -1
	s_cmp_eq_u32 s65, 12
	s_cselect_b32 s45, s35, s43
	s_cselect_b32 s44, s61, s42
	s_cselect_b32 s43, s21, s64
	s_cselect_b32 s42, s62, s63
	v_lshl_add_u64 v[234:235], s[40:41], 0, v[138:139]
	s_add_i32 m0, s49, 0xc000
	ds_read_b128 v[202:205], v160
	ds_read_b128 v[206:209], v160 offset:1024
	ds_read_b128 v[210:213], v160 offset:2048
	ds_read_b128 v[214:217], v160 offset:3072
	ds_read_b128 v[218:221], v160 offset:4096
	ds_read_b128 v[222:225], v160 offset:5120
	ds_read_b128 v[226:229], v160 offset:6144
	ds_read_b128 v[230:233], v160 offset:7168
	global_load_lds_dwordx4 v[234:235], off
	v_lshl_add_u64 v[234:235], s[40:41], 0, v[140:141]
	s_add_i32 m0, s49, 0xe000
	s_nop 0
	global_load_lds_dwordx4 v[234:235], off
	s_waitcnt vmcnt(8) lgkmcnt(0)
	s_barrier
	s_setprio 1
	v_mfma_f32_16x16x32_bf16 v[126:129], v[168:171], v[202:205], v[126:129]
	v_mfma_f32_16x16x32_bf16 v[118:121], v[176:179], v[202:205], v[118:121]
	v_mfma_f32_16x16x32_bf16 v[110:113], v[168:171], v[210:213], v[110:113]
	v_mfma_f32_16x16x32_bf16 v[102:105], v[176:179], v[210:213], v[102:105]
	v_mfma_f32_16x16x32_bf16 v[94:97], v[168:171], v[218:221], v[94:97]
	v_mfma_f32_16x16x32_bf16 v[86:89], v[176:179], v[218:221], v[86:89]
	v_mfma_f32_16x16x32_bf16 v[78:81], v[168:171], v[226:229], v[78:81]
	v_mfma_f32_16x16x32_bf16 v[70:73], v[176:179], v[226:229], v[70:73]
	v_mfma_f32_16x16x32_bf16 v[126:129], v[172:175], v[206:209], v[126:129]
	v_mfma_f32_16x16x32_bf16 v[118:121], v[180:183], v[206:209], v[118:121]
	v_mfma_f32_16x16x32_bf16 v[110:113], v[172:175], v[214:217], v[110:113]
	v_mfma_f32_16x16x32_bf16 v[102:105], v[180:183], v[214:217], v[102:105]
	v_mfma_f32_16x16x32_bf16 v[94:97], v[172:175], v[222:225], v[94:97]
	v_mfma_f32_16x16x32_bf16 v[86:89], v[180:183], v[222:225], v[86:89]
	v_mfma_f32_16x16x32_bf16 v[78:81], v[172:175], v[230:233], v[78:81]
	v_mfma_f32_16x16x32_bf16 v[70:73], v[180:183], v[230:233], v[70:73]
	v_mfma_f32_16x16x32_bf16 v[122:125], v[186:189], v[202:205], v[122:125]
	v_mfma_f32_16x16x32_bf16 v[114:117], v[194:197], v[202:205], v[114:117]
	v_mfma_f32_16x16x32_bf16 v[106:109], v[186:189], v[210:213], v[106:109]
	v_mfma_f32_16x16x32_bf16 v[98:101], v[194:197], v[210:213], v[98:101]
	v_mfma_f32_16x16x32_bf16 v[90:93], v[186:189], v[218:221], v[90:93]
	v_mfma_f32_16x16x32_bf16 v[82:85], v[194:197], v[218:221], v[82:85]
	v_mfma_f32_16x16x32_bf16 v[74:77], v[186:189], v[226:229], v[74:77]
	v_mfma_f32_16x16x32_bf16 v[66:69], v[194:197], v[226:229], v[66:69]
	v_mfma_f32_16x16x32_bf16 v[122:125], v[190:193], v[206:209], v[122:125]
	v_mfma_f32_16x16x32_bf16 v[114:117], v[198:201], v[206:209], v[114:117]
	v_mfma_f32_16x16x32_bf16 v[106:109], v[190:193], v[214:217], v[106:109]
	v_mfma_f32_16x16x32_bf16 v[98:101], v[198:201], v[214:217], v[98:101]
	v_mfma_f32_16x16x32_bf16 v[90:93], v[190:193], v[222:225], v[90:93]
	v_mfma_f32_16x16x32_bf16 v[82:85], v[198:201], v[222:225], v[82:85]
	v_mfma_f32_16x16x32_bf16 v[74:77], v[190:193], v[230:233], v[74:77]
	v_mfma_f32_16x16x32_bf16 v[66:69], v[198:201], v[230:233], v[66:69]
	s_setprio 0
	s_barrier
	s_add_i32 s66, s57, s46
	v_lshl_add_u64 v[234:235], s[42:43], 0, v[134:135]
	s_mov_b32 m0, s66
	ds_read_b128 v[202:205], v160 offset:16384
	ds_read_b128 v[206:209], v160 offset:17408
	ds_read_b128 v[210:213], v160 offset:18432
	ds_read_b128 v[214:217], v160 offset:19456
	ds_read_b128 v[218:221], v160 offset:20480
	ds_read_b128 v[222:225], v160 offset:21504
	ds_read_b128 v[226:229], v160 offset:22528
	ds_read_b128 v[230:233], v160 offset:23552
	global_load_lds_dwordx4 v[234:235], off
	s_add_i32 m0, s66, 0x2000
	s_add_u32 s66, s42, 0x40000
	v_lshl_add_u64 v[236:237], s[42:43], 0, v[130:131]
	s_addc_u32 s67, s43, 0
	s_add_i32 s68, s58, s46
	global_load_lds_dwordx4 v[236:237], off
	v_lshl_add_u64 v[238:239], s[66:67], 0, v[134:135]
	s_mov_b32 m0, s68
	v_lshl_add_u64 v[240:241], s[44:45], 0, v[132:133]
	global_load_lds_dwordx4 v[238:239], off
	v_lshl_add_u64 v[238:239], s[66:67], 0, v[130:131]
	s_add_i32 m0, s68, 0x2000
	s_nop 0
	global_load_lds_dwordx4 v[238:239], off
	v_lshl_add_u64 v[238:239], s[44:45], 0, v[136:137]
	s_mov_b32 m0, s49
	s_nop 0
	global_load_lds_dwordx4 v[238:239], off
	s_mov_b32 m0, s50
	s_nop 0
	global_load_lds_dwordx4 v[240:241], off
	s_waitcnt vmcnt(8) lgkmcnt(0)
	s_barrier
; #define PG8_STAGE(bufoff, gbase, voff) do { _Pragma("unroll") for (int _i = 0; _i < 2; ++_i) \
;         __builtin_amdgcn_global_load_lds((const unsigned*)((const char*)(gbase) + (voff)[_i]), (LAS unsigned*)(lds + (bufoff) + ldsw + _i * 8192), 16, 0, 0); } while (0)
; #define PG8_LDA(dst, b, h) do { _Pragma("unroll") for (int m = 0; m < 4; ++m) _Pragma("unroll") for (int k = 0; k < 2; ++k) dst[m][k] = *(const LAS bf16x8*)(lds + PG8_SA(b, h) + aoff + m * 2048 + k * 1024); } while (0)
; #define PG8_LDB(dst, b, h) do { _Pragma("unroll") for (int n = 0; n < 2; ++n) _Pragma("unroll") for (int k = 0; k < 2; ++k) dst[n][k] = *(const LAS bf16x8*)(lds + PG8_SB(b, h) + boff + n * 2048 + k * 1024); } while (0)
; #define PG8_MMA(ai, bj, At, Bt) do { __builtin_amdgcn_s_setprio(1); _Pragma("unroll") for (int m = 0; m < 4; ++m) _Pragma("unroll") for (int n = 0; n < 2; ++n) _Pragma("unroll") for (int k = 0; k < 2; ++k) \
;         acc[ai][bj][m][n] = __builtin_amdgcn_mfma_f32_16x16x32_bf16(Bt[n][k], At[m][k], acc[ai][bj][m][n], 0, 0, 0); __builtin_amdgcn_s_setprio(0); } while (0)
; #define PG8_WAIT_V(n) asm volatile("s_waitcnt vmcnt(" #n ")" ::: "memory")
; #define PG8_WAIT_L(n) asm volatile("s_waitcnt lgkmcnt(" #n ")" ::: "memory")
; #define PG8_BAR __builtin_amdgcn_s_barrier()
; #define PG8_SCHED __builtin_amdgcn_sched_barrier(0)
; template <class Epi, class Sched>
; DI void gemm_phase(LAS unsigned char* lds, const Gemm g, const Sched& S, const Epi& E) {
;     ...
;             PG8_WAIT_V(8); PG8_WAIT_L(0); PG8_BAR; PG8_MMA(1, 0, At, B0); PG8_MMA(1, 1, At, B1); PG8_BAR; PG8_SCHED;
;             PG8_LDB(B0, 1, 0); PG8_LDB(B1, 1, 1); PG8_SCHED; PG8_LDA(At, 1, 0); PG8_STAGE(PG8_SA(0, 1), a2 + hstepA, voffA);
;             PG8_WAIT_V(8); PG8_WAIT_L(0); PG8_BAR; PG8_MMA(0, 0, At, B0); PG8_MMA(0, 1, At, B1); PG8_BAR; PG8_SCHED;
	s_setprio 1
	v_mfma_f32_16x16x32_bf16 v[62:65], v[168:171], v[202:205], v[62:65]
	v_mfma_f32_16x16x32_bf16 v[54:57], v[176:179], v[202:205], v[54:57]
	v_mfma_f32_16x16x32_bf16 v[46:49], v[168:171], v[210:213], v[46:49]
	v_mfma_f32_16x16x32_bf16 v[38:41], v[176:179], v[210:213], v[38:41]
	v_mfma_f32_16x16x32_bf16 v[30:33], v[168:171], v[218:221], v[30:33]
	v_mfma_f32_16x16x32_bf16 v[22:25], v[176:179], v[218:221], v[22:25]
	v_mfma_f32_16x16x32_bf16 v[14:17], v[168:171], v[226:229], v[14:17]
	v_mfma_f32_16x16x32_bf16 v[6:9], v[176:179], v[226:229], v[6:9]
	v_mfma_f32_16x16x32_bf16 v[62:65], v[172:175], v[206:209], v[62:65]
	v_mfma_f32_16x16x32_bf16 v[54:57], v[180:183], v[206:209], v[54:57]
	v_mfma_f32_16x16x32_bf16 v[46:49], v[172:175], v[214:217], v[46:49]
	v_mfma_f32_16x16x32_bf16 v[38:41], v[180:183], v[214:217], v[38:41]
	v_mfma_f32_16x16x32_bf16 v[30:33], v[172:175], v[222:225], v[30:33]
	v_mfma_f32_16x16x32_bf16 v[22:25], v[180:183], v[222:225], v[22:25]
	v_mfma_f32_16x16x32_bf16 v[14:17], v[172:175], v[230:233], v[14:17]
	v_mfma_f32_16x16x32_bf16 v[6:9], v[180:183], v[230:233], v[6:9]
	v_mfma_f32_16x16x32_bf16 v[58:61], v[186:189], v[202:205], v[58:61]
	v_mfma_f32_16x16x32_bf16 v[50:53], v[194:197], v[202:205], v[50:53]
	v_mfma_f32_16x16x32_bf16 v[42:45], v[186:189], v[210:213], v[42:45]
	v_mfma_f32_16x16x32_bf16 v[34:37], v[194:197], v[210:213], v[34:37]
	v_mfma_f32_16x16x32_bf16 v[26:29], v[186:189], v[218:221], v[26:29]
	v_mfma_f32_16x16x32_bf16 v[18:21], v[194:197], v[218:221], v[18:21]
	v_mfma_f32_16x16x32_bf16 v[10:13], v[186:189], v[226:229], v[10:13]
	v_mfma_f32_16x16x32_bf16 v[2:5], v[194:197], v[226:229], v[2:5]
	v_mfma_f32_16x16x32_bf16 v[58:61], v[190:193], v[206:209], v[58:61]
	v_mfma_f32_16x16x32_bf16 v[50:53], v[198:201], v[206:209], v[50:53]
	v_mfma_f32_16x16x32_bf16 v[42:45], v[190:193], v[214:217], v[42:45]
	v_mfma_f32_16x16x32_bf16 v[34:37], v[198:201], v[214:217], v[34:37]
	v_mfma_f32_16x16x32_bf16 v[26:29], v[190:193], v[222:225], v[26:29]
	v_mfma_f32_16x16x32_bf16 v[18:21], v[198:201], v[222:225], v[18:21]
	v_mfma_f32_16x16x32_bf16 v[10:13], v[190:193], v[230:233], v[10:13]
	v_mfma_f32_16x16x32_bf16 v[2:5], v[198:201], v[230:233], v[2:5]
	s_setprio 0
	s_barrier
	s_add_i32 s66, 0, 0x18000
	v_add_u32_e32 v167, s66, v158
	s_add_i32 s67, 0, 0x1c000
	ds_read_b128 v[168:171], v167
	ds_read_b128 v[172:175], v167 offset:1024
	ds_read_b128 v[176:179], v167 offset:2048
	ds_read_b128 v[180:183], v167 offset:3072
	v_add_u32_e32 v167, s67, v158
	ds_read_b128 v[186:189], v167
	ds_read_b128 v[190:193], v167 offset:1024
	ds_read_b128 v[194:197], v167 offset:2048
	ds_read_b128 v[198:201], v167 offset:3072
	s_add_u32 s44, s44, 0x40000
	s_addc_u32 s45, s45, 0
	s_mov_b32 m0, s51
	v_lshl_add_u64 v[242:243], s[44:45], 0, v[136:137]
	ds_read_b128 v[202:205], v160 offset:32768
	ds_read_b128 v[206:209], v160 offset:33792
	ds_read_b128 v[210:213], v160 offset:34816
	ds_read_b128 v[214:217], v160 offset:35840
	ds_read_b128 v[218:221], v160 offset:36864
	ds_read_b128 v[222:225], v160 offset:37888
	ds_read_b128 v[226:229], v160 offset:38912
	ds_read_b128 v[230:233], v160 offset:39936
	global_load_lds_dwordx4 v[242:243], off
	v_lshl_add_u64 v[242:243], s[44:45], 0, v[132:133]
	s_mov_b32 m0, s52
	s_nop 0
	global_load_lds_dwordx4 v[242:243], off
	s_waitcnt vmcnt(8) lgkmcnt(0)
	s_barrier
	s_setprio 1
	v_mfma_f32_16x16x32_bf16 v[126:129], v[168:171], v[202:205], v[126:129]
	v_mfma_f32_16x16x32_bf16 v[118:121], v[176:179], v[202:205], v[118:121]
	v_mfma_f32_16x16x32_bf16 v[110:113], v[168:171], v[210:213], v[110:113]
	v_mfma_f32_16x16x32_bf16 v[102:105], v[176:179], v[210:213], v[102:105]
	v_mfma_f32_16x16x32_bf16 v[94:97], v[168:171], v[218:221], v[94:97]
	v_mfma_f32_16x16x32_bf16 v[86:89], v[176:179], v[218:221], v[86:89]
	v_mfma_f32_16x16x32_bf16 v[78:81], v[168:171], v[226:229], v[78:81]
	v_mfma_f32_16x16x32_bf16 v[70:73], v[176:179], v[226:229], v[70:73]
	v_mfma_f32_16x16x32_bf16 v[126:129], v[172:175], v[206:209], v[126:129]
	v_mfma_f32_16x16x32_bf16 v[118:121], v[180:183], v[206:209], v[118:121]
	v_mfma_f32_16x16x32_bf16 v[110:113], v[172:175], v[214:217], v[110:113]
	v_mfma_f32_16x16x32_bf16 v[102:105], v[180:183], v[214:217], v[102:105]
	v_mfma_f32_16x16x32_bf16 v[94:97], v[172:175], v[222:225], v[94:97]
	v_mfma_f32_16x16x32_bf16 v[86:89], v[180:183], v[222:225], v[86:89]
	v_mfma_f32_16x16x32_bf16 v[78:81], v[172:175], v[230:233], v[78:81]
	v_mfma_f32_16x16x32_bf16 v[70:73], v[180:183], v[230:233], v[70:73]
	v_mfma_f32_16x16x32_bf16 v[122:125], v[186:189], v[202:205], v[122:125]
	v_mfma_f32_16x16x32_bf16 v[114:117], v[194:197], v[202:205], v[114:117]
	v_mfma_f32_16x16x32_bf16 v[106:109], v[186:189], v[210:213], v[106:109]
	v_mfma_f32_16x16x32_bf16 v[98:101], v[194:197], v[210:213], v[98:101]
	v_mfma_f32_16x16x32_bf16 v[90:93], v[186:189], v[218:221], v[90:93]
	v_mfma_f32_16x16x32_bf16 v[82:85], v[194:197], v[218:221], v[82:85]
	v_mfma_f32_16x16x32_bf16 v[74:77], v[186:189], v[226:229], v[74:77]
	v_mfma_f32_16x16x32_bf16 v[66:69], v[194:197], v[226:229], v[66:69]
	v_mfma_f32_16x16x32_bf16 v[122:125], v[190:193], v[206:209], v[122:125]
	v_mfma_f32_16x16x32_bf16 v[114:117], v[198:201], v[206:209], v[114:117]
	v_mfma_f32_16x16x32_bf16 v[106:109], v[190:193], v[214:217], v[106:109]
	v_mfma_f32_16x16x32_bf16 v[98:101], v[198:201], v[214:217], v[98:101]
	v_mfma_f32_16x16x32_bf16 v[90:93], v[190:193], v[222:225], v[90:93]
	v_mfma_f32_16x16x32_bf16 v[82:85], v[198:201], v[222:225], v[82:85]
	v_mfma_f32_16x16x32_bf16 v[74:77], v[190:193], v[230:233], v[74:77]
	v_mfma_f32_16x16x32_bf16 v[66:69], v[198:201], v[230:233], v[66:69]
	s_setprio 0
	s_barrier
; #define PG8_STAGE(bufoff, gbase, voff) do { _Pragma("unroll") for (int _i = 0; _i < 2; ++_i) \
;         __builtin_amdgcn_global_load_lds((const unsigned*)((const char*)(gbase) + (voff)[_i]), (LAS unsigned*)(lds + (bufoff) + ldsw + _i * 8192), 16, 0, 0); } while (0)
; #define PG8_LDA(dst, b, h) do { _Pragma("unroll") for (int m = 0; m < 4; ++m) _Pragma("unroll") for (int k = 0; k < 2; ++k) dst[m][k] = *(const LAS bf16x8*)(lds + PG8_SA(b, h) + aoff + m * 2048 + k * 1024); } while (0)
; #define PG8_MMA(ai, bj, At, Bt) do { __builtin_amdgcn_s_setprio(1); _Pragma("unroll") for (int m = 0; m < 4; ++m) _Pragma("unroll") for (int n = 0; n < 2; ++n) _Pragma("unroll") for (int k = 0; k < 2; ++k) \
;         acc[ai][bj][m][n] = __builtin_amdgcn_mfma_f32_16x16x32_bf16(Bt[n][k], At[m][k], acc[ai][bj][m][n], 0, 0, 0); __builtin_amdgcn_s_setprio(0); } while (0)
; #define PG8_WAIT_V(n) asm volatile("s_waitcnt vmcnt(" #n ")" ::: "memory")
; #define PG8_WAIT_L(n) asm volatile("s_waitcnt lgkmcnt(" #n ")" ::: "memory")
; #define PG8_BAR __builtin_amdgcn_s_barrier()
; #define PG8_SCHED __builtin_amdgcn_sched_barrier(0)
; template <class Epi, class Sched>
; DI void gemm_phase(LAS unsigned char* lds, const Gemm g, const Sched& S, const Epi& E) {
;     ...
;             PG8_LDA(At, 1, 1); PG8_STAGE(PG8_SB(1, 0), b3, voffB); PG8_STAGE(PG8_SB(1, 1), b3 + hstepB, voffB); PG8_STAGE(PG8_SA(1, 0), a3, voffA);
;             PG8_WAIT_V(8); PG8_WAIT_L(0); PG8_BAR; PG8_MMA(1, 0, At, B0); PG8_MMA(1, 1, At, B1); PG8_BAR; PG8_SCHED;
;         }
;         if (wr == 0) PG8_BAR;
	s_add_i32 s44, s66, s46
	v_lshl_add_u64 v[234:235], v[234:235], 0, s[16:17]
	s_mov_b32 m0, s44
	ds_read_b128 v[202:205], v160 offset:49152
	ds_read_b128 v[206:209], v160 offset:50176
	ds_read_b128 v[210:213], v160 offset:51200
	ds_read_b128 v[214:217], v160 offset:52224
	ds_read_b128 v[218:221], v160 offset:53248
	ds_read_b128 v[222:225], v160 offset:54272
	ds_read_b128 v[226:229], v160 offset:55296
	ds_read_b128 v[230:233], v160 offset:56320
	global_load_lds_dwordx4 v[234:235], off
	s_add_i32 m0, s44, 0x2000
	s_add_u32 s42, s42, 0x40080
	v_lshl_add_u64 v[234:235], v[236:237], 0, s[16:17]
	s_addc_u32 s43, s43, 0
	s_add_i32 s44, s67, s46
	global_load_lds_dwordx4 v[234:235], off
	v_lshl_add_u64 v[234:235], s[42:43], 0, v[134:135]
	s_mov_b32 m0, s44
	s_nop 0
	global_load_lds_dwordx4 v[234:235], off
	v_lshl_add_u64 v[234:235], s[42:43], 0, v[130:131]
	s_add_i32 m0, s44, 0x2000
	s_nop 0
	global_load_lds_dwordx4 v[234:235], off
	v_lshl_add_u64 v[234:235], v[238:239], 0, s[16:17]
	s_mov_b32 m0, s54
	s_nop 0
	global_load_lds_dwordx4 v[234:235], off
	v_lshl_add_u64 v[234:235], v[240:241], 0, s[16:17]
	s_mov_b32 m0, s55
	s_nop 0
	global_load_lds_dwordx4 v[234:235], off
	s_waitcnt vmcnt(8) lgkmcnt(0)
	s_barrier
	s_setprio 1
	v_mfma_f32_16x16x32_bf16 v[62:65], v[168:171], v[202:205], v[62:65]
	v_mfma_f32_16x16x32_bf16 v[54:57], v[176:179], v[202:205], v[54:57]
	v_mfma_f32_16x16x32_bf16 v[46:49], v[168:171], v[210:213], v[46:49]
	v_mfma_f32_16x16x32_bf16 v[38:41], v[176:179], v[210:213], v[38:41]
	v_mfma_f32_16x16x32_bf16 v[30:33], v[168:171], v[218:221], v[30:33]
	v_mfma_f32_16x16x32_bf16 v[22:25], v[176:179], v[218:221], v[22:25]
	v_mfma_f32_16x16x32_bf16 v[14:17], v[168:171], v[226:229], v[14:17]
	v_mfma_f32_16x16x32_bf16 v[6:9], v[176:179], v[226:229], v[6:9]
	v_mfma_f32_16x16x32_bf16 v[62:65], v[172:175], v[206:209], v[62:65]
	v_mfma_f32_16x16x32_bf16 v[54:57], v[180:183], v[206:209], v[54:57]
	v_mfma_f32_16x16x32_bf16 v[46:49], v[172:175], v[214:217], v[46:49]
	v_mfma_f32_16x16x32_bf16 v[38:41], v[180:183], v[214:217], v[38:41]
	v_mfma_f32_16x16x32_bf16 v[30:33], v[172:175], v[222:225], v[30:33]
	v_mfma_f32_16x16x32_bf16 v[22:25], v[180:183], v[222:225], v[22:25]
	v_mfma_f32_16x16x32_bf16 v[14:17], v[172:175], v[230:233], v[14:17]
	v_mfma_f32_16x16x32_bf16 v[6:9], v[180:183], v[230:233], v[6:9]
	v_mfma_f32_16x16x32_bf16 v[58:61], v[186:189], v[202:205], v[58:61]
	v_mfma_f32_16x16x32_bf16 v[50:53], v[194:197], v[202:205], v[50:53]
	v_mfma_f32_16x16x32_bf16 v[42:45], v[186:189], v[210:213], v[42:45]
	v_mfma_f32_16x16x32_bf16 v[34:37], v[194:197], v[210:213], v[34:37]
	v_mfma_f32_16x16x32_bf16 v[26:29], v[186:189], v[218:221], v[26:29]
	v_mfma_f32_16x16x32_bf16 v[18:21], v[194:197], v[218:221], v[18:21]
	v_mfma_f32_16x16x32_bf16 v[10:13], v[186:189], v[226:229], v[10:13]
	v_mfma_f32_16x16x32_bf16 v[2:5], v[194:197], v[226:229], v[2:5]
	v_mfma_f32_16x16x32_bf16 v[58:61], v[190:193], v[206:209], v[58:61]
	v_mfma_f32_16x16x32_bf16 v[50:53], v[198:201], v[206:209], v[50:53]
	v_mfma_f32_16x16x32_bf16 v[42:45], v[190:193], v[214:217], v[42:45]
	v_mfma_f32_16x16x32_bf16 v[34:37], v[198:201], v[214:217], v[34:37]
	v_mfma_f32_16x16x32_bf16 v[26:29], v[190:193], v[222:225], v[26:29]
	v_mfma_f32_16x16x32_bf16 v[18:21], v[198:201], v[222:225], v[18:21]
	v_mfma_f32_16x16x32_bf16 v[10:13], v[190:193], v[230:233], v[10:13]
	v_mfma_f32_16x16x32_bf16 v[2:5], v[198:201], v[230:233], v[2:5]
	s_setprio 0
	s_barrier
	s_add_i32 s65, s65, 2
	s_add_u32 s40, s40, 0x100
	s_addc_u32 s41, s41, 0
	s_add_u32 s63, s63, 0x100
	s_addc_u32 s64, s64, 0
	s_cmp_gt_u32 s65, 13
	s_cbranch_scc0 .LBB0_179
	s_and_b64 vcc, exec, s[18:19]
	s_cbranch_vccz .LBB0_182
	s_barrier

; #define PG8_STAGE(bufoff, gbase, voff) do { _Pragma("unroll") for (int _i = 0; _i < 2; ++_i) \
;         __builtin_amdgcn_global_load_lds((const unsigned*)((const char*)(gbase) + (voff)[_i]), (LAS unsigned*)(lds + (bufoff) + ldsw + _i * 8192), 16, 0, 0); } while (0)
; #define PG8_LDA(dst, b, h) do { _Pragma("unroll") for (int m = 0; m < 4; ++m) _Pragma("unroll") for (int k = 0; k < 2; ++k) dst[m][k] = *(const LAS bf16x8*)(lds + PG8_SA(b, h) + aoff + m * 2048 + k * 1024); } while (0)
; #define PG8_LDB(dst, b, h) do { _Pragma("unroll") for (int n = 0; n < 2; ++n) _Pragma("unroll") for (int k = 0; k < 2; ++k) dst[n][k] = *(const LAS bf16x8*)(lds + PG8_SB(b, h) + boff + n * 2048 + k * 1024); } while (0)
; #define PG8_MMA(ai, bj, At, Bt) do { __builtin_amdgcn_s_setprio(1); _Pragma("unroll") for (int m = 0; m < 4; ++m) _Pragma("unroll") for (int n = 0; n < 2; ++n) _Pragma("unroll") for (int k = 0; k < 2; ++k) \
;         acc[ai][bj][m][n] = __builtin_amdgcn_mfma_f32_16x16x32_bf16(Bt[n][k], At[m][k], acc[ai][bj][m][n], 0, 0, 0); __builtin_amdgcn_s_setprio(0); } while (0)
; #define PG8_WAIT_V(n) asm volatile("s_waitcnt vmcnt(" #n ")" ::: "memory")
; #define PG8_WAIT_L(n) asm volatile("s_waitcnt lgkmcnt(" #n ")" ::: "memory")
; #define PG8_BAR __builtin_amdgcn_s_barrier()
; #define PG8_SCHED __builtin_amdgcn_sched_barrier(0)
; template <class Epi, class Sched>
; DI void gemm_phase(LAS unsigned char* lds, const Gemm g, const Sched& S, const Epi& E) {
;     ...
;             const bool last = (t == nt - 2);
;             const char* a1 = cA + (size_t)(t + 1) * kstep;
;             const char* a2 = last ? nA : cA + (size_t)(t + 2) * kstep; const char* b2 = last ? nB : cB + (size_t)(t + 2) * kstep;
;             const char* a3 = a2 + kstep; const char* b3 = b2 + kstep;
;             PG8_LDB(B0, 0, 0); PG8_LDB(B1, 0, 1); PG8_SCHED; PG8_LDA(At, 0, 0); PG8_STAGE(PG8_SA(1, 1), a1 + hstepA, voffA);
;             PG8_WAIT_V(8); PG8_WAIT_L(0); PG8_BAR; PG8_MMA(0, 0, At, B0); PG8_MMA(0, 1, At, B1); PG8_BAR; PG8_SCHED;
;             PG8_LDA(At, 0, 1); PG8_STAGE(PG8_SB(0, 0), b2, voffB); PG8_STAGE(PG8_SB(0, 1), b2 + hstepB, voffB); PG8_STAGE(PG8_SA(0, 0), a2, voffA);
;             PG8_WAIT_V(8); PG8_WAIT_L(0); PG8_BAR; PG8_MMA(1, 0, At, B0); PG8_MMA(1, 1, At, B1); PG8_BAR; PG8_SCHED;
.LBB0_278:
	ds_read_b128 v[148:151], v154
	ds_read_b128 v[158:161], v154 offset:1024
	ds_read_b128 v[162:165], v154 offset:2048
	ds_read_b128 v[166:169], v154 offset:3072
	ds_read_b128 v[170:173], v155
	ds_read_b128 v[174:177], v155 offset:1024
	ds_read_b128 v[178:181], v155 offset:2048
	ds_read_b128 v[186:189], v155 offset:3072
	s_add_u32 s38, s36, 0xfff50080
	s_addc_u32 s39, s37, -1
	s_cmp_eq_u32 s62, 40
	s_cselect_b32 s41, s9, s39
	s_cselect_b32 s40, s8, s38
	s_cselect_b32 s39, s35, s61
	s_cselect_b32 s38, s34, s60
	v_lshl_add_u64 v[182:183], s[36:37], 0, v[138:139]
	s_add_i32 m0, s45, 0xc000
	ds_read_b128 v[190:193], v156
	ds_read_b128 v[194:197], v156 offset:1024
	ds_read_b128 v[198:201], v156 offset:2048
	ds_read_b128 v[202:205], v156 offset:3072
	ds_read_b128 v[206:209], v156 offset:4096
	ds_read_b128 v[210:213], v156 offset:5120
	ds_read_b128 v[214:217], v156 offset:6144
	ds_read_b128 v[218:221], v156 offset:7168
	global_load_lds_dwordx4 v[182:183], off
	v_lshl_add_u64 v[182:183], s[36:37], 0, v[140:141]
	s_add_i32 m0, s45, 0xe000
	s_nop 0
	global_load_lds_dwordx4 v[182:183], off
	s_waitcnt vmcnt(8) lgkmcnt(0)
	s_barrier
	s_setprio 1
	v_mfma_f32_16x16x32_bf16 v[126:129], v[148:151], v[190:193], v[126:129]
	v_mfma_f32_16x16x32_bf16 v[122:125], v[162:165], v[190:193], v[122:125]
	v_mfma_f32_16x16x32_bf16 v[110:113], v[148:151], v[198:201], v[110:113]
	v_mfma_f32_16x16x32_bf16 v[106:109], v[162:165], v[198:201], v[106:109]
	v_mfma_f32_16x16x32_bf16 v[94:97], v[148:151], v[206:209], v[94:97]
	v_mfma_f32_16x16x32_bf16 v[90:93], v[162:165], v[206:209], v[90:93]
	v_mfma_f32_16x16x32_bf16 v[78:81], v[148:151], v[214:217], v[78:81]
	v_mfma_f32_16x16x32_bf16 v[74:77], v[162:165], v[214:217], v[74:77]
	v_mfma_f32_16x16x32_bf16 v[126:129], v[158:161], v[194:197], v[126:129]
	v_mfma_f32_16x16x32_bf16 v[122:125], v[166:169], v[194:197], v[122:125]
	v_mfma_f32_16x16x32_bf16 v[110:113], v[158:161], v[202:205], v[110:113]
	v_mfma_f32_16x16x32_bf16 v[106:109], v[166:169], v[202:205], v[106:109]
	v_mfma_f32_16x16x32_bf16 v[94:97], v[158:161], v[210:213], v[94:97]
	v_mfma_f32_16x16x32_bf16 v[90:93], v[166:169], v[210:213], v[90:93]
	v_mfma_f32_16x16x32_bf16 v[78:81], v[158:161], v[218:221], v[78:81]
	v_mfma_f32_16x16x32_bf16 v[74:77], v[166:169], v[218:221], v[74:77]
	v_mfma_f32_16x16x32_bf16 v[118:121], v[170:173], v[190:193], v[118:121]
	v_mfma_f32_16x16x32_bf16 v[114:117], v[178:181], v[190:193], v[114:117]
	v_mfma_f32_16x16x32_bf16 v[102:105], v[170:173], v[198:201], v[102:105]
	v_mfma_f32_16x16x32_bf16 v[98:101], v[178:181], v[198:201], v[98:101]
	v_mfma_f32_16x16x32_bf16 v[86:89], v[170:173], v[206:209], v[86:89]
	v_mfma_f32_16x16x32_bf16 v[82:85], v[178:181], v[206:209], v[82:85]
	v_mfma_f32_16x16x32_bf16 v[70:73], v[170:173], v[214:217], v[70:73]
	v_mfma_f32_16x16x32_bf16 v[66:69], v[178:181], v[214:217], v[66:69]
	v_mfma_f32_16x16x32_bf16 v[118:121], v[174:177], v[194:197], v[118:121]
	v_mfma_f32_16x16x32_bf16 v[114:117], v[186:189], v[194:197], v[114:117]
	v_mfma_f32_16x16x32_bf16 v[102:105], v[174:177], v[202:205], v[102:105]
	v_mfma_f32_16x16x32_bf16 v[98:101], v[186:189], v[202:205], v[98:101]
	v_mfma_f32_16x16x32_bf16 v[86:89], v[174:177], v[210:213], v[86:89]
	v_mfma_f32_16x16x32_bf16 v[82:85], v[186:189], v[210:213], v[82:85]
	v_mfma_f32_16x16x32_bf16 v[70:73], v[174:177], v[218:221], v[70:73]
	v_mfma_f32_16x16x32_bf16 v[66:69], v[186:189], v[218:221], v[66:69]
	s_setprio 0
	s_barrier
	s_add_i32 s63, s54, s44
	v_lshl_add_u64 v[182:183], s[38:39], 0, v[132:133]
	s_mov_b32 m0, s63
	ds_read_b128 v[190:193], v156 offset:16384
	ds_read_b128 v[194:197], v156 offset:17408
	ds_read_b128 v[198:201], v156 offset:18432
	ds_read_b128 v[202:205], v156 offset:19456
	ds_read_b128 v[206:209], v156 offset:20480
	ds_read_b128 v[210:213], v156 offset:21504
	ds_read_b128 v[214:217], v156 offset:22528
	ds_read_b128 v[218:221], v156 offset:23552
	global_load_lds_dwordx4 v[182:183], off
	s_add_i32 m0, s63, 0x2000
	s_add_u32 s64, s38, 0xb0000
	v_lshl_add_u64 v[222:223], s[38:39], 0, v[136:137]
	s_addc_u32 s65, s39, 0
	s_add_i32 s63, s55, s44
	global_load_lds_dwordx4 v[222:223], off
	v_lshl_add_u64 v[224:225], s[64:65], 0, v[132:133]
	s_mov_b32 m0, s63
	v_lshl_add_u64 v[226:227], s[40:41], 0, v[134:135]
	global_load_lds_dwordx4 v[224:225], off
	v_lshl_add_u64 v[224:225], s[64:65], 0, v[136:137]
	s_add_i32 m0, s63, 0x2000
	s_nop 0
	global_load_lds_dwordx4 v[224:225], off
	v_lshl_add_u64 v[224:225], s[40:41], 0, v[130:131]
	s_mov_b32 m0, s45
	s_nop 0
	global_load_lds_dwordx4 v[224:225], off
	s_mov_b32 m0, s46
	s_nop 0
	global_load_lds_dwordx4 v[226:227], off
	s_waitcnt vmcnt(8) lgkmcnt(0)
	s_barrier
; #define PG8_STAGE(bufoff, gbase, voff) do { _Pragma("unroll") for (int _i = 0; _i < 2; ++_i) \
;         __builtin_amdgcn_global_load_lds((const unsigned*)((const char*)(gbase) + (voff)[_i]), (LAS unsigned*)(lds + (bufoff) + ldsw + _i * 8192), 16, 0, 0); } while (0)
; #define PG8_LDA(dst, b, h) do { _Pragma("unroll") for (int m = 0; m < 4; ++m) _Pragma("unroll") for (int k = 0; k < 2; ++k) dst[m][k] = *(const LAS bf16x8*)(lds + PG8_SA(b, h) + aoff + m * 2048 + k * 1024); } while (0)
; #define PG8_LDB(dst, b, h) do { _Pragma("unroll") for (int n = 0; n < 2; ++n) _Pragma("unroll") for (int k = 0; k < 2; ++k) dst[n][k] = *(const LAS bf16x8*)(lds + PG8_SB(b, h) + boff + n * 2048 + k * 1024); } while (0)
; #define PG8_MMA(ai, bj, At, Bt) do { __builtin_amdgcn_s_setprio(1); _Pragma("unroll") for (int m = 0; m < 4; ++m) _Pragma("unroll") for (int n = 0; n < 2; ++n) _Pragma("unroll") for (int k = 0; k < 2; ++k) \
;         acc[ai][bj][m][n] = __builtin_amdgcn_mfma_f32_16x16x32_bf16(Bt[n][k], At[m][k], acc[ai][bj][m][n], 0, 0, 0); __builtin_amdgcn_s_setprio(0); } while (0)
; #define PG8_WAIT_V(n) asm volatile("s_waitcnt vmcnt(" #n ")" ::: "memory")
; #define PG8_WAIT_L(n) asm volatile("s_waitcnt lgkmcnt(" #n ")" ::: "memory")
; #define PG8_BAR __builtin_amdgcn_s_barrier()
; #define PG8_SCHED __builtin_amdgcn_sched_barrier(0)
; template <class Epi, class Sched>
; DI void gemm_phase(LAS unsigned char* lds, const Gemm g, const Sched& S, const Epi& E) {
;     ...
;             PG8_WAIT_V(8); PG8_WAIT_L(0); PG8_BAR; PG8_MMA(1, 0, At, B0); PG8_MMA(1, 1, At, B1); PG8_BAR; PG8_SCHED;
;             PG8_LDB(B0, 1, 0); PG8_LDB(B1, 1, 1); PG8_SCHED; PG8_LDA(At, 1, 0); PG8_STAGE(PG8_SA(0, 1), a2 + hstepA, voffA);
;             PG8_WAIT_V(8); PG8_WAIT_L(0); PG8_BAR; PG8_MMA(0, 0, At, B0); PG8_MMA(0, 1, At, B1); PG8_BAR; PG8_SCHED;
	s_setprio 1
	v_mfma_f32_16x16x32_bf16 v[62:65], v[148:151], v[190:193], v[62:65]
	v_mfma_f32_16x16x32_bf16 v[58:61], v[162:165], v[190:193], v[58:61]
	v_mfma_f32_16x16x32_bf16 v[46:49], v[148:151], v[198:201], v[46:49]
	v_mfma_f32_16x16x32_bf16 v[42:45], v[162:165], v[198:201], v[42:45]
	v_mfma_f32_16x16x32_bf16 v[30:33], v[148:151], v[206:209], v[30:33]
	v_mfma_f32_16x16x32_bf16 v[26:29], v[162:165], v[206:209], v[26:29]
	v_mfma_f32_16x16x32_bf16 v[14:17], v[148:151], v[214:217], v[14:17]
	v_mfma_f32_16x16x32_bf16 v[10:13], v[162:165], v[214:217], v[10:13]
	v_mfma_f32_16x16x32_bf16 v[62:65], v[158:161], v[194:197], v[62:65]
	v_mfma_f32_16x16x32_bf16 v[58:61], v[166:169], v[194:197], v[58:61]
	v_mfma_f32_16x16x32_bf16 v[46:49], v[158:161], v[202:205], v[46:49]
	v_mfma_f32_16x16x32_bf16 v[42:45], v[166:169], v[202:205], v[42:45]
	v_mfma_f32_16x16x32_bf16 v[30:33], v[158:161], v[210:213], v[30:33]
	v_mfma_f32_16x16x32_bf16 v[26:29], v[166:169], v[210:213], v[26:29]
	v_mfma_f32_16x16x32_bf16 v[14:17], v[158:161], v[218:221], v[14:17]
	v_mfma_f32_16x16x32_bf16 v[10:13], v[166:169], v[218:221], v[10:13]
	v_mfma_f32_16x16x32_bf16 v[54:57], v[170:173], v[190:193], v[54:57]
	v_mfma_f32_16x16x32_bf16 v[50:53], v[178:181], v[190:193], v[50:53]
	v_mfma_f32_16x16x32_bf16 v[38:41], v[170:173], v[198:201], v[38:41]
	v_mfma_f32_16x16x32_bf16 v[34:37], v[178:181], v[198:201], v[34:37]
	v_mfma_f32_16x16x32_bf16 v[22:25], v[170:173], v[206:209], v[22:25]
	v_mfma_f32_16x16x32_bf16 v[18:21], v[178:181], v[206:209], v[18:21]
	v_mfma_f32_16x16x32_bf16 v[6:9], v[170:173], v[214:217], v[6:9]
	v_mfma_f32_16x16x32_bf16 v[2:5], v[178:181], v[214:217], v[2:5]
	v_mfma_f32_16x16x32_bf16 v[54:57], v[174:177], v[194:197], v[54:57]
	v_mfma_f32_16x16x32_bf16 v[50:53], v[186:189], v[194:197], v[50:53]
	v_mfma_f32_16x16x32_bf16 v[38:41], v[174:177], v[202:205], v[38:41]
	v_mfma_f32_16x16x32_bf16 v[34:37], v[186:189], v[202:205], v[34:37]
	v_mfma_f32_16x16x32_bf16 v[22:25], v[174:177], v[210:213], v[22:25]
	v_mfma_f32_16x16x32_bf16 v[18:21], v[186:189], v[210:213], v[18:21]
	v_mfma_f32_16x16x32_bf16 v[6:9], v[174:177], v[218:221], v[6:9]
	v_mfma_f32_16x16x32_bf16 v[2:5], v[186:189], v[218:221], v[2:5]
	s_setprio 0
	s_barrier
	s_add_i32 s63, 0, 0x18000
	s_add_i32 s64, 0, 0x1c000
	v_add_u32_e32 v166, s63, v152
	v_add_u32_e32 v185, s64, v152
	ds_read_b128 v[148:151], v166
	ds_read_b128 v[158:161], v166 offset:1024
	ds_read_b128 v[162:165], v166 offset:2048
	ds_read_b128 v[166:169], v166 offset:3072
	ds_read_b128 v[170:173], v185
	ds_read_b128 v[174:177], v185 offset:1024
	ds_read_b128 v[178:181], v185 offset:2048
	ds_read_b128 v[186:189], v185 offset:3072
	s_add_u32 s40, s40, 0xb0000
	s_addc_u32 s41, s41, 0
	s_mov_b32 m0, s47
	v_lshl_add_u64 v[228:229], s[40:41], 0, v[130:131]
	ds_read_b128 v[190:193], v156 offset:32768
	ds_read_b128 v[194:197], v156 offset:33792
	ds_read_b128 v[198:201], v156 offset:34816
	ds_read_b128 v[202:205], v156 offset:35840
	ds_read_b128 v[206:209], v156 offset:36864
	ds_read_b128 v[210:213], v156 offset:37888
	ds_read_b128 v[214:217], v156 offset:38912
	ds_read_b128 v[218:221], v156 offset:39936
	global_load_lds_dwordx4 v[228:229], off
	v_lshl_add_u64 v[228:229], s[40:41], 0, v[134:135]
	s_mov_b32 m0, s48
	s_nop 0
	global_load_lds_dwordx4 v[228:229], off
	s_waitcnt vmcnt(8) lgkmcnt(0)
	s_barrier
	s_setprio 1
	v_mfma_f32_16x16x32_bf16 v[126:129], v[148:151], v[190:193], v[126:129]
	v_mfma_f32_16x16x32_bf16 v[122:125], v[162:165], v[190:193], v[122:125]
	v_mfma_f32_16x16x32_bf16 v[110:113], v[148:151], v[198:201], v[110:113]
	v_mfma_f32_16x16x32_bf16 v[106:109], v[162:165], v[198:201], v[106:109]
	v_mfma_f32_16x16x32_bf16 v[94:97], v[148:151], v[206:209], v[94:97]
	v_mfma_f32_16x16x32_bf16 v[90:93], v[162:165], v[206:209], v[90:93]
	v_mfma_f32_16x16x32_bf16 v[78:81], v[148:151], v[214:217], v[78:81]
	v_mfma_f32_16x16x32_bf16 v[74:77], v[162:165], v[214:217], v[74:77]
	v_mfma_f32_16x16x32_bf16 v[126:129], v[158:161], v[194:197], v[126:129]
	v_mfma_f32_16x16x32_bf16 v[122:125], v[166:169], v[194:197], v[122:125]
	v_mfma_f32_16x16x32_bf16 v[110:113], v[158:161], v[202:205], v[110:113]
	v_mfma_f32_16x16x32_bf16 v[106:109], v[166:169], v[202:205], v[106:109]
	v_mfma_f32_16x16x32_bf16 v[94:97], v[158:161], v[210:213], v[94:97]
	v_mfma_f32_16x16x32_bf16 v[90:93], v[166:169], v[210:213], v[90:93]
	v_mfma_f32_16x16x32_bf16 v[78:81], v[158:161], v[218:221], v[78:81]
	v_mfma_f32_16x16x32_bf16 v[74:77], v[166:169], v[218:221], v[74:77]
	v_mfma_f32_16x16x32_bf16 v[118:121], v[170:173], v[190:193], v[118:121]
	v_mfma_f32_16x16x32_bf16 v[114:117], v[178:181], v[190:193], v[114:117]
	v_mfma_f32_16x16x32_bf16 v[102:105], v[170:173], v[198:201], v[102:105]
	v_mfma_f32_16x16x32_bf16 v[98:101], v[178:181], v[198:201], v[98:101]
	v_mfma_f32_16x16x32_bf16 v[86:89], v[170:173], v[206:209], v[86:89]
	v_mfma_f32_16x16x32_bf16 v[82:85], v[178:181], v[206:209], v[82:85]
	v_mfma_f32_16x16x32_bf16 v[70:73], v[170:173], v[214:217], v[70:73]
	v_mfma_f32_16x16x32_bf16 v[66:69], v[178:181], v[214:217], v[66:69]
	v_mfma_f32_16x16x32_bf16 v[118:121], v[174:177], v[194:197], v[118:121]
	v_mfma_f32_16x16x32_bf16 v[114:117], v[186:189], v[194:197], v[114:117]
	v_mfma_f32_16x16x32_bf16 v[102:105], v[174:177], v[202:205], v[102:105]
	v_mfma_f32_16x16x32_bf16 v[98:101], v[186:189], v[202:205], v[98:101]
	v_mfma_f32_16x16x32_bf16 v[86:89], v[174:177], v[210:213], v[86:89]
	v_mfma_f32_16x16x32_bf16 v[82:85], v[186:189], v[210:213], v[82:85]
	v_mfma_f32_16x16x32_bf16 v[70:73], v[174:177], v[218:221], v[70:73]
	v_mfma_f32_16x16x32_bf16 v[66:69], v[186:189], v[218:221], v[66:69]
	s_setprio 0
	s_barrier
; #define PG8_STAGE(bufoff, gbase, voff) do { _Pragma("unroll") for (int _i = 0; _i < 2; ++_i) \
;         __builtin_amdgcn_global_load_lds((const unsigned*)((const char*)(gbase) + (voff)[_i]), (LAS unsigned*)(lds + (bufoff) + ldsw + _i * 8192), 16, 0, 0); } while (0)
; #define PG8_LDA(dst, b, h) do { _Pragma("unroll") for (int m = 0; m < 4; ++m) _Pragma("unroll") for (int k = 0; k < 2; ++k) dst[m][k] = *(const LAS bf16x8*)(lds + PG8_SA(b, h) + aoff + m * 2048 + k * 1024); } while (0)
; #define PG8_MMA(ai, bj, At, Bt) do { __builtin_amdgcn_s_setprio(1); _Pragma("unroll") for (int m = 0; m < 4; ++m) _Pragma("unroll") for (int n = 0; n < 2; ++n) _Pragma("unroll") for (int k = 0; k < 2; ++k) \
;         acc[ai][bj][m][n] = __builtin_amdgcn_mfma_f32_16x16x32_bf16(Bt[n][k], At[m][k], acc[ai][bj][m][n], 0, 0, 0); __builtin_amdgcn_s_setprio(0); } while (0)
; #define PG8_WAIT_V(n) asm volatile("s_waitcnt vmcnt(" #n ")" ::: "memory")
; #define PG8_WAIT_L(n) asm volatile("s_waitcnt lgkmcnt(" #n ")" ::: "memory")
; #define PG8_BAR __builtin_amdgcn_s_barrier()
; #define PG8_SCHED __builtin_amdgcn_sched_barrier(0)
; template <class Epi, class Sched>
; DI void gemm_phase(LAS unsigned char* lds, const Gemm g, const Sched& S, const Epi& E) {
;     ...
;             PG8_LDA(At, 1, 1); PG8_STAGE(PG8_SB(1, 0), b3, voffB); PG8_STAGE(PG8_SB(1, 1), b3 + hstepB, voffB); PG8_STAGE(PG8_SA(1, 0), a3, voffA);
;             PG8_WAIT_V(8); PG8_WAIT_L(0); PG8_BAR; PG8_MMA(1, 0, At, B0); PG8_MMA(1, 1, At, B1); PG8_BAR; PG8_SCHED;
;         }
;         if (wr == 0) PG8_BAR;
	s_add_i32 s40, s63, s44
	v_lshl_add_u64 v[182:183], v[182:183], 0, s[16:17]
	s_mov_b32 m0, s40
	ds_read_b128 v[190:193], v156 offset:49152
	ds_read_b128 v[194:197], v156 offset:50176
	ds_read_b128 v[198:201], v156 offset:51200
	ds_read_b128 v[202:205], v156 offset:52224
	ds_read_b128 v[206:209], v156 offset:53248
	ds_read_b128 v[210:213], v156 offset:54272
	ds_read_b128 v[214:217], v156 offset:55296
	ds_read_b128 v[218:221], v156 offset:56320
	global_load_lds_dwordx4 v[182:183], off
	s_add_i32 m0, s40, 0x2000
	s_add_u32 s38, s38, 0xb0080
	v_lshl_add_u64 v[182:183], v[222:223], 0, s[16:17]
	s_addc_u32 s39, s39, 0
	s_add_i32 s40, s64, s44
	global_load_lds_dwordx4 v[182:183], off
	v_lshl_add_u64 v[182:183], s[38:39], 0, v[132:133]
	s_mov_b32 m0, s40
	s_nop 0
	global_load_lds_dwordx4 v[182:183], off
	v_lshl_add_u64 v[182:183], s[38:39], 0, v[136:137]
	s_add_i32 m0, s40, 0x2000
	s_nop 0
	global_load_lds_dwordx4 v[182:183], off
	v_lshl_add_u64 v[182:183], v[224:225], 0, s[16:17]
	s_mov_b32 m0, s50
	s_nop 0
	global_load_lds_dwordx4 v[182:183], off
	v_lshl_add_u64 v[182:183], v[226:227], 0, s[16:17]
	s_mov_b32 m0, s51
	s_nop 0
	global_load_lds_dwordx4 v[182:183], off
	s_waitcnt vmcnt(8) lgkmcnt(0)
	s_barrier
	s_setprio 1
	v_mfma_f32_16x16x32_bf16 v[62:65], v[148:151], v[190:193], v[62:65]
	v_mfma_f32_16x16x32_bf16 v[58:61], v[162:165], v[190:193], v[58:61]
	v_mfma_f32_16x16x32_bf16 v[46:49], v[148:151], v[198:201], v[46:49]
	v_mfma_f32_16x16x32_bf16 v[42:45], v[162:165], v[198:201], v[42:45]
	v_mfma_f32_16x16x32_bf16 v[30:33], v[148:151], v[206:209], v[30:33]
	v_mfma_f32_16x16x32_bf16 v[26:29], v[162:165], v[206:209], v[26:29]
	v_mfma_f32_16x16x32_bf16 v[14:17], v[148:151], v[214:217], v[14:17]
	v_mfma_f32_16x16x32_bf16 v[10:13], v[162:165], v[214:217], v[10:13]
	v_mfma_f32_16x16x32_bf16 v[62:65], v[158:161], v[194:197], v[62:65]
	v_mfma_f32_16x16x32_bf16 v[58:61], v[166:169], v[194:197], v[58:61]
	v_mfma_f32_16x16x32_bf16 v[46:49], v[158:161], v[202:205], v[46:49]
	v_mfma_f32_16x16x32_bf16 v[42:45], v[166:169], v[202:205], v[42:45]
	v_mfma_f32_16x16x32_bf16 v[30:33], v[158:161], v[210:213], v[30:33]
	v_mfma_f32_16x16x32_bf16 v[26:29], v[166:169], v[210:213], v[26:29]
	v_mfma_f32_16x16x32_bf16 v[14:17], v[158:161], v[218:221], v[14:17]
	v_mfma_f32_16x16x32_bf16 v[10:13], v[166:169], v[218:221], v[10:13]
	v_mfma_f32_16x16x32_bf16 v[54:57], v[170:173], v[190:193], v[54:57]
	v_mfma_f32_16x16x32_bf16 v[50:53], v[178:181], v[190:193], v[50:53]
	v_mfma_f32_16x16x32_bf16 v[38:41], v[170:173], v[198:201], v[38:41]
	v_mfma_f32_16x16x32_bf16 v[34:37], v[178:181], v[198:201], v[34:37]
	v_mfma_f32_16x16x32_bf16 v[22:25], v[170:173], v[206:209], v[22:25]
	v_mfma_f32_16x16x32_bf16 v[18:21], v[178:181], v[206:209], v[18:21]
	v_mfma_f32_16x16x32_bf16 v[6:9], v[170:173], v[214:217], v[6:9]
	v_mfma_f32_16x16x32_bf16 v[2:5], v[178:181], v[214:217], v[2:5]
	v_mfma_f32_16x16x32_bf16 v[54:57], v[174:177], v[194:197], v[54:57]
	v_mfma_f32_16x16x32_bf16 v[50:53], v[186:189], v[194:197], v[50:53]
	v_mfma_f32_16x16x32_bf16 v[38:41], v[174:177], v[202:205], v[38:41]
	v_mfma_f32_16x16x32_bf16 v[34:37], v[186:189], v[202:205], v[34:37]
	v_mfma_f32_16x16x32_bf16 v[22:25], v[174:177], v[210:213], v[22:25]
	v_mfma_f32_16x16x32_bf16 v[18:21], v[186:189], v[210:213], v[18:21]
	v_mfma_f32_16x16x32_bf16 v[6:9], v[174:177], v[218:221], v[6:9]
	v_mfma_f32_16x16x32_bf16 v[2:5], v[186:189], v[218:221], v[2:5]
	s_setprio 0
	s_barrier
	s_add_i32 s62, s62, 2
	s_add_u32 s36, s36, 0x100
	s_addc_u32 s37, s37, 0
	s_add_u32 s60, s60, 0x100
	s_addc_u32 s61, s61, 0
	s_cmp_gt_u32 s62, 41
	s_cbranch_scc0 .LBB0_278
	s_and_b64 vcc, exec, s[18:19]
	s_cbranch_vccz .LBB0_281
	s_barrier

; #define PG8_STAGE(bufoff, gbase, voff) do { _Pragma("unroll") for (int _i = 0; _i < 2; ++_i) \
;         __builtin_amdgcn_global_load_lds((const unsigned*)((const char*)(gbase) + (voff)[_i]), (LAS unsigned*)(lds + (bufoff) + ldsw + _i * 8192), 16, 0, 0); } while (0)
; #define PG8_LDA(dst, b, h) do { _Pragma("unroll") for (int m = 0; m < 4; ++m) _Pragma("unroll") for (int k = 0; k < 2; ++k) dst[m][k] = *(const LAS bf16x8*)(lds + PG8_SA(b, h) + aoff + m * 2048 + k * 1024); } while (0)
; #define PG8_LDB(dst, b, h) do { _Pragma("unroll") for (int n = 0; n < 2; ++n) _Pragma("unroll") for (int k = 0; k < 2; ++k) dst[n][k] = *(const LAS bf16x8*)(lds + PG8_SB(b, h) + boff + n * 2048 + k * 1024); } while (0)
; #define PG8_MMA(ai, bj, At, Bt) do { __builtin_amdgcn_s_setprio(1); _Pragma("unroll") for (int m = 0; m < 4; ++m) _Pragma("unroll") for (int n = 0; n < 2; ++n) _Pragma("unroll") for (int k = 0; k < 2; ++k) \
;         acc[ai][bj][m][n] = __builtin_amdgcn_mfma_f32_16x16x32_bf16(Bt[n][k], At[m][k], acc[ai][bj][m][n], 0, 0, 0); __builtin_amdgcn_s_setprio(0); } while (0)
; #define PG8_WAIT_V(n) asm volatile("s_waitcnt vmcnt(" #n ")" ::: "memory")
; #define PG8_WAIT_L(n) asm volatile("s_waitcnt lgkmcnt(" #n ")" ::: "memory")
; #define PG8_BAR __builtin_amdgcn_s_barrier()
; #define PG8_SCHED __builtin_amdgcn_sched_barrier(0)
; template <class Epi, class Sched>
; DI void gemm_phase(LAS unsigned char* lds, const Gemm g, const Sched& S, const Epi& E) {
;     ...
;         for (int t = 0; t < nt; t += 2) {
;             const bool last = (t == nt - 2);
;             const char* a1 = cA + (size_t)(t + 1) * kstep;
;             const char* a2 = last ? nA : cA + (size_t)(t + 2) * kstep; const char* b2 = last ? nB : cB + (size_t)(t + 2) * kstep;
;             const char* a3 = a2 + kstep; const char* b3 = b2 + kstep;
;             PG8_LDB(B0, 0, 0); PG8_LDB(B1, 0, 1); PG8_SCHED; PG8_LDA(At, 0, 0); PG8_STAGE(PG8_SA(1, 1), a1 + hstepA, voffA);
;             PG8_WAIT_V(8); PG8_WAIT_L(0); PG8_BAR; PG8_MMA(0, 0, At, B0); PG8_MMA(0, 1, At, B1); PG8_BAR; PG8_SCHED;
;             PG8_LDA(At, 0, 1); PG8_STAGE(PG8_SB(0, 0), b2, voffB); PG8_STAGE(PG8_SB(0, 1), b2 + hstepB, voffB); PG8_STAGE(PG8_SA(0, 0), a2, voffA);
;             PG8_WAIT_V(8); PG8_WAIT_L(0); PG8_BAR; PG8_MMA(1, 0, At, B0); PG8_MMA(1, 1, At, B1); PG8_BAR; PG8_SCHED;
.LBB0_381:
	ds_read_b128 v[138:141], v188
	ds_read_b128 v[142:145], v188 offset:1024
	ds_read_b128 v[176:179], v188 offset:2048
	ds_read_b128 v[198:201], v188 offset:3072
	ds_read_b128 v[202:205], v189
	ds_read_b128 v[206:209], v189 offset:1024
	ds_read_b128 v[210:213], v189 offset:2048
	ds_read_b128 v[214:217], v189 offset:3072
	s_add_u32 s64, s10, 0xfffc0080
	s_addc_u32 s65, s11, -1
	s_cmp_eq_u32 s69, 12
	s_cselect_b32 s67, s13, s65
	s_cselect_b32 s66, s29, s64
	s_cselect_b32 s65, s36, s68
	s_cselect_b32 s64, s57, s59
	v_lshl_add_u64 v[172:173], s[10:11], 0, v[162:163]
	s_add_i32 m0, s79, 0xc000
	ds_read_b128 v[218:221], v186
	ds_read_b128 v[222:225], v186 offset:1024
	ds_read_b128 v[226:229], v186 offset:2048
	ds_read_b128 v[230:233], v186 offset:3072
	ds_read_b128 v[234:237], v186 offset:4096
	ds_read_b128 v[238:241], v186 offset:5120
	ds_read_b128 v[242:245], v186 offset:6144
	ds_read_b128 v[246:249], v186 offset:7168
	global_load_lds_dwordx4 v[172:173], off
	v_lshl_add_u64 v[172:173], s[10:11], 0, v[164:165]
	s_add_i32 m0, s79, 0xe000
	s_nop 0
	global_load_lds_dwordx4 v[172:173], off
	s_waitcnt vmcnt(8) lgkmcnt(0)
	s_barrier
	s_setprio 1
	v_mfma_f32_16x16x32_bf16 v[126:129], v[138:141], v[218:221], v[126:129]
	v_mfma_f32_16x16x32_bf16 v[122:125], v[176:179], v[218:221], v[122:125]
	v_mfma_f32_16x16x32_bf16 v[110:113], v[138:141], v[226:229], v[110:113]
	v_mfma_f32_16x16x32_bf16 v[106:109], v[176:179], v[226:229], v[106:109]
	v_mfma_f32_16x16x32_bf16 v[94:97], v[138:141], v[234:237], v[94:97]
	v_mfma_f32_16x16x32_bf16 v[90:93], v[176:179], v[234:237], v[90:93]
	v_mfma_f32_16x16x32_bf16 v[78:81], v[138:141], v[242:245], v[78:81]
	v_mfma_f32_16x16x32_bf16 v[74:77], v[176:179], v[242:245], v[74:77]
	v_mfma_f32_16x16x32_bf16 v[126:129], v[142:145], v[222:225], v[126:129]
	v_mfma_f32_16x16x32_bf16 v[122:125], v[198:201], v[222:225], v[122:125]
	v_mfma_f32_16x16x32_bf16 v[110:113], v[142:145], v[230:233], v[110:113]
	v_mfma_f32_16x16x32_bf16 v[106:109], v[198:201], v[230:233], v[106:109]
	v_mfma_f32_16x16x32_bf16 v[94:97], v[142:145], v[238:241], v[94:97]
	v_mfma_f32_16x16x32_bf16 v[90:93], v[198:201], v[238:241], v[90:93]
	v_mfma_f32_16x16x32_bf16 v[78:81], v[142:145], v[246:249], v[78:81]
	v_mfma_f32_16x16x32_bf16 v[74:77], v[198:201], v[246:249], v[74:77]
	v_mfma_f32_16x16x32_bf16 v[118:121], v[202:205], v[218:221], v[118:121]
	v_mfma_f32_16x16x32_bf16 v[114:117], v[210:213], v[218:221], v[114:117]
	v_mfma_f32_16x16x32_bf16 v[102:105], v[202:205], v[226:229], v[102:105]
	v_mfma_f32_16x16x32_bf16 v[98:101], v[210:213], v[226:229], v[98:101]
	v_mfma_f32_16x16x32_bf16 v[86:89], v[202:205], v[234:237], v[86:89]
	v_mfma_f32_16x16x32_bf16 v[82:85], v[210:213], v[234:237], v[82:85]
	v_mfma_f32_16x16x32_bf16 v[70:73], v[202:205], v[242:245], v[70:73]
	v_mfma_f32_16x16x32_bf16 v[66:69], v[210:213], v[242:245], v[66:69]
	v_mfma_f32_16x16x32_bf16 v[118:121], v[206:209], v[222:225], v[118:121]
	v_mfma_f32_16x16x32_bf16 v[114:117], v[214:217], v[222:225], v[114:117]
	v_mfma_f32_16x16x32_bf16 v[102:105], v[206:209], v[230:233], v[102:105]
	v_mfma_f32_16x16x32_bf16 v[98:101], v[214:217], v[230:233], v[98:101]
	v_mfma_f32_16x16x32_bf16 v[86:89], v[206:209], v[238:241], v[86:89]
	v_mfma_f32_16x16x32_bf16 v[82:85], v[214:217], v[238:241], v[82:85]
	v_mfma_f32_16x16x32_bf16 v[70:73], v[206:209], v[246:249], v[70:73]
	v_mfma_f32_16x16x32_bf16 v[66:69], v[214:217], v[246:249], v[66:69]
	s_setprio 0
	s_barrier
	s_add_i32 s70, s94, s78
	v_lshl_add_u64 v[172:173], s[64:65], 0, v[150:151]
	s_mov_b32 m0, s70
	ds_read_b128 v[218:221], v186 offset:16384
	ds_read_b128 v[222:225], v186 offset:17408
	ds_read_b128 v[226:229], v186 offset:18432
	ds_read_b128 v[230:233], v186 offset:19456
	ds_read_b128 v[234:237], v186 offset:20480
	ds_read_b128 v[238:241], v186 offset:21504
	ds_read_b128 v[242:245], v186 offset:22528
	ds_read_b128 v[246:249], v186 offset:23552
	global_load_lds_dwordx4 v[172:173], off
	s_add_i32 m0, s70, 0x2000
	s_add_u32 s70, s64, 0x40000
	v_lshl_add_u64 v[180:181], s[64:65], 0, v[154:155]
	s_addc_u32 s71, s65, 0
	s_add_i32 s72, s95, s78
	global_load_lds_dwordx4 v[180:181], off
	v_lshl_add_u64 v[250:251], s[70:71], 0, v[150:151]
	s_mov_b32 m0, s72
	v_lshl_add_u64 v[252:253], s[66:67], 0, v[152:153]
	global_load_lds_dwordx4 v[250:251], off
	v_lshl_add_u64 v[250:251], s[70:71], 0, v[154:155]
	s_add_i32 m0, s72, 0x2000
	s_nop 0
	global_load_lds_dwordx4 v[250:251], off
	v_lshl_add_u64 v[250:251], s[66:67], 0, v[148:149]
	s_mov_b32 m0, s79
	s_nop 0
	global_load_lds_dwordx4 v[250:251], off
	s_mov_b32 m0, s80
	s_nop 0
	global_load_lds_dwordx4 v[252:253], off
	s_waitcnt vmcnt(8) lgkmcnt(0)
	s_barrier
; #define PG8_STAGE(bufoff, gbase, voff) do { _Pragma("unroll") for (int _i = 0; _i < 2; ++_i) \
;         __builtin_amdgcn_global_load_lds((const unsigned*)((const char*)(gbase) + (voff)[_i]), (LAS unsigned*)(lds + (bufoff) + ldsw + _i * 8192), 16, 0, 0); } while (0)
; #define PG8_LDA(dst, b, h) do { _Pragma("unroll") for (int m = 0; m < 4; ++m) _Pragma("unroll") for (int k = 0; k < 2; ++k) dst[m][k] = *(const LAS bf16x8*)(lds + PG8_SA(b, h) + aoff + m * 2048 + k * 1024); } while (0)
; #define PG8_LDB(dst, b, h) do { _Pragma("unroll") for (int n = 0; n < 2; ++n) _Pragma("unroll") for (int k = 0; k < 2; ++k) dst[n][k] = *(const LAS bf16x8*)(lds + PG8_SB(b, h) + boff + n * 2048 + k * 1024); } while (0)
; #define PG8_MMA(ai, bj, At, Bt) do { __builtin_amdgcn_s_setprio(1); _Pragma("unroll") for (int m = 0; m < 4; ++m) _Pragma("unroll") for (int n = 0; n < 2; ++n) _Pragma("unroll") for (int k = 0; k < 2; ++k) \
;         acc[ai][bj][m][n] = __builtin_amdgcn_mfma_f32_16x16x32_bf16(Bt[n][k], At[m][k], acc[ai][bj][m][n], 0, 0, 0); __builtin_amdgcn_s_setprio(0); } while (0)
; #define PG8_WAIT_V(n) asm volatile("s_waitcnt vmcnt(" #n ")" ::: "memory")
; #define PG8_WAIT_L(n) asm volatile("s_waitcnt lgkmcnt(" #n ")" ::: "memory")
; #define PG8_BAR __builtin_amdgcn_s_barrier()
; #define PG8_SCHED __builtin_amdgcn_sched_barrier(0)
; template <class Epi, class Sched>
; DI void gemm_phase(LAS unsigned char* lds, const Gemm g, const Sched& S, const Epi& E) {
;     ...
;             PG8_WAIT_V(8); PG8_WAIT_L(0); PG8_BAR; PG8_MMA(1, 0, At, B0); PG8_MMA(1, 1, At, B1); PG8_BAR; PG8_SCHED;
;             PG8_LDB(B0, 1, 0); PG8_LDB(B1, 1, 1); PG8_SCHED; PG8_LDA(At, 1, 0); PG8_STAGE(PG8_SA(0, 1), a2 + hstepA, voffA);
;             PG8_WAIT_V(8); PG8_WAIT_L(0); PG8_BAR; PG8_MMA(0, 0, At, B0); PG8_MMA(0, 1, At, B1); PG8_BAR; PG8_SCHED;
	s_setprio 1
	v_mfma_f32_16x16x32_bf16 v[62:65], v[138:141], v[218:221], v[62:65]
	v_mfma_f32_16x16x32_bf16 v[58:61], v[176:179], v[218:221], v[58:61]
	v_mfma_f32_16x16x32_bf16 v[46:49], v[138:141], v[226:229], v[46:49]
	v_mfma_f32_16x16x32_bf16 v[42:45], v[176:179], v[226:229], v[42:45]
	v_mfma_f32_16x16x32_bf16 v[30:33], v[138:141], v[234:237], v[30:33]
	v_mfma_f32_16x16x32_bf16 v[26:29], v[176:179], v[234:237], v[26:29]
	v_mfma_f32_16x16x32_bf16 v[14:17], v[138:141], v[242:245], v[14:17]
	v_mfma_f32_16x16x32_bf16 v[10:13], v[176:179], v[242:245], v[10:13]
	v_mfma_f32_16x16x32_bf16 v[62:65], v[142:145], v[222:225], v[62:65]
	v_mfma_f32_16x16x32_bf16 v[58:61], v[198:201], v[222:225], v[58:61]
	v_mfma_f32_16x16x32_bf16 v[46:49], v[142:145], v[230:233], v[46:49]
	v_mfma_f32_16x16x32_bf16 v[42:45], v[198:201], v[230:233], v[42:45]
	v_mfma_f32_16x16x32_bf16 v[30:33], v[142:145], v[238:241], v[30:33]
	v_mfma_f32_16x16x32_bf16 v[26:29], v[198:201], v[238:241], v[26:29]
	v_mfma_f32_16x16x32_bf16 v[14:17], v[142:145], v[246:249], v[14:17]
	v_mfma_f32_16x16x32_bf16 v[10:13], v[198:201], v[246:249], v[10:13]
	v_mfma_f32_16x16x32_bf16 v[54:57], v[202:205], v[218:221], v[54:57]
	v_mfma_f32_16x16x32_bf16 v[50:53], v[210:213], v[218:221], v[50:53]
	v_mfma_f32_16x16x32_bf16 v[38:41], v[202:205], v[226:229], v[38:41]
	v_mfma_f32_16x16x32_bf16 v[34:37], v[210:213], v[226:229], v[34:37]
	v_mfma_f32_16x16x32_bf16 v[22:25], v[202:205], v[234:237], v[22:25]
	v_mfma_f32_16x16x32_bf16 v[18:21], v[210:213], v[234:237], v[18:21]
	v_mfma_f32_16x16x32_bf16 v[6:9], v[202:205], v[242:245], v[6:9]
	v_mfma_f32_16x16x32_bf16 v[2:5], v[210:213], v[242:245], v[2:5]
	v_mfma_f32_16x16x32_bf16 v[54:57], v[206:209], v[222:225], v[54:57]
	v_mfma_f32_16x16x32_bf16 v[50:53], v[214:217], v[222:225], v[50:53]
	v_mfma_f32_16x16x32_bf16 v[38:41], v[206:209], v[230:233], v[38:41]
	v_mfma_f32_16x16x32_bf16 v[34:37], v[214:217], v[230:233], v[34:37]
	v_mfma_f32_16x16x32_bf16 v[22:25], v[206:209], v[238:241], v[22:25]
	v_mfma_f32_16x16x32_bf16 v[18:21], v[214:217], v[238:241], v[18:21]
	v_mfma_f32_16x16x32_bf16 v[6:9], v[206:209], v[246:249], v[6:9]
	v_mfma_f32_16x16x32_bf16 v[2:5], v[214:217], v[246:249], v[2:5]
	s_setprio 0
	s_barrier
	s_add_i32 s70, 0, 0x18000
	v_add_u32_e32 v156, s70, v159
	s_add_i32 s71, 0, 0x1c000
	ds_read_b128 v[138:141], v156
	ds_read_b128 v[142:145], v156 offset:1024
	ds_read_b128 v[176:179], v156 offset:2048
	ds_read_b128 v[198:201], v156 offset:3072
	v_add_u32_e32 v156, s71, v159
	ds_read_b128 v[202:205], v156
	ds_read_b128 v[206:209], v156 offset:1024
	ds_read_b128 v[210:213], v156 offset:2048
	ds_read_b128 v[214:217], v156 offset:3072
	s_add_u32 s66, s66, 0x40000
	s_addc_u32 s67, s67, 0
	s_mov_b32 m0, s81
	v_lshl_add_u64 v[254:255], s[66:67], 0, v[148:149]
	ds_read_b128 v[218:221], v186 offset:32768
	ds_read_b128 v[222:225], v186 offset:33792
	ds_read_b128 v[226:229], v186 offset:34816
	ds_read_b128 v[230:233], v186 offset:35840
	ds_read_b128 v[234:237], v186 offset:36864
	ds_read_b128 v[238:241], v186 offset:37888
	ds_read_b128 v[242:245], v186 offset:38912
	ds_read_b128 v[246:249], v186 offset:39936
	global_load_lds_dwordx4 v[254:255], off
	v_lshl_add_u64 v[254:255], s[66:67], 0, v[152:153]
	s_mov_b32 m0, s82
	s_nop 0
	global_load_lds_dwordx4 v[254:255], off
	s_waitcnt vmcnt(8) lgkmcnt(0)
	s_barrier
	s_setprio 1
	v_mfma_f32_16x16x32_bf16 v[126:129], v[138:141], v[218:221], v[126:129]
	v_mfma_f32_16x16x32_bf16 v[122:125], v[176:179], v[218:221], v[122:125]
	v_mfma_f32_16x16x32_bf16 v[110:113], v[138:141], v[226:229], v[110:113]
	v_mfma_f32_16x16x32_bf16 v[106:109], v[176:179], v[226:229], v[106:109]
	v_mfma_f32_16x16x32_bf16 v[94:97], v[138:141], v[234:237], v[94:97]
	v_mfma_f32_16x16x32_bf16 v[90:93], v[176:179], v[234:237], v[90:93]
	v_mfma_f32_16x16x32_bf16 v[78:81], v[138:141], v[242:245], v[78:81]
	v_mfma_f32_16x16x32_bf16 v[74:77], v[176:179], v[242:245], v[74:77]
	v_mfma_f32_16x16x32_bf16 v[126:129], v[142:145], v[222:225], v[126:129]
	v_mfma_f32_16x16x32_bf16 v[122:125], v[198:201], v[222:225], v[122:125]
	v_mfma_f32_16x16x32_bf16 v[110:113], v[142:145], v[230:233], v[110:113]
	v_mfma_f32_16x16x32_bf16 v[106:109], v[198:201], v[230:233], v[106:109]
	v_mfma_f32_16x16x32_bf16 v[94:97], v[142:145], v[238:241], v[94:97]
	v_mfma_f32_16x16x32_bf16 v[90:93], v[198:201], v[238:241], v[90:93]
	v_mfma_f32_16x16x32_bf16 v[78:81], v[142:145], v[246:249], v[78:81]
	v_mfma_f32_16x16x32_bf16 v[74:77], v[198:201], v[246:249], v[74:77]
	v_mfma_f32_16x16x32_bf16 v[118:121], v[202:205], v[218:221], v[118:121]
	v_mfma_f32_16x16x32_bf16 v[114:117], v[210:213], v[218:221], v[114:117]
	v_mfma_f32_16x16x32_bf16 v[102:105], v[202:205], v[226:229], v[102:105]
	v_mfma_f32_16x16x32_bf16 v[98:101], v[210:213], v[226:229], v[98:101]
	v_mfma_f32_16x16x32_bf16 v[86:89], v[202:205], v[234:237], v[86:89]
	v_mfma_f32_16x16x32_bf16 v[82:85], v[210:213], v[234:237], v[82:85]
	v_mfma_f32_16x16x32_bf16 v[70:73], v[202:205], v[242:245], v[70:73]
	v_mfma_f32_16x16x32_bf16 v[66:69], v[210:213], v[242:245], v[66:69]
	v_mfma_f32_16x16x32_bf16 v[118:121], v[206:209], v[222:225], v[118:121]
	v_mfma_f32_16x16x32_bf16 v[114:117], v[214:217], v[222:225], v[114:117]
	v_mfma_f32_16x16x32_bf16 v[102:105], v[206:209], v[230:233], v[102:105]
	v_mfma_f32_16x16x32_bf16 v[98:101], v[214:217], v[230:233], v[98:101]
	v_mfma_f32_16x16x32_bf16 v[86:89], v[206:209], v[238:241], v[86:89]
	v_mfma_f32_16x16x32_bf16 v[82:85], v[214:217], v[238:241], v[82:85]
	v_mfma_f32_16x16x32_bf16 v[70:73], v[206:209], v[246:249], v[70:73]
	v_mfma_f32_16x16x32_bf16 v[66:69], v[214:217], v[246:249], v[66:69]
	s_setprio 0
	s_barrier
; #define PG8_STAGE(bufoff, gbase, voff) do { _Pragma("unroll") for (int _i = 0; _i < 2; ++_i) \
;         __builtin_amdgcn_global_load_lds((const unsigned*)((const char*)(gbase) + (voff)[_i]), (LAS unsigned*)(lds + (bufoff) + ldsw + _i * 8192), 16, 0, 0); } while (0)
; #define PG8_LDA(dst, b, h) do { _Pragma("unroll") for (int m = 0; m < 4; ++m) _Pragma("unroll") for (int k = 0; k < 2; ++k) dst[m][k] = *(const LAS bf16x8*)(lds + PG8_SA(b, h) + aoff + m * 2048 + k * 1024); } while (0)
; #define PG8_MMA(ai, bj, At, Bt) do { __builtin_amdgcn_s_setprio(1); _Pragma("unroll") for (int m = 0; m < 4; ++m) _Pragma("unroll") for (int n = 0; n < 2; ++n) _Pragma("unroll") for (int k = 0; k < 2; ++k) \
;         acc[ai][bj][m][n] = __builtin_amdgcn_mfma_f32_16x16x32_bf16(Bt[n][k], At[m][k], acc[ai][bj][m][n], 0, 0, 0); __builtin_amdgcn_s_setprio(0); } while (0)
; #define PG8_WAIT_V(n) asm volatile("s_waitcnt vmcnt(" #n ")" ::: "memory")
; #define PG8_WAIT_L(n) asm volatile("s_waitcnt lgkmcnt(" #n ")" ::: "memory")
; #define PG8_BAR __builtin_amdgcn_s_barrier()
; #define PG8_SCHED __builtin_amdgcn_sched_barrier(0)
; template <class Epi, class Sched>
; DI void gemm_phase(LAS unsigned char* lds, const Gemm g, const Sched& S, const Epi& E) {
;     ...
;             PG8_LDA(At, 1, 1); PG8_STAGE(PG8_SB(1, 0), b3, voffB); PG8_STAGE(PG8_SB(1, 1), b3 + hstepB, voffB); PG8_STAGE(PG8_SA(1, 0), a3, voffA);
;             PG8_WAIT_V(8); PG8_WAIT_L(0); PG8_BAR; PG8_MMA(1, 0, At, B0); PG8_MMA(1, 1, At, B1); PG8_BAR; PG8_SCHED;
;         }
;         if (wr == 0) PG8_BAR;
	s_add_i32 s66, s70, s78
	v_lshl_add_u64 v[172:173], v[172:173], 0, s[50:51]
	s_mov_b32 m0, s66
	ds_read_b128 v[218:221], v186 offset:49152
	ds_read_b128 v[222:225], v186 offset:50176
	ds_read_b128 v[226:229], v186 offset:51200
	ds_read_b128 v[230:233], v186 offset:52224
	ds_read_b128 v[234:237], v186 offset:53248
	ds_read_b128 v[238:241], v186 offset:54272
	ds_read_b128 v[242:245], v186 offset:55296
	ds_read_b128 v[246:249], v186 offset:56320
	global_load_lds_dwordx4 v[172:173], off
	s_add_i32 m0, s66, 0x2000
	s_add_u32 s64, s64, 0x40080
	v_lshl_add_u64 v[172:173], v[180:181], 0, s[50:51]
	s_addc_u32 s65, s65, 0
	s_add_i32 s66, s71, s78
	global_load_lds_dwordx4 v[172:173], off
	v_lshl_add_u64 v[172:173], s[64:65], 0, v[150:151]
	s_mov_b32 m0, s66
	s_nop 0
	global_load_lds_dwordx4 v[172:173], off
	v_lshl_add_u64 v[172:173], s[64:65], 0, v[154:155]
	s_add_i32 m0, s66, 0x2000
	s_nop 0
	global_load_lds_dwordx4 v[172:173], off
	v_lshl_add_u64 v[172:173], v[250:251], 0, s[50:51]
	s_mov_b32 m0, s86
	s_nop 0
	global_load_lds_dwordx4 v[172:173], off
	v_lshl_add_u64 v[172:173], v[252:253], 0, s[50:51]
	s_mov_b32 m0, s87
	s_nop 0
	global_load_lds_dwordx4 v[172:173], off
	s_waitcnt vmcnt(8) lgkmcnt(0)
	s_barrier
	s_setprio 1
	v_mfma_f32_16x16x32_bf16 v[62:65], v[138:141], v[218:221], v[62:65]
	v_mfma_f32_16x16x32_bf16 v[58:61], v[176:179], v[218:221], v[58:61]
	v_mfma_f32_16x16x32_bf16 v[46:49], v[138:141], v[226:229], v[46:49]
	v_mfma_f32_16x16x32_bf16 v[42:45], v[176:179], v[226:229], v[42:45]
	v_mfma_f32_16x16x32_bf16 v[30:33], v[138:141], v[234:237], v[30:33]
	v_mfma_f32_16x16x32_bf16 v[26:29], v[176:179], v[234:237], v[26:29]
	v_mfma_f32_16x16x32_bf16 v[14:17], v[138:141], v[242:245], v[14:17]
	v_mfma_f32_16x16x32_bf16 v[10:13], v[176:179], v[242:245], v[10:13]
	v_mfma_f32_16x16x32_bf16 v[62:65], v[142:145], v[222:225], v[62:65]
	v_mfma_f32_16x16x32_bf16 v[58:61], v[198:201], v[222:225], v[58:61]
	v_mfma_f32_16x16x32_bf16 v[46:49], v[142:145], v[230:233], v[46:49]
	v_mfma_f32_16x16x32_bf16 v[42:45], v[198:201], v[230:233], v[42:45]
	v_mfma_f32_16x16x32_bf16 v[30:33], v[142:145], v[238:241], v[30:33]
	v_mfma_f32_16x16x32_bf16 v[26:29], v[198:201], v[238:241], v[26:29]
	v_mfma_f32_16x16x32_bf16 v[14:17], v[142:145], v[246:249], v[14:17]
	v_mfma_f32_16x16x32_bf16 v[10:13], v[198:201], v[246:249], v[10:13]
	v_mfma_f32_16x16x32_bf16 v[54:57], v[202:205], v[218:221], v[54:57]
	v_mfma_f32_16x16x32_bf16 v[50:53], v[210:213], v[218:221], v[50:53]
	v_mfma_f32_16x16x32_bf16 v[38:41], v[202:205], v[226:229], v[38:41]
	v_mfma_f32_16x16x32_bf16 v[34:37], v[210:213], v[226:229], v[34:37]
	v_mfma_f32_16x16x32_bf16 v[22:25], v[202:205], v[234:237], v[22:25]
	v_mfma_f32_16x16x32_bf16 v[18:21], v[210:213], v[234:237], v[18:21]
	v_mfma_f32_16x16x32_bf16 v[6:9], v[202:205], v[242:245], v[6:9]
	v_mfma_f32_16x16x32_bf16 v[2:5], v[210:213], v[242:245], v[2:5]
	v_mfma_f32_16x16x32_bf16 v[54:57], v[206:209], v[222:225], v[54:57]
	v_mfma_f32_16x16x32_bf16 v[50:53], v[214:217], v[222:225], v[50:53]
	v_mfma_f32_16x16x32_bf16 v[38:41], v[206:209], v[230:233], v[38:41]
	v_mfma_f32_16x16x32_bf16 v[34:37], v[214:217], v[230:233], v[34:37]
	v_mfma_f32_16x16x32_bf16 v[22:25], v[206:209], v[238:241], v[22:25]
	v_mfma_f32_16x16x32_bf16 v[18:21], v[214:217], v[238:241], v[18:21]
	v_mfma_f32_16x16x32_bf16 v[6:9], v[206:209], v[246:249], v[6:9]
	v_mfma_f32_16x16x32_bf16 v[2:5], v[214:217], v[246:249], v[2:5]
	s_setprio 0
	s_barrier
	s_add_i32 s69, s69, 2
	s_add_u32 s10, s10, 0x100
	s_addc_u32 s11, s11, 0
	s_add_u32 s59, s59, 0x100
	s_addc_u32 s68, s68, 0
	s_cmp_gt_u32 s69, 13
	s_cbranch_scc0 .LBB0_381
	s_and_b64 vcc, exec, s[52:53]
	s_cbranch_vccnz .LBB0_386
	s_cmp_gt_i32 s12, 4
	s_mov_b64 s[10:11], -1
	s_cbranch_scc1 .LBB0_387

; #define PG8_STAGE(bufoff, gbase, voff) do { _Pragma("unroll") for (int _i = 0; _i < 2; ++_i) \
;         __builtin_amdgcn_global_load_lds((const unsigned*)((const char*)(gbase) + (voff)[_i]), (LAS unsigned*)(lds + (bufoff) + ldsw + _i * 8192), 16, 0, 0); } while (0)
; #define PG8_LDA(dst, b, h) do { _Pragma("unroll") for (int m = 0; m < 4; ++m) _Pragma("unroll") for (int k = 0; k < 2; ++k) dst[m][k] = *(const LAS bf16x8*)(lds + PG8_SA(b, h) + aoff + m * 2048 + k * 1024); } while (0)
; #define PG8_LDB(dst, b, h) do { _Pragma("unroll") for (int n = 0; n < 2; ++n) _Pragma("unroll") for (int k = 0; k < 2; ++k) dst[n][k] = *(const LAS bf16x8*)(lds + PG8_SB(b, h) + boff + n * 2048 + k * 1024); } while (0)
; #define PG8_MMA(ai, bj, At, Bt) do { __builtin_amdgcn_s_setprio(1); _Pragma("unroll") for (int m = 0; m < 4; ++m) _Pragma("unroll") for (int n = 0; n < 2; ++n) _Pragma("unroll") for (int k = 0; k < 2; ++k) \
;         acc[ai][bj][m][n] = __builtin_amdgcn_mfma_f32_16x16x32_bf16(Bt[n][k], At[m][k], acc[ai][bj][m][n], 0, 0, 0); __builtin_amdgcn_s_setprio(0); } while (0)
; #define PG8_WAIT_V(n) asm volatile("s_waitcnt vmcnt(" #n ")" ::: "memory")
; #define PG8_WAIT_L(n) asm volatile("s_waitcnt lgkmcnt(" #n ")" ::: "memory")
; #define PG8_BAR __builtin_amdgcn_s_barrier()
; #define PG8_SCHED __builtin_amdgcn_sched_barrier(0)
; template <class Epi, class Sched>
; DI void gemm_phase(LAS unsigned char* lds, const Gemm g, const Sched& S, const Epi& E) {
;     ...
;         for (int t = 0; t < nt; t += 2) {
;             const bool last = (t == nt - 2);
;             const char* a1 = cA + (size_t)(t + 1) * kstep;
;             const char* a2 = last ? nA : cA + (size_t)(t + 2) * kstep; const char* b2 = last ? nB : cB + (size_t)(t + 2) * kstep;
;             const char* a3 = a2 + kstep; const char* b3 = b2 + kstep;
;             PG8_LDB(B0, 0, 0); PG8_LDB(B1, 0, 1); PG8_SCHED; PG8_LDA(At, 0, 0); PG8_STAGE(PG8_SA(1, 1), a1 + hstepA, voffA);
;             PG8_WAIT_V(8); PG8_WAIT_L(0); PG8_BAR; PG8_MMA(0, 0, At, B0); PG8_MMA(0, 1, At, B1); PG8_BAR; PG8_SCHED;
.LBB0_579:
	ds_read_b128 v[150:153], v142
	ds_read_b128 v[154:157], v142 offset:1024
	ds_read_b128 v[158:161], v142 offset:2048
	ds_read_b128 v[162:165], v142 offset:3072
	ds_read_b128 v[166:169], v143
	ds_read_b128 v[170:173], v143 offset:1024
	ds_read_b128 v[174:177], v143 offset:2048
	ds_read_b128 v[178:181], v143 offset:3072
	s_add_u32 s16, s8, s12
	s_addc_u32 s17, s9, s13
	s_add_u32 s16, s16, 0x100
	s_addc_u32 s17, s17, 0
	s_add_u32 s52, s39, s12
	s_addc_u32 s53, s40, s13
	s_cmpk_eq_i32 s12, 0xf00
	s_cselect_b32 s19, s9, s17
	s_cselect_b32 s18, s8, s16
	s_cselect_b32 s17, s7, s53
	s_cselect_b32 s16, s6, s52
	s_mov_b32 m0, s42
	v_lshl_add_u64 v[182:183], v[138:139], 0, s[12:13]
	ds_read_b128 v[186:189], v145
	ds_read_b128 v[190:193], v145 offset:1024
	ds_read_b128 v[194:197], v145 offset:2048
	ds_read_b128 v[198:201], v145 offset:3072
	ds_read_b128 v[202:205], v145 offset:4096
	ds_read_b128 v[206:209], v145 offset:5120
	ds_read_b128 v[210:213], v145 offset:6144
	ds_read_b128 v[214:217], v145 offset:7168
	global_load_lds_dwordx4 v[182:183], off
	v_lshl_add_u64 v[182:183], v[140:141], 0, s[12:13]
	s_mov_b32 m0, s43
	s_nop 0
	global_load_lds_dwordx4 v[182:183], off
	s_waitcnt vmcnt(8) lgkmcnt(0)
	s_barrier
	s_setprio 1
	v_mfma_f32_16x16x32_bf16 v[126:129], v[150:153], v[186:189], v[126:129]
	v_mfma_f32_16x16x32_bf16 v[122:125], v[158:161], v[186:189], v[122:125]
	v_mfma_f32_16x16x32_bf16 v[118:121], v[150:153], v[194:197], v[118:121]
	v_mfma_f32_16x16x32_bf16 v[114:117], v[158:161], v[194:197], v[114:117]
	v_mfma_f32_16x16x32_bf16 v[110:113], v[150:153], v[202:205], v[110:113]
	v_mfma_f32_16x16x32_bf16 v[106:109], v[158:161], v[202:205], v[106:109]
	v_mfma_f32_16x16x32_bf16 v[102:105], v[150:153], v[210:213], v[102:105]
	v_mfma_f32_16x16x32_bf16 v[98:101], v[158:161], v[210:213], v[98:101]
	v_mfma_f32_16x16x32_bf16 v[126:129], v[154:157], v[190:193], v[126:129]
	v_mfma_f32_16x16x32_bf16 v[122:125], v[162:165], v[190:193], v[122:125]
	v_mfma_f32_16x16x32_bf16 v[118:121], v[154:157], v[198:201], v[118:121]
	v_mfma_f32_16x16x32_bf16 v[114:117], v[162:165], v[198:201], v[114:117]
	v_mfma_f32_16x16x32_bf16 v[110:113], v[154:157], v[206:209], v[110:113]
	v_mfma_f32_16x16x32_bf16 v[106:109], v[162:165], v[206:209], v[106:109]
	v_mfma_f32_16x16x32_bf16 v[102:105], v[154:157], v[214:217], v[102:105]
	v_mfma_f32_16x16x32_bf16 v[98:101], v[162:165], v[214:217], v[98:101]
	v_mfma_f32_16x16x32_bf16 v[62:65], v[166:169], v[186:189], v[62:65]
	v_mfma_f32_16x16x32_bf16 v[58:61], v[174:177], v[186:189], v[58:61]
	v_mfma_f32_16x16x32_bf16 v[54:57], v[166:169], v[194:197], v[54:57]
	v_mfma_f32_16x16x32_bf16 v[50:53], v[174:177], v[194:197], v[50:53]
	v_mfma_f32_16x16x32_bf16 v[46:49], v[166:169], v[202:205], v[46:49]
	v_mfma_f32_16x16x32_bf16 v[42:45], v[174:177], v[202:205], v[42:45]
	v_mfma_f32_16x16x32_bf16 v[38:41], v[166:169], v[210:213], v[38:41]
	v_mfma_f32_16x16x32_bf16 v[34:37], v[174:177], v[210:213], v[34:37]
	v_mfma_f32_16x16x32_bf16 v[62:65], v[170:173], v[190:193], v[62:65]
	v_mfma_f32_16x16x32_bf16 v[58:61], v[178:181], v[190:193], v[58:61]
	v_mfma_f32_16x16x32_bf16 v[54:57], v[170:173], v[198:201], v[54:57]
	v_mfma_f32_16x16x32_bf16 v[50:53], v[178:181], v[198:201], v[50:53]
	v_mfma_f32_16x16x32_bf16 v[46:49], v[170:173], v[206:209], v[46:49]
	v_mfma_f32_16x16x32_bf16 v[42:45], v[178:181], v[206:209], v[42:45]
	v_mfma_f32_16x16x32_bf16 v[38:41], v[170:173], v[214:217], v[38:41]
	v_mfma_f32_16x16x32_bf16 v[34:37], v[178:181], v[214:217], v[34:37]
	s_setprio 0
	s_barrier
	s_mov_b32 m0, s44
	v_lshl_add_u64 v[182:183], s[16:17], 0, v[134:135]
	s_add_u32 s52, s16, 0x80000
	ds_read_b128 v[186:189], v145 offset:16384
	ds_read_b128 v[190:193], v145 offset:17408
	ds_read_b128 v[194:197], v145 offset:18432
	ds_read_b128 v[198:201], v145 offset:19456
	ds_read_b128 v[202:205], v145 offset:20480
	ds_read_b128 v[206:209], v145 offset:21504
	ds_read_b128 v[210:213], v145 offset:22528
	ds_read_b128 v[214:217], v145 offset:23552
	global_load_lds_dwordx4 v[182:183], off
	v_lshl_add_u64 v[218:219], s[16:17], 0, v[130:131]
	s_mov_b32 m0, s45
	s_addc_u32 s53, s17, 0
	global_load_lds_dwordx4 v[218:219], off
	v_lshl_add_u64 v[220:221], s[52:53], 0, v[134:135]
	s_mov_b32 m0, s46
	v_lshl_add_u64 v[222:223], s[18:19], 0, v[132:133]
	global_load_lds_dwordx4 v[220:221], off
	v_lshl_add_u64 v[220:221], s[52:53], 0, v[130:131]
	s_mov_b32 m0, s47
	s_nop 0
	global_load_lds_dwordx4 v[220:221], off
	v_lshl_add_u64 v[220:221], s[18:19], 0, v[136:137]
	s_mov_b32 m0, s28
	s_nop 0
	global_load_lds_dwordx4 v[220:221], off
	s_mov_b32 m0, s29
	s_nop 0
	global_load_lds_dwordx4 v[222:223], off
	s_waitcnt vmcnt(8) lgkmcnt(0)
	s_barrier
; #define PG8_STAGE(bufoff, gbase, voff) do { _Pragma("unroll") for (int _i = 0; _i < 2; ++_i) \
;         __builtin_amdgcn_global_load_lds((const unsigned*)((const char*)(gbase) + (voff)[_i]), (LAS unsigned*)(lds + (bufoff) + ldsw + _i * 8192), 16, 0, 0); } while (0)
; #define PG8_LDA(dst, b, h) do { _Pragma("unroll") for (int m = 0; m < 4; ++m) _Pragma("unroll") for (int k = 0; k < 2; ++k) dst[m][k] = *(const LAS bf16x8*)(lds + PG8_SA(b, h) + aoff + m * 2048 + k * 1024); } while (0)
; #define PG8_LDB(dst, b, h) do { _Pragma("unroll") for (int n = 0; n < 2; ++n) _Pragma("unroll") for (int k = 0; k < 2; ++k) dst[n][k] = *(const LAS bf16x8*)(lds + PG8_SB(b, h) + boff + n * 2048 + k * 1024); } while (0)
; #define PG8_MMA(ai, bj, At, Bt) do { __builtin_amdgcn_s_setprio(1); _Pragma("unroll") for (int m = 0; m < 4; ++m) _Pragma("unroll") for (int n = 0; n < 2; ++n) _Pragma("unroll") for (int k = 0; k < 2; ++k) \
;         acc[ai][bj][m][n] = __builtin_amdgcn_mfma_f32_16x16x32_bf16(Bt[n][k], At[m][k], acc[ai][bj][m][n], 0, 0, 0); __builtin_amdgcn_s_setprio(0); } while (0)
; #define PG8_WAIT_V(n) asm volatile("s_waitcnt vmcnt(" #n ")" ::: "memory")
; #define PG8_WAIT_L(n) asm volatile("s_waitcnt lgkmcnt(" #n ")" ::: "memory")
; #define PG8_BAR __builtin_amdgcn_s_barrier()
; #define PG8_SCHED __builtin_amdgcn_sched_barrier(0)
; template <class Epi, class Sched>
; DI void gemm_phase(LAS unsigned char* lds, const Gemm g, const Sched& S, const Epi& E) {
;     ...
;             PG8_WAIT_V(8); PG8_WAIT_L(0); PG8_BAR; PG8_MMA(0, 0, At, B0); PG8_MMA(0, 1, At, B1); PG8_BAR; PG8_SCHED;
;             PG8_LDA(At, 0, 1); PG8_STAGE(PG8_SB(0, 0), b2, voffB); PG8_STAGE(PG8_SB(0, 1), b2 + hstepB, voffB); PG8_STAGE(PG8_SA(0, 0), a2, voffA);
;             PG8_WAIT_V(8); PG8_WAIT_L(0); PG8_BAR; PG8_MMA(1, 0, At, B0); PG8_MMA(1, 1, At, B1); PG8_BAR; PG8_SCHED;
;             PG8_LDB(B0, 1, 0); PG8_LDB(B1, 1, 1); PG8_SCHED; PG8_LDA(At, 1, 0); PG8_STAGE(PG8_SA(0, 1), a2 + hstepA, voffA);
;             PG8_WAIT_V(8); PG8_WAIT_L(0); PG8_BAR; PG8_MMA(0, 0, At, B0); PG8_MMA(0, 1, At, B1); PG8_BAR; PG8_SCHED;
	s_setprio 1
	v_mfma_f32_16x16x32_bf16 v[94:97], v[150:153], v[186:189], v[94:97]
	v_mfma_f32_16x16x32_bf16 v[90:93], v[158:161], v[186:189], v[90:93]
	v_mfma_f32_16x16x32_bf16 v[86:89], v[150:153], v[194:197], v[86:89]
	v_mfma_f32_16x16x32_bf16 v[82:85], v[158:161], v[194:197], v[82:85]
	v_mfma_f32_16x16x32_bf16 v[78:81], v[150:153], v[202:205], v[78:81]
	v_mfma_f32_16x16x32_bf16 v[74:77], v[158:161], v[202:205], v[74:77]
	v_mfma_f32_16x16x32_bf16 v[70:73], v[150:153], v[210:213], v[70:73]
	v_mfma_f32_16x16x32_bf16 v[66:69], v[158:161], v[210:213], v[66:69]
	v_mfma_f32_16x16x32_bf16 v[94:97], v[154:157], v[190:193], v[94:97]
	v_mfma_f32_16x16x32_bf16 v[90:93], v[162:165], v[190:193], v[90:93]
	v_mfma_f32_16x16x32_bf16 v[86:89], v[154:157], v[198:201], v[86:89]
	v_mfma_f32_16x16x32_bf16 v[82:85], v[162:165], v[198:201], v[82:85]
	v_mfma_f32_16x16x32_bf16 v[78:81], v[154:157], v[206:209], v[78:81]
	v_mfma_f32_16x16x32_bf16 v[74:77], v[162:165], v[206:209], v[74:77]
	v_mfma_f32_16x16x32_bf16 v[70:73], v[154:157], v[214:217], v[70:73]
	v_mfma_f32_16x16x32_bf16 v[66:69], v[162:165], v[214:217], v[66:69]
	v_mfma_f32_16x16x32_bf16 v[30:33], v[166:169], v[186:189], v[30:33]
	v_mfma_f32_16x16x32_bf16 v[26:29], v[174:177], v[186:189], v[26:29]
	v_mfma_f32_16x16x32_bf16 v[22:25], v[166:169], v[194:197], v[22:25]
	v_mfma_f32_16x16x32_bf16 v[18:21], v[174:177], v[194:197], v[18:21]
	v_mfma_f32_16x16x32_bf16 v[14:17], v[166:169], v[202:205], v[14:17]
	v_mfma_f32_16x16x32_bf16 v[10:13], v[174:177], v[202:205], v[10:13]
	v_mfma_f32_16x16x32_bf16 v[6:9], v[166:169], v[210:213], v[6:9]
	v_mfma_f32_16x16x32_bf16 v[2:5], v[174:177], v[210:213], v[2:5]
	v_mfma_f32_16x16x32_bf16 v[30:33], v[170:173], v[190:193], v[30:33]
	v_mfma_f32_16x16x32_bf16 v[26:29], v[178:181], v[190:193], v[26:29]
	v_mfma_f32_16x16x32_bf16 v[22:25], v[170:173], v[198:201], v[22:25]
	v_mfma_f32_16x16x32_bf16 v[18:21], v[178:181], v[198:201], v[18:21]
	v_mfma_f32_16x16x32_bf16 v[14:17], v[170:173], v[206:209], v[14:17]
	v_mfma_f32_16x16x32_bf16 v[10:13], v[178:181], v[206:209], v[10:13]
	v_mfma_f32_16x16x32_bf16 v[6:9], v[170:173], v[214:217], v[6:9]
	v_mfma_f32_16x16x32_bf16 v[2:5], v[178:181], v[214:217], v[2:5]
	s_setprio 0
	s_barrier
	ds_read_b128 v[150:153], v147
	ds_read_b128 v[154:157], v147 offset:1024
	ds_read_b128 v[158:161], v147 offset:2048
	ds_read_b128 v[162:165], v147 offset:3072
	ds_read_b128 v[166:169], v148
	ds_read_b128 v[170:173], v148 offset:1024
	ds_read_b128 v[174:177], v148 offset:2048
	ds_read_b128 v[178:181], v148 offset:3072
	s_add_u32 s18, s18, 0x40000
	s_addc_u32 s19, s19, 0
	s_mov_b32 m0, s34
	v_lshl_add_u64 v[224:225], s[18:19], 0, v[136:137]
	ds_read_b128 v[186:189], v145 offset:32768
	ds_read_b128 v[190:193], v145 offset:33792
	ds_read_b128 v[194:197], v145 offset:34816
	ds_read_b128 v[198:201], v145 offset:35840
	ds_read_b128 v[202:205], v145 offset:36864
	ds_read_b128 v[206:209], v145 offset:37888
	ds_read_b128 v[210:213], v145 offset:38912
	ds_read_b128 v[214:217], v145 offset:39936
	global_load_lds_dwordx4 v[224:225], off
	v_lshl_add_u64 v[224:225], s[18:19], 0, v[132:133]
	s_mov_b32 m0, s35
	s_nop 0
	global_load_lds_dwordx4 v[224:225], off
	s_waitcnt vmcnt(8) lgkmcnt(0)
	s_barrier
	s_setprio 1
	v_mfma_f32_16x16x32_bf16 v[126:129], v[150:153], v[186:189], v[126:129]
	v_mfma_f32_16x16x32_bf16 v[122:125], v[158:161], v[186:189], v[122:125]
	v_mfma_f32_16x16x32_bf16 v[118:121], v[150:153], v[194:197], v[118:121]
	v_mfma_f32_16x16x32_bf16 v[114:117], v[158:161], v[194:197], v[114:117]
	v_mfma_f32_16x16x32_bf16 v[110:113], v[150:153], v[202:205], v[110:113]
	v_mfma_f32_16x16x32_bf16 v[106:109], v[158:161], v[202:205], v[106:109]
	v_mfma_f32_16x16x32_bf16 v[102:105], v[150:153], v[210:213], v[102:105]
	v_mfma_f32_16x16x32_bf16 v[98:101], v[158:161], v[210:213], v[98:101]
	v_mfma_f32_16x16x32_bf16 v[126:129], v[154:157], v[190:193], v[126:129]
	v_mfma_f32_16x16x32_bf16 v[122:125], v[162:165], v[190:193], v[122:125]
	v_mfma_f32_16x16x32_bf16 v[118:121], v[154:157], v[198:201], v[118:121]
	v_mfma_f32_16x16x32_bf16 v[114:117], v[162:165], v[198:201], v[114:117]
	v_mfma_f32_16x16x32_bf16 v[110:113], v[154:157], v[206:209], v[110:113]
	v_mfma_f32_16x16x32_bf16 v[106:109], v[162:165], v[206:209], v[106:109]
	v_mfma_f32_16x16x32_bf16 v[102:105], v[154:157], v[214:217], v[102:105]
	v_mfma_f32_16x16x32_bf16 v[98:101], v[162:165], v[214:217], v[98:101]
	v_mfma_f32_16x16x32_bf16 v[62:65], v[166:169], v[186:189], v[62:65]
	v_mfma_f32_16x16x32_bf16 v[58:61], v[174:177], v[186:189], v[58:61]
	v_mfma_f32_16x16x32_bf16 v[54:57], v[166:169], v[194:197], v[54:57]
	v_mfma_f32_16x16x32_bf16 v[50:53], v[174:177], v[194:197], v[50:53]
	v_mfma_f32_16x16x32_bf16 v[46:49], v[166:169], v[202:205], v[46:49]
	v_mfma_f32_16x16x32_bf16 v[42:45], v[174:177], v[202:205], v[42:45]
	v_mfma_f32_16x16x32_bf16 v[38:41], v[166:169], v[210:213], v[38:41]
	v_mfma_f32_16x16x32_bf16 v[34:37], v[174:177], v[210:213], v[34:37]
	v_mfma_f32_16x16x32_bf16 v[62:65], v[170:173], v[190:193], v[62:65]
	v_mfma_f32_16x16x32_bf16 v[58:61], v[178:181], v[190:193], v[58:61]
	v_mfma_f32_16x16x32_bf16 v[54:57], v[170:173], v[198:201], v[54:57]
	v_mfma_f32_16x16x32_bf16 v[50:53], v[178:181], v[198:201], v[50:53]
	v_mfma_f32_16x16x32_bf16 v[46:49], v[170:173], v[206:209], v[46:49]
	v_mfma_f32_16x16x32_bf16 v[42:45], v[178:181], v[206:209], v[42:45]
	v_mfma_f32_16x16x32_bf16 v[38:41], v[170:173], v[214:217], v[38:41]
	v_mfma_f32_16x16x32_bf16 v[34:37], v[178:181], v[214:217], v[34:37]
	s_setprio 0
	s_barrier
; #define PG8_STAGE(bufoff, gbase, voff) do { _Pragma("unroll") for (int _i = 0; _i < 2; ++_i) \
;         __builtin_amdgcn_global_load_lds((const unsigned*)((const char*)(gbase) + (voff)[_i]), (LAS unsigned*)(lds + (bufoff) + ldsw + _i * 8192), 16, 0, 0); } while (0)
; #define PG8_LDA(dst, b, h) do { _Pragma("unroll") for (int m = 0; m < 4; ++m) _Pragma("unroll") for (int k = 0; k < 2; ++k) dst[m][k] = *(const LAS bf16x8*)(lds + PG8_SA(b, h) + aoff + m * 2048 + k * 1024); } while (0)
; #define PG8_MMA(ai, bj, At, Bt) do { __builtin_amdgcn_s_setprio(1); _Pragma("unroll") for (int m = 0; m < 4; ++m) _Pragma("unroll") for (int n = 0; n < 2; ++n) _Pragma("unroll") for (int k = 0; k < 2; ++k) \
;         acc[ai][bj][m][n] = __builtin_amdgcn_mfma_f32_16x16x32_bf16(Bt[n][k], At[m][k], acc[ai][bj][m][n], 0, 0, 0); __builtin_amdgcn_s_setprio(0); } while (0)
; #define PG8_WAIT_V(n) asm volatile("s_waitcnt vmcnt(" #n ")" ::: "memory")
; #define PG8_WAIT_L(n) asm volatile("s_waitcnt lgkmcnt(" #n ")" ::: "memory")
; #define PG8_BAR __builtin_amdgcn_s_barrier()
; #define PG8_SCHED __builtin_amdgcn_sched_barrier(0)
; template <class Epi, class Sched>
; DI void gemm_phase(LAS unsigned char* lds, const Gemm g, const Sched& S, const Epi& E) {
;     ...
;             PG8_LDA(At, 1, 1); PG8_STAGE(PG8_SB(1, 0), b3, voffB); PG8_STAGE(PG8_SB(1, 1), b3 + hstepB, voffB); PG8_STAGE(PG8_SA(1, 0), a3, voffA);
;             PG8_WAIT_V(8); PG8_WAIT_L(0); PG8_BAR; PG8_MMA(1, 0, At, B0); PG8_MMA(1, 1, At, B1); PG8_BAR; PG8_SCHED;
;         }
;         if (wr == 0) PG8_BAR;
	s_mov_b32 m0, s48
	v_lshl_add_u64 v[182:183], v[182:183], 0, s[10:11]
	s_add_u32 s16, s16, 0x80080
	ds_read_b128 v[186:189], v145 offset:49152
	ds_read_b128 v[190:193], v145 offset:50176
	ds_read_b128 v[194:197], v145 offset:51200
	ds_read_b128 v[198:201], v145 offset:52224
	ds_read_b128 v[202:205], v145 offset:53248
	ds_read_b128 v[206:209], v145 offset:54272
	ds_read_b128 v[210:213], v145 offset:55296
	ds_read_b128 v[214:217], v145 offset:56320
	global_load_lds_dwordx4 v[182:183], off
	v_lshl_add_u64 v[182:183], v[218:219], 0, s[10:11]
	s_mov_b32 m0, s49
	s_addc_u32 s17, s17, 0
	global_load_lds_dwordx4 v[182:183], off
	v_lshl_add_u64 v[182:183], s[16:17], 0, v[134:135]
	s_mov_b32 m0, s50
	s_nop 0
	global_load_lds_dwordx4 v[182:183], off
	v_lshl_add_u64 v[182:183], s[16:17], 0, v[130:131]
	s_mov_b32 m0, s51
	s_nop 0
	global_load_lds_dwordx4 v[182:183], off
	v_lshl_add_u64 v[182:183], v[220:221], 0, s[10:11]
	s_mov_b32 m0, s37
	s_nop 0
	global_load_lds_dwordx4 v[182:183], off
	v_lshl_add_u64 v[182:183], v[222:223], 0, s[10:11]
	s_mov_b32 m0, s38
	s_nop 0
	global_load_lds_dwordx4 v[182:183], off
	s_waitcnt vmcnt(8) lgkmcnt(0)
	s_barrier
	s_setprio 1
	v_mfma_f32_16x16x32_bf16 v[94:97], v[150:153], v[186:189], v[94:97]
	v_mfma_f32_16x16x32_bf16 v[90:93], v[158:161], v[186:189], v[90:93]
	v_mfma_f32_16x16x32_bf16 v[86:89], v[150:153], v[194:197], v[86:89]
	v_mfma_f32_16x16x32_bf16 v[82:85], v[158:161], v[194:197], v[82:85]
	v_mfma_f32_16x16x32_bf16 v[78:81], v[150:153], v[202:205], v[78:81]
	v_mfma_f32_16x16x32_bf16 v[74:77], v[158:161], v[202:205], v[74:77]
	v_mfma_f32_16x16x32_bf16 v[70:73], v[150:153], v[210:213], v[70:73]
	v_mfma_f32_16x16x32_bf16 v[66:69], v[158:161], v[210:213], v[66:69]
	v_mfma_f32_16x16x32_bf16 v[94:97], v[154:157], v[190:193], v[94:97]
	v_mfma_f32_16x16x32_bf16 v[90:93], v[162:165], v[190:193], v[90:93]
	v_mfma_f32_16x16x32_bf16 v[86:89], v[154:157], v[198:201], v[86:89]
	v_mfma_f32_16x16x32_bf16 v[82:85], v[162:165], v[198:201], v[82:85]
	v_mfma_f32_16x16x32_bf16 v[78:81], v[154:157], v[206:209], v[78:81]
	v_mfma_f32_16x16x32_bf16 v[74:77], v[162:165], v[206:209], v[74:77]
	v_mfma_f32_16x16x32_bf16 v[70:73], v[154:157], v[214:217], v[70:73]
	v_mfma_f32_16x16x32_bf16 v[66:69], v[162:165], v[214:217], v[66:69]
	v_mfma_f32_16x16x32_bf16 v[30:33], v[166:169], v[186:189], v[30:33]
	v_mfma_f32_16x16x32_bf16 v[26:29], v[174:177], v[186:189], v[26:29]
	v_mfma_f32_16x16x32_bf16 v[22:25], v[166:169], v[194:197], v[22:25]
	v_mfma_f32_16x16x32_bf16 v[18:21], v[174:177], v[194:197], v[18:21]
	v_mfma_f32_16x16x32_bf16 v[14:17], v[166:169], v[202:205], v[14:17]
	v_mfma_f32_16x16x32_bf16 v[10:13], v[174:177], v[202:205], v[10:13]
	v_mfma_f32_16x16x32_bf16 v[6:9], v[166:169], v[210:213], v[6:9]
	v_mfma_f32_16x16x32_bf16 v[2:5], v[174:177], v[210:213], v[2:5]
	v_mfma_f32_16x16x32_bf16 v[30:33], v[170:173], v[190:193], v[30:33]
	v_mfma_f32_16x16x32_bf16 v[26:29], v[178:181], v[190:193], v[26:29]
	v_mfma_f32_16x16x32_bf16 v[22:25], v[170:173], v[198:201], v[22:25]
	v_mfma_f32_16x16x32_bf16 v[18:21], v[178:181], v[198:201], v[18:21]
	v_mfma_f32_16x16x32_bf16 v[14:17], v[170:173], v[206:209], v[14:17]
	v_mfma_f32_16x16x32_bf16 v[10:13], v[178:181], v[206:209], v[10:13]
	v_mfma_f32_16x16x32_bf16 v[6:9], v[170:173], v[214:217], v[6:9]
	v_mfma_f32_16x16x32_bf16 v[2:5], v[178:181], v[214:217], v[2:5]
	s_setprio 0
	s_barrier
	s_add_i32 s41, s41, 2
	s_add_u32 s12, s12, 0x100
	s_addc_u32 s13, s13, 0
	s_cmp_gt_u32 s41, 29
	s_cbranch_scc0 .LBB0_579
	s_cmpk_lt_u32 s21, 0x100
	s_cbranch_scc0 .LBB0_582
	s_barrier

; #define PG8_STAGE(bufoff, gbase, voff) do { _Pragma("unroll") for (int _i = 0; _i < 2; ++_i) \
;         __builtin_amdgcn_global_load_lds((const unsigned*)((const char*)(gbase) + (voff)[_i]), (LAS unsigned*)(lds + (bufoff) + ldsw + _i * 8192), 16, 0, 0); } while (0)
; #define PG8_LDA(dst, b, h) do { _Pragma("unroll") for (int m = 0; m < 4; ++m) _Pragma("unroll") for (int k = 0; k < 2; ++k) dst[m][k] = *(const LAS bf16x8*)(lds + PG8_SA(b, h) + aoff + m * 2048 + k * 1024); } while (0)
; #define PG8_LDB(dst, b, h) do { _Pragma("unroll") for (int n = 0; n < 2; ++n) _Pragma("unroll") for (int k = 0; k < 2; ++k) dst[n][k] = *(const LAS bf16x8*)(lds + PG8_SB(b, h) + boff + n * 2048 + k * 1024); } while (0)
; #define PG8_MMA(ai, bj, At, Bt) do { __builtin_amdgcn_s_setprio(1); _Pragma("unroll") for (int m = 0; m < 4; ++m) _Pragma("unroll") for (int n = 0; n < 2; ++n) _Pragma("unroll") for (int k = 0; k < 2; ++k) \
;         acc[ai][bj][m][n] = __builtin_amdgcn_mfma_f32_16x16x32_bf16(Bt[n][k], At[m][k], acc[ai][bj][m][n], 0, 0, 0); __builtin_amdgcn_s_setprio(0); } while (0)
; #define PG8_WAIT_V(n) asm volatile("s_waitcnt vmcnt(" #n ")" ::: "memory")
; #define PG8_WAIT_L(n) asm volatile("s_waitcnt lgkmcnt(" #n ")" ::: "memory")
; #define PG8_BAR __builtin_amdgcn_s_barrier()
; #define PG8_SCHED __builtin_amdgcn_sched_barrier(0)
; template <class Epi, class Sched>
; DI void gemm_phase(LAS unsigned char* lds, const Gemm g, const Sched& S, const Epi& E) {
;     ...
;         for (int t = 0; t < nt; t += 2) {
;             const bool last = (t == nt - 2);
;             const char* a1 = cA + (size_t)(t + 1) * kstep;
;             const char* a2 = last ? nA : cA + (size_t)(t + 2) * kstep; const char* b2 = last ? nB : cB + (size_t)(t + 2) * kstep;
;             const char* a3 = a2 + kstep; const char* b3 = b2 + kstep;
;             PG8_LDB(B0, 0, 0); PG8_LDB(B1, 0, 1); PG8_SCHED; PG8_LDA(At, 0, 0); PG8_STAGE(PG8_SA(1, 1), a1 + hstepA, voffA);
;             PG8_WAIT_V(8); PG8_WAIT_L(0); PG8_BAR; PG8_MMA(0, 0, At, B0); PG8_MMA(0, 1, At, B1); PG8_BAR; PG8_SCHED;
.LBB0_972:
	v_add_u32_e32 v158, s64, v162
	v_add_u32_e32 v180, s65, v162
	ds_read_b128 v[146:149], v158
	ds_read_b128 v[150:153], v158 offset:1024
	ds_read_b128 v[154:157], v158 offset:2048
	ds_read_b128 v[158:161], v158 offset:3072
	ds_read_b128 v[168:171], v180
	ds_read_b128 v[172:175], v180 offset:1024
	ds_read_b128 v[176:179], v180 offset:2048
	ds_read_b128 v[180:183], v180 offset:3072
	s_add_u32 s46, s44, 0xfffe0080
	s_addc_u32 s47, s45, -1
	s_cmp_eq_u32 s72, 4
	s_cselect_b32 s49, s39, s47
	s_cselect_b32 s48, s68, s46
	s_cselect_b32 s47, s37, s71
	s_cselect_b32 s46, s69, s70
	v_lshl_add_u64 v[218:219], s[44:45], 0, v[138:139]
	s_add_i32 m0, s53, 0xc000
	ds_read_b128 v[186:189], v167
	ds_read_b128 v[190:193], v167 offset:1024
	ds_read_b128 v[194:197], v167 offset:2048
	ds_read_b128 v[198:201], v167 offset:3072
	ds_read_b128 v[202:205], v167 offset:4096
	ds_read_b128 v[206:209], v167 offset:5120
	ds_read_b128 v[210:213], v167 offset:6144
	ds_read_b128 v[214:217], v167 offset:7168
	global_load_lds_dwordx4 v[218:219], off
	v_lshl_add_u64 v[218:219], s[44:45], 0, v[140:141]
	s_add_i32 m0, s53, 0xe000
	s_nop 0
	global_load_lds_dwordx4 v[218:219], off
	s_waitcnt vmcnt(8) lgkmcnt(0)
	s_barrier
	s_setprio 1
	v_mfma_f32_16x16x32_bf16 v[126:129], v[146:149], v[186:189], v[126:129]
	v_mfma_f32_16x16x32_bf16 v[122:125], v[154:157], v[186:189], v[122:125]
	v_mfma_f32_16x16x32_bf16 v[118:121], v[146:149], v[194:197], v[118:121]
	v_mfma_f32_16x16x32_bf16 v[114:117], v[154:157], v[194:197], v[114:117]
	v_mfma_f32_16x16x32_bf16 v[110:113], v[146:149], v[202:205], v[110:113]
	v_mfma_f32_16x16x32_bf16 v[106:109], v[154:157], v[202:205], v[106:109]
	v_mfma_f32_16x16x32_bf16 v[102:105], v[146:149], v[210:213], v[102:105]
	v_mfma_f32_16x16x32_bf16 v[98:101], v[154:157], v[210:213], v[98:101]
	v_mfma_f32_16x16x32_bf16 v[126:129], v[150:153], v[190:193], v[126:129]
	v_mfma_f32_16x16x32_bf16 v[122:125], v[158:161], v[190:193], v[122:125]
	v_mfma_f32_16x16x32_bf16 v[118:121], v[150:153], v[198:201], v[118:121]
	v_mfma_f32_16x16x32_bf16 v[114:117], v[158:161], v[198:201], v[114:117]
	v_mfma_f32_16x16x32_bf16 v[110:113], v[150:153], v[206:209], v[110:113]
	v_mfma_f32_16x16x32_bf16 v[106:109], v[158:161], v[206:209], v[106:109]
	v_mfma_f32_16x16x32_bf16 v[102:105], v[150:153], v[214:217], v[102:105]
	v_mfma_f32_16x16x32_bf16 v[98:101], v[158:161], v[214:217], v[98:101]
	v_mfma_f32_16x16x32_bf16 v[94:97], v[168:171], v[186:189], v[94:97]
	v_mfma_f32_16x16x32_bf16 v[90:93], v[176:179], v[186:189], v[90:93]
	v_mfma_f32_16x16x32_bf16 v[86:89], v[168:171], v[194:197], v[86:89]
	v_mfma_f32_16x16x32_bf16 v[82:85], v[176:179], v[194:197], v[82:85]
	v_mfma_f32_16x16x32_bf16 v[78:81], v[168:171], v[202:205], v[78:81]
	v_mfma_f32_16x16x32_bf16 v[74:77], v[176:179], v[202:205], v[74:77]
	v_mfma_f32_16x16x32_bf16 v[70:73], v[168:171], v[210:213], v[70:73]
	v_mfma_f32_16x16x32_bf16 v[66:69], v[176:179], v[210:213], v[66:69]
	v_mfma_f32_16x16x32_bf16 v[94:97], v[172:175], v[190:193], v[94:97]
	v_mfma_f32_16x16x32_bf16 v[90:93], v[180:183], v[190:193], v[90:93]
	v_mfma_f32_16x16x32_bf16 v[86:89], v[172:175], v[198:201], v[86:89]
	v_mfma_f32_16x16x32_bf16 v[82:85], v[180:183], v[198:201], v[82:85]
	v_mfma_f32_16x16x32_bf16 v[78:81], v[172:175], v[206:209], v[78:81]
	v_mfma_f32_16x16x32_bf16 v[74:77], v[180:183], v[206:209], v[74:77]
	v_mfma_f32_16x16x32_bf16 v[70:73], v[172:175], v[214:217], v[70:73]
	v_mfma_f32_16x16x32_bf16 v[66:69], v[180:183], v[214:217], v[66:69]
	s_setprio 0
	s_barrier
	s_add_i32 s73, s64, s52
	v_lshl_add_u64 v[218:219], s[46:47], 0, v[132:133]
	s_mov_b32 m0, s73
	ds_read_b128 v[186:189], v167 offset:16384
	ds_read_b128 v[190:193], v167 offset:17408
	ds_read_b128 v[194:197], v167 offset:18432
	ds_read_b128 v[198:201], v167 offset:19456
	ds_read_b128 v[202:205], v167 offset:20480
	ds_read_b128 v[206:209], v167 offset:21504
	ds_read_b128 v[210:213], v167 offset:22528
	ds_read_b128 v[214:217], v167 offset:23552
	global_load_lds_dwordx4 v[218:219], off
	s_add_i32 m0, s73, 0x2000
	s_add_u32 s74, s46, 0x20000
	v_lshl_add_u64 v[220:221], s[46:47], 0, v[136:137]
	s_addc_u32 s75, s47, 0
	s_add_i32 s73, s65, s52
	global_load_lds_dwordx4 v[220:221], off
	v_lshl_add_u64 v[222:223], s[74:75], 0, v[132:133]
	s_mov_b32 m0, s73
	v_lshl_add_u64 v[224:225], s[48:49], 0, v[134:135]
	global_load_lds_dwordx4 v[222:223], off
	v_lshl_add_u64 v[222:223], s[74:75], 0, v[136:137]
	s_add_i32 m0, s73, 0x2000
	s_nop 0
	global_load_lds_dwordx4 v[222:223], off
	v_lshl_add_u64 v[222:223], s[48:49], 0, v[130:131]
	s_mov_b32 m0, s53
	s_nop 0
	global_load_lds_dwordx4 v[222:223], off
	s_mov_b32 m0, s54
	s_nop 0
	global_load_lds_dwordx4 v[224:225], off
	s_waitcnt vmcnt(8) lgkmcnt(0)
	s_barrier
; #define PG8_STAGE(bufoff, gbase, voff) do { _Pragma("unroll") for (int _i = 0; _i < 2; ++_i) \
;         __builtin_amdgcn_global_load_lds((const unsigned*)((const char*)(gbase) + (voff)[_i]), (LAS unsigned*)(lds + (bufoff) + ldsw + _i * 8192), 16, 0, 0); } while (0)
; #define PG8_LDA(dst, b, h) do { _Pragma("unroll") for (int m = 0; m < 4; ++m) _Pragma("unroll") for (int k = 0; k < 2; ++k) dst[m][k] = *(const LAS bf16x8*)(lds + PG8_SA(b, h) + aoff + m * 2048 + k * 1024); } while (0)
; #define PG8_LDB(dst, b, h) do { _Pragma("unroll") for (int n = 0; n < 2; ++n) _Pragma("unroll") for (int k = 0; k < 2; ++k) dst[n][k] = *(const LAS bf16x8*)(lds + PG8_SB(b, h) + boff + n * 2048 + k * 1024); } while (0)
; #define PG8_MMA(ai, bj, At, Bt) do { __builtin_amdgcn_s_setprio(1); _Pragma("unroll") for (int m = 0; m < 4; ++m) _Pragma("unroll") for (int n = 0; n < 2; ++n) _Pragma("unroll") for (int k = 0; k < 2; ++k) \
;         acc[ai][bj][m][n] = __builtin_amdgcn_mfma_f32_16x16x32_bf16(Bt[n][k], At[m][k], acc[ai][bj][m][n], 0, 0, 0); __builtin_amdgcn_s_setprio(0); } while (0)
; #define PG8_WAIT_V(n) asm volatile("s_waitcnt vmcnt(" #n ")" ::: "memory")
; #define PG8_WAIT_L(n) asm volatile("s_waitcnt lgkmcnt(" #n ")" ::: "memory")
; #define PG8_BAR __builtin_amdgcn_s_barrier()
; #define PG8_SCHED __builtin_amdgcn_sched_barrier(0)
; template <class Epi, class Sched>
; DI void gemm_phase(LAS unsigned char* lds, const Gemm g, const Sched& S, const Epi& E) {
;     ...
;             PG8_WAIT_V(8); PG8_WAIT_L(0); PG8_BAR; PG8_MMA(0, 0, At, B0); PG8_MMA(0, 1, At, B1); PG8_BAR; PG8_SCHED;
;             PG8_LDA(At, 0, 1); PG8_STAGE(PG8_SB(0, 0), b2, voffB); PG8_STAGE(PG8_SB(0, 1), b2 + hstepB, voffB); PG8_STAGE(PG8_SA(0, 0), a2, voffA);
;             PG8_WAIT_V(8); PG8_WAIT_L(0); PG8_BAR; PG8_MMA(1, 0, At, B0); PG8_MMA(1, 1, At, B1); PG8_BAR; PG8_SCHED;
;             PG8_LDB(B0, 1, 0); PG8_LDB(B1, 1, 1); PG8_SCHED; PG8_LDA(At, 1, 0); PG8_STAGE(PG8_SA(0, 1), a2 + hstepA, voffA);
;             PG8_WAIT_V(8); PG8_WAIT_L(0); PG8_BAR; PG8_MMA(0, 0, At, B0); PG8_MMA(0, 1, At, B1); PG8_BAR; PG8_SCHED;
	s_setprio 1
	v_mfma_f32_16x16x32_bf16 v[62:65], v[146:149], v[186:189], v[62:65]
	v_mfma_f32_16x16x32_bf16 v[58:61], v[154:157], v[186:189], v[58:61]
	v_mfma_f32_16x16x32_bf16 v[54:57], v[146:149], v[194:197], v[54:57]
	v_mfma_f32_16x16x32_bf16 v[50:53], v[154:157], v[194:197], v[50:53]
	v_mfma_f32_16x16x32_bf16 v[46:49], v[146:149], v[202:205], v[46:49]
	v_mfma_f32_16x16x32_bf16 v[42:45], v[154:157], v[202:205], v[42:45]
	v_mfma_f32_16x16x32_bf16 v[38:41], v[146:149], v[210:213], v[38:41]
	v_mfma_f32_16x16x32_bf16 v[34:37], v[154:157], v[210:213], v[34:37]
	v_mfma_f32_16x16x32_bf16 v[62:65], v[150:153], v[190:193], v[62:65]
	v_mfma_f32_16x16x32_bf16 v[58:61], v[158:161], v[190:193], v[58:61]
	v_mfma_f32_16x16x32_bf16 v[54:57], v[150:153], v[198:201], v[54:57]
	v_mfma_f32_16x16x32_bf16 v[50:53], v[158:161], v[198:201], v[50:53]
	v_mfma_f32_16x16x32_bf16 v[46:49], v[150:153], v[206:209], v[46:49]
	v_mfma_f32_16x16x32_bf16 v[42:45], v[158:161], v[206:209], v[42:45]
	v_mfma_f32_16x16x32_bf16 v[38:41], v[150:153], v[214:217], v[38:41]
	v_mfma_f32_16x16x32_bf16 v[34:37], v[158:161], v[214:217], v[34:37]
	v_mfma_f32_16x16x32_bf16 v[30:33], v[168:171], v[186:189], v[30:33]
	v_mfma_f32_16x16x32_bf16 v[26:29], v[176:179], v[186:189], v[26:29]
	v_mfma_f32_16x16x32_bf16 v[22:25], v[168:171], v[194:197], v[22:25]
	v_mfma_f32_16x16x32_bf16 v[18:21], v[176:179], v[194:197], v[18:21]
	v_mfma_f32_16x16x32_bf16 v[14:17], v[168:171], v[202:205], v[14:17]
	v_mfma_f32_16x16x32_bf16 v[10:13], v[176:179], v[202:205], v[10:13]
	v_mfma_f32_16x16x32_bf16 v[6:9], v[168:171], v[210:213], v[6:9]
	v_mfma_f32_16x16x32_bf16 v[2:5], v[176:179], v[210:213], v[2:5]
	v_mfma_f32_16x16x32_bf16 v[30:33], v[172:175], v[190:193], v[30:33]
	v_mfma_f32_16x16x32_bf16 v[26:29], v[180:183], v[190:193], v[26:29]
	v_mfma_f32_16x16x32_bf16 v[22:25], v[172:175], v[198:201], v[22:25]
	v_mfma_f32_16x16x32_bf16 v[18:21], v[180:183], v[198:201], v[18:21]
	v_mfma_f32_16x16x32_bf16 v[14:17], v[172:175], v[206:209], v[14:17]
	v_mfma_f32_16x16x32_bf16 v[10:13], v[180:183], v[206:209], v[10:13]
	v_mfma_f32_16x16x32_bf16 v[6:9], v[172:175], v[214:217], v[6:9]
	v_mfma_f32_16x16x32_bf16 v[2:5], v[180:183], v[214:217], v[2:5]
	s_setprio 0
	s_barrier
	s_add_i32 s73, 0, 0x18000
	s_add_i32 s74, 0, 0x1c000
	v_add_u32_e32 v158, s73, v162
	v_add_u32_e32 v180, s74, v162
	ds_read_b128 v[146:149], v158
	ds_read_b128 v[150:153], v158 offset:1024
	ds_read_b128 v[154:157], v158 offset:2048
	ds_read_b128 v[158:161], v158 offset:3072
	ds_read_b128 v[168:171], v180
	ds_read_b128 v[172:175], v180 offset:1024
	ds_read_b128 v[176:179], v180 offset:2048
	ds_read_b128 v[180:183], v180 offset:3072
	s_add_u32 s48, s48, 0x20000
	s_addc_u32 s49, s49, 0
	s_mov_b32 m0, s55
	v_lshl_add_u64 v[226:227], s[48:49], 0, v[130:131]
	ds_read_b128 v[186:189], v167 offset:32768
	ds_read_b128 v[190:193], v167 offset:33792
	ds_read_b128 v[194:197], v167 offset:34816
	ds_read_b128 v[198:201], v167 offset:35840
	ds_read_b128 v[202:205], v167 offset:36864
	ds_read_b128 v[206:209], v167 offset:37888
	ds_read_b128 v[210:213], v167 offset:38912
	ds_read_b128 v[214:217], v167 offset:39936
	global_load_lds_dwordx4 v[226:227], off
	v_lshl_add_u64 v[226:227], s[48:49], 0, v[134:135]
	s_mov_b32 m0, s56
	s_nop 0
	global_load_lds_dwordx4 v[226:227], off
	s_waitcnt vmcnt(8) lgkmcnt(0)
	s_barrier
	s_setprio 1
	v_mfma_f32_16x16x32_bf16 v[126:129], v[146:149], v[186:189], v[126:129]
	v_mfma_f32_16x16x32_bf16 v[122:125], v[154:157], v[186:189], v[122:125]
	v_mfma_f32_16x16x32_bf16 v[118:121], v[146:149], v[194:197], v[118:121]
	v_mfma_f32_16x16x32_bf16 v[114:117], v[154:157], v[194:197], v[114:117]
	v_mfma_f32_16x16x32_bf16 v[110:113], v[146:149], v[202:205], v[110:113]
	v_mfma_f32_16x16x32_bf16 v[106:109], v[154:157], v[202:205], v[106:109]
	v_mfma_f32_16x16x32_bf16 v[102:105], v[146:149], v[210:213], v[102:105]
	v_mfma_f32_16x16x32_bf16 v[98:101], v[154:157], v[210:213], v[98:101]
	v_mfma_f32_16x16x32_bf16 v[126:129], v[150:153], v[190:193], v[126:129]
	v_mfma_f32_16x16x32_bf16 v[122:125], v[158:161], v[190:193], v[122:125]
	v_mfma_f32_16x16x32_bf16 v[118:121], v[150:153], v[198:201], v[118:121]
	v_mfma_f32_16x16x32_bf16 v[114:117], v[158:161], v[198:201], v[114:117]
	v_mfma_f32_16x16x32_bf16 v[110:113], v[150:153], v[206:209], v[110:113]
	v_mfma_f32_16x16x32_bf16 v[106:109], v[158:161], v[206:209], v[106:109]
	v_mfma_f32_16x16x32_bf16 v[102:105], v[150:153], v[214:217], v[102:105]
	v_mfma_f32_16x16x32_bf16 v[98:101], v[158:161], v[214:217], v[98:101]
	v_mfma_f32_16x16x32_bf16 v[94:97], v[168:171], v[186:189], v[94:97]
	v_mfma_f32_16x16x32_bf16 v[90:93], v[176:179], v[186:189], v[90:93]
	v_mfma_f32_16x16x32_bf16 v[86:89], v[168:171], v[194:197], v[86:89]
	v_mfma_f32_16x16x32_bf16 v[82:85], v[176:179], v[194:197], v[82:85]
	v_mfma_f32_16x16x32_bf16 v[78:81], v[168:171], v[202:205], v[78:81]
	v_mfma_f32_16x16x32_bf16 v[74:77], v[176:179], v[202:205], v[74:77]
	v_mfma_f32_16x16x32_bf16 v[70:73], v[168:171], v[210:213], v[70:73]
	v_mfma_f32_16x16x32_bf16 v[66:69], v[176:179], v[210:213], v[66:69]
	v_mfma_f32_16x16x32_bf16 v[94:97], v[172:175], v[190:193], v[94:97]
	v_mfma_f32_16x16x32_bf16 v[90:93], v[180:183], v[190:193], v[90:93]
	v_mfma_f32_16x16x32_bf16 v[86:89], v[172:175], v[198:201], v[86:89]
	v_mfma_f32_16x16x32_bf16 v[82:85], v[180:183], v[198:201], v[82:85]
	v_mfma_f32_16x16x32_bf16 v[78:81], v[172:175], v[206:209], v[78:81]
	v_mfma_f32_16x16x32_bf16 v[74:77], v[180:183], v[206:209], v[74:77]
	v_mfma_f32_16x16x32_bf16 v[70:73], v[172:175], v[214:217], v[70:73]
	v_mfma_f32_16x16x32_bf16 v[66:69], v[180:183], v[214:217], v[66:69]
	s_setprio 0
	s_barrier
; #define PG8_STAGE(bufoff, gbase, voff) do { _Pragma("unroll") for (int _i = 0; _i < 2; ++_i) \
;         __builtin_amdgcn_global_load_lds((const unsigned*)((const char*)(gbase) + (voff)[_i]), (LAS unsigned*)(lds + (bufoff) + ldsw + _i * 8192), 16, 0, 0); } while (0)
; #define PG8_LDA(dst, b, h) do { _Pragma("unroll") for (int m = 0; m < 4; ++m) _Pragma("unroll") for (int k = 0; k < 2; ++k) dst[m][k] = *(const LAS bf16x8*)(lds + PG8_SA(b, h) + aoff + m * 2048 + k * 1024); } while (0)
; #define PG8_MMA(ai, bj, At, Bt) do { __builtin_amdgcn_s_setprio(1); _Pragma("unroll") for (int m = 0; m < 4; ++m) _Pragma("unroll") for (int n = 0; n < 2; ++n) _Pragma("unroll") for (int k = 0; k < 2; ++k) \
;         acc[ai][bj][m][n] = __builtin_amdgcn_mfma_f32_16x16x32_bf16(Bt[n][k], At[m][k], acc[ai][bj][m][n], 0, 0, 0); __builtin_amdgcn_s_setprio(0); } while (0)
; #define PG8_WAIT_V(n) asm volatile("s_waitcnt vmcnt(" #n ")" ::: "memory")
; #define PG8_WAIT_L(n) asm volatile("s_waitcnt lgkmcnt(" #n ")" ::: "memory")
; #define PG8_BAR __builtin_amdgcn_s_barrier()
; #define PG8_SCHED __builtin_amdgcn_sched_barrier(0)
; template <class Epi, class Sched>
; DI void gemm_phase(LAS unsigned char* lds, const Gemm g, const Sched& S, const Epi& E) {
;     ...
;             PG8_LDA(At, 1, 1); PG8_STAGE(PG8_SB(1, 0), b3, voffB); PG8_STAGE(PG8_SB(1, 1), b3 + hstepB, voffB); PG8_STAGE(PG8_SA(1, 0), a3, voffA);
;             PG8_WAIT_V(8); PG8_WAIT_L(0); PG8_BAR; PG8_MMA(1, 0, At, B0); PG8_MMA(1, 1, At, B1); PG8_BAR; PG8_SCHED;
;         }
;         if (wr == 0) PG8_BAR;
	s_add_i32 s48, s73, s52
	v_lshl_add_u64 v[218:219], v[218:219], 0, s[20:21]
	s_mov_b32 m0, s48
	ds_read_b128 v[186:189], v167 offset:49152
	ds_read_b128 v[190:193], v167 offset:50176
	ds_read_b128 v[194:197], v167 offset:51200
	ds_read_b128 v[198:201], v167 offset:52224
	ds_read_b128 v[202:205], v167 offset:53248
	ds_read_b128 v[206:209], v167 offset:54272
	ds_read_b128 v[210:213], v167 offset:55296
	ds_read_b128 v[214:217], v167 offset:56320
	global_load_lds_dwordx4 v[218:219], off
	s_add_i32 m0, s48, 0x2000
	s_add_u32 s46, s46, 0x20080
	v_lshl_add_u64 v[218:219], v[220:221], 0, s[20:21]
	s_addc_u32 s47, s47, 0
	s_add_i32 s48, s74, s52
	global_load_lds_dwordx4 v[218:219], off
	v_lshl_add_u64 v[218:219], s[46:47], 0, v[132:133]
	s_mov_b32 m0, s48
	s_nop 0
	global_load_lds_dwordx4 v[218:219], off
	v_lshl_add_u64 v[218:219], s[46:47], 0, v[136:137]
	s_add_i32 m0, s48, 0x2000
	s_nop 0
	global_load_lds_dwordx4 v[218:219], off
	v_lshl_add_u64 v[218:219], v[222:223], 0, s[20:21]
	s_mov_b32 m0, s61
	s_nop 0
	global_load_lds_dwordx4 v[218:219], off
	v_lshl_add_u64 v[218:219], v[224:225], 0, s[20:21]
	s_mov_b32 m0, s62
	s_nop 0
	global_load_lds_dwordx4 v[218:219], off
	s_waitcnt vmcnt(8) lgkmcnt(0)
	s_barrier
	s_setprio 1
	v_mfma_f32_16x16x32_bf16 v[62:65], v[146:149], v[186:189], v[62:65]
	v_mfma_f32_16x16x32_bf16 v[58:61], v[154:157], v[186:189], v[58:61]
	v_mfma_f32_16x16x32_bf16 v[54:57], v[146:149], v[194:197], v[54:57]
	v_mfma_f32_16x16x32_bf16 v[50:53], v[154:157], v[194:197], v[50:53]
	v_mfma_f32_16x16x32_bf16 v[46:49], v[146:149], v[202:205], v[46:49]
	v_mfma_f32_16x16x32_bf16 v[42:45], v[154:157], v[202:205], v[42:45]
	v_mfma_f32_16x16x32_bf16 v[38:41], v[146:149], v[210:213], v[38:41]
	v_mfma_f32_16x16x32_bf16 v[34:37], v[154:157], v[210:213], v[34:37]
	v_mfma_f32_16x16x32_bf16 v[62:65], v[150:153], v[190:193], v[62:65]
	v_mfma_f32_16x16x32_bf16 v[58:61], v[158:161], v[190:193], v[58:61]
	v_mfma_f32_16x16x32_bf16 v[54:57], v[150:153], v[198:201], v[54:57]
	v_mfma_f32_16x16x32_bf16 v[50:53], v[158:161], v[198:201], v[50:53]
	v_mfma_f32_16x16x32_bf16 v[46:49], v[150:153], v[206:209], v[46:49]
	v_mfma_f32_16x16x32_bf16 v[42:45], v[158:161], v[206:209], v[42:45]
	v_mfma_f32_16x16x32_bf16 v[38:41], v[150:153], v[214:217], v[38:41]
	v_mfma_f32_16x16x32_bf16 v[34:37], v[158:161], v[214:217], v[34:37]
	v_mfma_f32_16x16x32_bf16 v[30:33], v[168:171], v[186:189], v[30:33]
	v_mfma_f32_16x16x32_bf16 v[26:29], v[176:179], v[186:189], v[26:29]
	v_mfma_f32_16x16x32_bf16 v[22:25], v[168:171], v[194:197], v[22:25]
	v_mfma_f32_16x16x32_bf16 v[18:21], v[176:179], v[194:197], v[18:21]
	v_mfma_f32_16x16x32_bf16 v[14:17], v[168:171], v[202:205], v[14:17]
	v_mfma_f32_16x16x32_bf16 v[10:13], v[176:179], v[202:205], v[10:13]
	v_mfma_f32_16x16x32_bf16 v[6:9], v[168:171], v[210:213], v[6:9]
	v_mfma_f32_16x16x32_bf16 v[2:5], v[176:179], v[210:213], v[2:5]
	v_mfma_f32_16x16x32_bf16 v[30:33], v[172:175], v[190:193], v[30:33]
	v_mfma_f32_16x16x32_bf16 v[26:29], v[180:183], v[190:193], v[26:29]
	v_mfma_f32_16x16x32_bf16 v[22:25], v[172:175], v[198:201], v[22:25]
	v_mfma_f32_16x16x32_bf16 v[18:21], v[180:183], v[198:201], v[18:21]
	v_mfma_f32_16x16x32_bf16 v[14:17], v[172:175], v[206:209], v[14:17]
	v_mfma_f32_16x16x32_bf16 v[10:13], v[180:183], v[206:209], v[10:13]
	v_mfma_f32_16x16x32_bf16 v[6:9], v[172:175], v[214:217], v[6:9]
	v_mfma_f32_16x16x32_bf16 v[2:5], v[180:183], v[214:217], v[2:5]
	s_setprio 0
	s_barrier
	s_add_i32 s72, s72, 2
	s_add_u32 s44, s44, 0x100
	s_addc_u32 s45, s45, 0
	s_add_u32 s70, s70, 0x100
	s_addc_u32 s71, s71, 0
	s_cmp_gt_u32 s72, 5
	s_cbranch_scc0 .LBB0_972
	s_and_b64 vcc, exec, s[34:35]
	s_cbranch_vccz .LBB0_975
	s_barrier

; #define PG8_STAGE(bufoff, gbase, voff) do { _Pragma("unroll") for (int _i = 0; _i < 2; ++_i) \
;         __builtin_amdgcn_global_load_lds((const unsigned*)((const char*)(gbase) + (voff)[_i]), (LAS unsigned*)(lds + (bufoff) + ldsw + _i * 8192), 16, 0, 0); } while (0)
; #define PG8_LDA(dst, b, h) do { _Pragma("unroll") for (int m = 0; m < 4; ++m) _Pragma("unroll") for (int k = 0; k < 2; ++k) dst[m][k] = *(const LAS bf16x8*)(lds + PG8_SA(b, h) + aoff + m * 2048 + k * 1024); } while (0)
; #define PG8_LDB(dst, b, h) do { _Pragma("unroll") for (int n = 0; n < 2; ++n) _Pragma("unroll") for (int k = 0; k < 2; ++k) dst[n][k] = *(const LAS bf16x8*)(lds + PG8_SB(b, h) + boff + n * 2048 + k * 1024); } while (0)
; #define PG8_MMA(ai, bj, At, Bt) do { __builtin_amdgcn_s_setprio(1); _Pragma("unroll") for (int m = 0; m < 4; ++m) _Pragma("unroll") for (int n = 0; n < 2; ++n) _Pragma("unroll") for (int k = 0; k < 2; ++k) \
;         acc[ai][bj][m][n] = __builtin_amdgcn_mfma_f32_16x16x32_bf16(Bt[n][k], At[m][k], acc[ai][bj][m][n], 0, 0, 0); __builtin_amdgcn_s_setprio(0); } while (0)
; #define PG8_WAIT_V(n) asm volatile("s_waitcnt vmcnt(" #n ")" ::: "memory")
; #define PG8_WAIT_L(n) asm volatile("s_waitcnt lgkmcnt(" #n ")" ::: "memory")
; #define PG8_BAR __builtin_amdgcn_s_barrier()
; #define PG8_SCHED __builtin_amdgcn_sched_barrier(0)
; template <class Epi, class Sched>
; DI void gemm_phase(LAS unsigned char* lds, const Gemm g, const Sched& S, const Epi& E) {
;     ...
;         for (int t = 0; t < nt; t += 2) {
;             const bool last = (t == nt - 2);
;             const char* a1 = cA + (size_t)(t + 1) * kstep;
;             const char* a2 = last ? nA : cA + (size_t)(t + 2) * kstep; const char* b2 = last ? nB : cB + (size_t)(t + 2) * kstep;
;             const char* a3 = a2 + kstep; const char* b3 = b2 + kstep;
;             PG8_LDB(B0, 0, 0); PG8_LDB(B1, 0, 1); PG8_SCHED; PG8_LDA(At, 0, 0); PG8_STAGE(PG8_SA(1, 1), a1 + hstepA, voffA);
;             PG8_WAIT_V(8); PG8_WAIT_L(0); PG8_BAR; PG8_MMA(0, 0, At, B0); PG8_MMA(0, 1, At, B1); PG8_BAR; PG8_SCHED;
.LBB0_1133:
	ds_read_b128 v[146:149], v152
	ds_read_b128 v[156:159], v152 offset:1024
	ds_read_b128 v[160:163], v152 offset:2048
	ds_read_b128 v[164:167], v152 offset:3072
	ds_read_b128 v[168:171], v153
	ds_read_b128 v[172:175], v153 offset:1024
	ds_read_b128 v[176:179], v153 offset:2048
	ds_read_b128 v[180:183], v153 offset:3072
	s_add_u32 s46, s44, 0xfffc0080
	s_addc_u32 s47, s45, -1
	s_cmp_eq_u32 s66, 12
	s_cselect_b32 s49, s35, s47
	s_cselect_b32 s48, s41, s46
	s_cselect_b32 s47, s21, s65
	s_cselect_b32 s46, s63, s64
	v_lshl_add_u64 v[218:219], s[44:45], 0, v[138:139]
	s_add_i32 m0, s43, 0xc000
	ds_read_b128 v[186:189], v154
	ds_read_b128 v[190:193], v154 offset:1024
	ds_read_b128 v[194:197], v154 offset:2048
	ds_read_b128 v[198:201], v154 offset:3072
	ds_read_b128 v[202:205], v154 offset:4096
	ds_read_b128 v[206:209], v154 offset:5120
	ds_read_b128 v[210:213], v154 offset:6144
	ds_read_b128 v[214:217], v154 offset:7168
	global_load_lds_dwordx4 v[218:219], off
	v_lshl_add_u64 v[218:219], s[44:45], 0, v[140:141]
	s_add_i32 m0, s43, 0xe000
	s_nop 0
	global_load_lds_dwordx4 v[218:219], off
	s_waitcnt vmcnt(8) lgkmcnt(0)
	s_barrier
	s_setprio 1
	v_mfma_f32_16x16x32_bf16 v[126:129], v[146:149], v[186:189], v[126:129]
	v_mfma_f32_16x16x32_bf16 v[122:125], v[160:163], v[186:189], v[122:125]
	v_mfma_f32_16x16x32_bf16 v[110:113], v[146:149], v[194:197], v[110:113]
	v_mfma_f32_16x16x32_bf16 v[106:109], v[160:163], v[194:197], v[106:109]
	v_mfma_f32_16x16x32_bf16 v[94:97], v[146:149], v[202:205], v[94:97]
	v_mfma_f32_16x16x32_bf16 v[90:93], v[160:163], v[202:205], v[90:93]
	v_mfma_f32_16x16x32_bf16 v[78:81], v[146:149], v[210:213], v[78:81]
	v_mfma_f32_16x16x32_bf16 v[74:77], v[160:163], v[210:213], v[74:77]
	v_mfma_f32_16x16x32_bf16 v[126:129], v[156:159], v[190:193], v[126:129]
	v_mfma_f32_16x16x32_bf16 v[122:125], v[164:167], v[190:193], v[122:125]
	v_mfma_f32_16x16x32_bf16 v[110:113], v[156:159], v[198:201], v[110:113]
	v_mfma_f32_16x16x32_bf16 v[106:109], v[164:167], v[198:201], v[106:109]
	v_mfma_f32_16x16x32_bf16 v[94:97], v[156:159], v[206:209], v[94:97]
	v_mfma_f32_16x16x32_bf16 v[90:93], v[164:167], v[206:209], v[90:93]
	v_mfma_f32_16x16x32_bf16 v[78:81], v[156:159], v[214:217], v[78:81]
	v_mfma_f32_16x16x32_bf16 v[74:77], v[164:167], v[214:217], v[74:77]
	v_mfma_f32_16x16x32_bf16 v[118:121], v[168:171], v[186:189], v[118:121]
	v_mfma_f32_16x16x32_bf16 v[114:117], v[176:179], v[186:189], v[114:117]
	v_mfma_f32_16x16x32_bf16 v[102:105], v[168:171], v[194:197], v[102:105]
	v_mfma_f32_16x16x32_bf16 v[98:101], v[176:179], v[194:197], v[98:101]
	v_mfma_f32_16x16x32_bf16 v[86:89], v[168:171], v[202:205], v[86:89]
	v_mfma_f32_16x16x32_bf16 v[82:85], v[176:179], v[202:205], v[82:85]
	v_mfma_f32_16x16x32_bf16 v[70:73], v[168:171], v[210:213], v[70:73]
	v_mfma_f32_16x16x32_bf16 v[66:69], v[176:179], v[210:213], v[66:69]
	v_mfma_f32_16x16x32_bf16 v[118:121], v[172:175], v[190:193], v[118:121]
	v_mfma_f32_16x16x32_bf16 v[114:117], v[180:183], v[190:193], v[114:117]
	v_mfma_f32_16x16x32_bf16 v[102:105], v[172:175], v[198:201], v[102:105]
	v_mfma_f32_16x16x32_bf16 v[98:101], v[180:183], v[198:201], v[98:101]
	v_mfma_f32_16x16x32_bf16 v[86:89], v[172:175], v[206:209], v[86:89]
	v_mfma_f32_16x16x32_bf16 v[82:85], v[180:183], v[206:209], v[82:85]
	v_mfma_f32_16x16x32_bf16 v[70:73], v[172:175], v[214:217], v[70:73]
	v_mfma_f32_16x16x32_bf16 v[66:69], v[180:183], v[214:217], v[66:69]
	s_setprio 0
	s_barrier
	s_add_i32 s67, s61, s52
	v_lshl_add_u64 v[218:219], s[46:47], 0, v[132:133]
	s_mov_b32 m0, s67
	ds_read_b128 v[186:189], v154 offset:16384
	ds_read_b128 v[190:193], v154 offset:17408
	ds_read_b128 v[194:197], v154 offset:18432
	ds_read_b128 v[198:201], v154 offset:19456
	ds_read_b128 v[202:205], v154 offset:20480
	ds_read_b128 v[206:209], v154 offset:21504
	ds_read_b128 v[210:213], v154 offset:22528
	ds_read_b128 v[214:217], v154 offset:23552
	global_load_lds_dwordx4 v[218:219], off
	s_add_i32 m0, s67, 0x2000
	s_add_u32 s68, s46, 0x40000
	v_lshl_add_u64 v[220:221], s[46:47], 0, v[136:137]
	s_addc_u32 s69, s47, 0
	s_add_i32 s67, s62, s52
	global_load_lds_dwordx4 v[220:221], off
	v_lshl_add_u64 v[222:223], s[68:69], 0, v[132:133]
	s_mov_b32 m0, s67
	v_lshl_add_u64 v[224:225], s[48:49], 0, v[134:135]
	global_load_lds_dwordx4 v[222:223], off
	v_lshl_add_u64 v[222:223], s[68:69], 0, v[136:137]
	s_add_i32 m0, s67, 0x2000
	s_nop 0
	global_load_lds_dwordx4 v[222:223], off
	v_lshl_add_u64 v[222:223], s[48:49], 0, v[130:131]
	s_mov_b32 m0, s43
	s_nop 0
	global_load_lds_dwordx4 v[222:223], off
	s_mov_b32 m0, s53
	s_nop 0
	global_load_lds_dwordx4 v[224:225], off
	s_waitcnt vmcnt(8) lgkmcnt(0)
	s_barrier
; #define PG8_STAGE(bufoff, gbase, voff) do { _Pragma("unroll") for (int _i = 0; _i < 2; ++_i) \
;         __builtin_amdgcn_global_load_lds((const unsigned*)((const char*)(gbase) + (voff)[_i]), (LAS unsigned*)(lds + (bufoff) + ldsw + _i * 8192), 16, 0, 0); } while (0)
; #define PG8_LDA(dst, b, h) do { _Pragma("unroll") for (int m = 0; m < 4; ++m) _Pragma("unroll") for (int k = 0; k < 2; ++k) dst[m][k] = *(const LAS bf16x8*)(lds + PG8_SA(b, h) + aoff + m * 2048 + k * 1024); } while (0)
; #define PG8_LDB(dst, b, h) do { _Pragma("unroll") for (int n = 0; n < 2; ++n) _Pragma("unroll") for (int k = 0; k < 2; ++k) dst[n][k] = *(const LAS bf16x8*)(lds + PG8_SB(b, h) + boff + n * 2048 + k * 1024); } while (0)
; #define PG8_MMA(ai, bj, At, Bt) do { __builtin_amdgcn_s_setprio(1); _Pragma("unroll") for (int m = 0; m < 4; ++m) _Pragma("unroll") for (int n = 0; n < 2; ++n) _Pragma("unroll") for (int k = 0; k < 2; ++k) \
;         acc[ai][bj][m][n] = __builtin_amdgcn_mfma_f32_16x16x32_bf16(Bt[n][k], At[m][k], acc[ai][bj][m][n], 0, 0, 0); __builtin_amdgcn_s_setprio(0); } while (0)
; #define PG8_WAIT_V(n) asm volatile("s_waitcnt vmcnt(" #n ")" ::: "memory")
; #define PG8_WAIT_L(n) asm volatile("s_waitcnt lgkmcnt(" #n ")" ::: "memory")
; #define PG8_BAR __builtin_amdgcn_s_barrier()
; #define PG8_SCHED __builtin_amdgcn_sched_barrier(0)
; template <class Epi, class Sched>
; DI void gemm_phase(LAS unsigned char* lds, const Gemm g, const Sched& S, const Epi& E) {
;     ...
;             PG8_WAIT_V(8); PG8_WAIT_L(0); PG8_BAR; PG8_MMA(0, 0, At, B0); PG8_MMA(0, 1, At, B1); PG8_BAR; PG8_SCHED;
;             PG8_LDA(At, 0, 1); PG8_STAGE(PG8_SB(0, 0), b2, voffB); PG8_STAGE(PG8_SB(0, 1), b2 + hstepB, voffB); PG8_STAGE(PG8_SA(0, 0), a2, voffA);
;             PG8_WAIT_V(8); PG8_WAIT_L(0); PG8_BAR; PG8_MMA(1, 0, At, B0); PG8_MMA(1, 1, At, B1); PG8_BAR; PG8_SCHED;
;             PG8_LDB(B0, 1, 0); PG8_LDB(B1, 1, 1); PG8_SCHED; PG8_LDA(At, 1, 0); PG8_STAGE(PG8_SA(0, 1), a2 + hstepA, voffA);
;             PG8_WAIT_V(8); PG8_WAIT_L(0); PG8_BAR; PG8_MMA(0, 0, At, B0); PG8_MMA(0, 1, At, B1); PG8_BAR; PG8_SCHED;
	s_setprio 1
	v_mfma_f32_16x16x32_bf16 v[62:65], v[146:149], v[186:189], v[62:65]
	v_mfma_f32_16x16x32_bf16 v[58:61], v[160:163], v[186:189], v[58:61]
	v_mfma_f32_16x16x32_bf16 v[46:49], v[146:149], v[194:197], v[46:49]
	v_mfma_f32_16x16x32_bf16 v[42:45], v[160:163], v[194:197], v[42:45]
	v_mfma_f32_16x16x32_bf16 v[30:33], v[146:149], v[202:205], v[30:33]
	v_mfma_f32_16x16x32_bf16 v[26:29], v[160:163], v[202:205], v[26:29]
	v_mfma_f32_16x16x32_bf16 v[14:17], v[146:149], v[210:213], v[14:17]
	v_mfma_f32_16x16x32_bf16 v[10:13], v[160:163], v[210:213], v[10:13]
	v_mfma_f32_16x16x32_bf16 v[62:65], v[156:159], v[190:193], v[62:65]
	v_mfma_f32_16x16x32_bf16 v[58:61], v[164:167], v[190:193], v[58:61]
	v_mfma_f32_16x16x32_bf16 v[46:49], v[156:159], v[198:201], v[46:49]
	v_mfma_f32_16x16x32_bf16 v[42:45], v[164:167], v[198:201], v[42:45]
	v_mfma_f32_16x16x32_bf16 v[30:33], v[156:159], v[206:209], v[30:33]
	v_mfma_f32_16x16x32_bf16 v[26:29], v[164:167], v[206:209], v[26:29]
	v_mfma_f32_16x16x32_bf16 v[14:17], v[156:159], v[214:217], v[14:17]
	v_mfma_f32_16x16x32_bf16 v[10:13], v[164:167], v[214:217], v[10:13]
	v_mfma_f32_16x16x32_bf16 v[54:57], v[168:171], v[186:189], v[54:57]
	v_mfma_f32_16x16x32_bf16 v[50:53], v[176:179], v[186:189], v[50:53]
	v_mfma_f32_16x16x32_bf16 v[38:41], v[168:171], v[194:197], v[38:41]
	v_mfma_f32_16x16x32_bf16 v[34:37], v[176:179], v[194:197], v[34:37]
	v_mfma_f32_16x16x32_bf16 v[22:25], v[168:171], v[202:205], v[22:25]
	v_mfma_f32_16x16x32_bf16 v[18:21], v[176:179], v[202:205], v[18:21]
	v_mfma_f32_16x16x32_bf16 v[6:9], v[168:171], v[210:213], v[6:9]
	v_mfma_f32_16x16x32_bf16 v[2:5], v[176:179], v[210:213], v[2:5]
	v_mfma_f32_16x16x32_bf16 v[54:57], v[172:175], v[190:193], v[54:57]
	v_mfma_f32_16x16x32_bf16 v[50:53], v[180:183], v[190:193], v[50:53]
	v_mfma_f32_16x16x32_bf16 v[38:41], v[172:175], v[198:201], v[38:41]
	v_mfma_f32_16x16x32_bf16 v[34:37], v[180:183], v[198:201], v[34:37]
	v_mfma_f32_16x16x32_bf16 v[22:25], v[172:175], v[206:209], v[22:25]
	v_mfma_f32_16x16x32_bf16 v[18:21], v[180:183], v[206:209], v[18:21]
	v_mfma_f32_16x16x32_bf16 v[6:9], v[172:175], v[214:217], v[6:9]
	v_mfma_f32_16x16x32_bf16 v[2:5], v[180:183], v[214:217], v[2:5]
	s_setprio 0
	s_barrier
	s_add_i32 s67, 0, 0x18000
	s_add_i32 s68, 0, 0x1c000
	v_add_u32_e32 v164, s67, v150
	v_add_u32_e32 v180, s68, v150
	ds_read_b128 v[146:149], v164
	ds_read_b128 v[156:159], v164 offset:1024
	ds_read_b128 v[160:163], v164 offset:2048
	ds_read_b128 v[164:167], v164 offset:3072
	ds_read_b128 v[168:171], v180
	ds_read_b128 v[172:175], v180 offset:1024
	ds_read_b128 v[176:179], v180 offset:2048
	ds_read_b128 v[180:183], v180 offset:3072
	s_add_u32 s48, s48, 0x40000
	s_addc_u32 s49, s49, 0
	s_mov_b32 m0, s54
	v_lshl_add_u64 v[226:227], s[48:49], 0, v[130:131]
	ds_read_b128 v[186:189], v154 offset:32768
	ds_read_b128 v[190:193], v154 offset:33792
	ds_read_b128 v[194:197], v154 offset:34816
	ds_read_b128 v[198:201], v154 offset:35840
	ds_read_b128 v[202:205], v154 offset:36864
	ds_read_b128 v[206:209], v154 offset:37888
	ds_read_b128 v[210:213], v154 offset:38912
	ds_read_b128 v[214:217], v154 offset:39936
	global_load_lds_dwordx4 v[226:227], off
	v_lshl_add_u64 v[226:227], s[48:49], 0, v[134:135]
	s_mov_b32 m0, s55
	s_nop 0
	global_load_lds_dwordx4 v[226:227], off
	s_waitcnt vmcnt(8) lgkmcnt(0)
	s_barrier
	s_setprio 1
	v_mfma_f32_16x16x32_bf16 v[126:129], v[146:149], v[186:189], v[126:129]
	v_mfma_f32_16x16x32_bf16 v[122:125], v[160:163], v[186:189], v[122:125]
	v_mfma_f32_16x16x32_bf16 v[110:113], v[146:149], v[194:197], v[110:113]
	v_mfma_f32_16x16x32_bf16 v[106:109], v[160:163], v[194:197], v[106:109]
	v_mfma_f32_16x16x32_bf16 v[94:97], v[146:149], v[202:205], v[94:97]
	v_mfma_f32_16x16x32_bf16 v[90:93], v[160:163], v[202:205], v[90:93]
	v_mfma_f32_16x16x32_bf16 v[78:81], v[146:149], v[210:213], v[78:81]
	v_mfma_f32_16x16x32_bf16 v[74:77], v[160:163], v[210:213], v[74:77]
	v_mfma_f32_16x16x32_bf16 v[126:129], v[156:159], v[190:193], v[126:129]
	v_mfma_f32_16x16x32_bf16 v[122:125], v[164:167], v[190:193], v[122:125]
	v_mfma_f32_16x16x32_bf16 v[110:113], v[156:159], v[198:201], v[110:113]
	v_mfma_f32_16x16x32_bf16 v[106:109], v[164:167], v[198:201], v[106:109]
	v_mfma_f32_16x16x32_bf16 v[94:97], v[156:159], v[206:209], v[94:97]
	v_mfma_f32_16x16x32_bf16 v[90:93], v[164:167], v[206:209], v[90:93]
	v_mfma_f32_16x16x32_bf16 v[78:81], v[156:159], v[214:217], v[78:81]
	v_mfma_f32_16x16x32_bf16 v[74:77], v[164:167], v[214:217], v[74:77]
	v_mfma_f32_16x16x32_bf16 v[118:121], v[168:171], v[186:189], v[118:121]
	v_mfma_f32_16x16x32_bf16 v[114:117], v[176:179], v[186:189], v[114:117]
	v_mfma_f32_16x16x32_bf16 v[102:105], v[168:171], v[194:197], v[102:105]
	v_mfma_f32_16x16x32_bf16 v[98:101], v[176:179], v[194:197], v[98:101]
	v_mfma_f32_16x16x32_bf16 v[86:89], v[168:171], v[202:205], v[86:89]
	v_mfma_f32_16x16x32_bf16 v[82:85], v[176:179], v[202:205], v[82:85]
	v_mfma_f32_16x16x32_bf16 v[70:73], v[168:171], v[210:213], v[70:73]
	v_mfma_f32_16x16x32_bf16 v[66:69], v[176:179], v[210:213], v[66:69]
	v_mfma_f32_16x16x32_bf16 v[118:121], v[172:175], v[190:193], v[118:121]
	v_mfma_f32_16x16x32_bf16 v[114:117], v[180:183], v[190:193], v[114:117]
	v_mfma_f32_16x16x32_bf16 v[102:105], v[172:175], v[198:201], v[102:105]
	v_mfma_f32_16x16x32_bf16 v[98:101], v[180:183], v[198:201], v[98:101]
	v_mfma_f32_16x16x32_bf16 v[86:89], v[172:175], v[206:209], v[86:89]
	v_mfma_f32_16x16x32_bf16 v[82:85], v[180:183], v[206:209], v[82:85]
	v_mfma_f32_16x16x32_bf16 v[70:73], v[172:175], v[214:217], v[70:73]
	v_mfma_f32_16x16x32_bf16 v[66:69], v[180:183], v[214:217], v[66:69]
	s_setprio 0
	s_barrier
; #define PG8_STAGE(bufoff, gbase, voff) do { _Pragma("unroll") for (int _i = 0; _i < 2; ++_i) \
;         __builtin_amdgcn_global_load_lds((const unsigned*)((const char*)(gbase) + (voff)[_i]), (LAS unsigned*)(lds + (bufoff) + ldsw + _i * 8192), 16, 0, 0); } while (0)
; #define PG8_LDA(dst, b, h) do { _Pragma("unroll") for (int m = 0; m < 4; ++m) _Pragma("unroll") for (int k = 0; k < 2; ++k) dst[m][k] = *(const LAS bf16x8*)(lds + PG8_SA(b, h) + aoff + m * 2048 + k * 1024); } while (0)
; #define PG8_MMA(ai, bj, At, Bt) do { __builtin_amdgcn_s_setprio(1); _Pragma("unroll") for (int m = 0; m < 4; ++m) _Pragma("unroll") for (int n = 0; n < 2; ++n) _Pragma("unroll") for (int k = 0; k < 2; ++k) \
;         acc[ai][bj][m][n] = __builtin_amdgcn_mfma_f32_16x16x32_bf16(Bt[n][k], At[m][k], acc[ai][bj][m][n], 0, 0, 0); __builtin_amdgcn_s_setprio(0); } while (0)
; #define PG8_WAIT_V(n) asm volatile("s_waitcnt vmcnt(" #n ")" ::: "memory")
; #define PG8_WAIT_L(n) asm volatile("s_waitcnt lgkmcnt(" #n ")" ::: "memory")
; #define PG8_BAR __builtin_amdgcn_s_barrier()
; #define PG8_SCHED __builtin_amdgcn_sched_barrier(0)
; template <class Epi, class Sched>
; DI void gemm_phase(LAS unsigned char* lds, const Gemm g, const Sched& S, const Epi& E) {
;     ...
;             PG8_LDA(At, 1, 1); PG8_STAGE(PG8_SB(1, 0), b3, voffB); PG8_STAGE(PG8_SB(1, 1), b3 + hstepB, voffB); PG8_STAGE(PG8_SA(1, 0), a3, voffA);
;             PG8_WAIT_V(8); PG8_WAIT_L(0); PG8_BAR; PG8_MMA(1, 0, At, B0); PG8_MMA(1, 1, At, B1); PG8_BAR; PG8_SCHED;
;         }
;         if (wr == 0) PG8_BAR;
	s_add_i32 s48, s67, s52
	v_lshl_add_u64 v[218:219], v[218:219], 0, s[16:17]
	s_mov_b32 m0, s48
	ds_read_b128 v[186:189], v154 offset:49152
	ds_read_b128 v[190:193], v154 offset:50176
	ds_read_b128 v[194:197], v154 offset:51200
	ds_read_b128 v[198:201], v154 offset:52224
	ds_read_b128 v[202:205], v154 offset:53248
	ds_read_b128 v[206:209], v154 offset:54272
	ds_read_b128 v[210:213], v154 offset:55296
	ds_read_b128 v[214:217], v154 offset:56320
	global_load_lds_dwordx4 v[218:219], off
	s_add_i32 m0, s48, 0x2000
	s_add_u32 s46, s46, 0x40080
	v_lshl_add_u64 v[218:219], v[220:221], 0, s[16:17]
	s_addc_u32 s47, s47, 0
	s_add_i32 s48, s68, s52
	global_load_lds_dwordx4 v[218:219], off
	v_lshl_add_u64 v[218:219], s[46:47], 0, v[132:133]
	s_mov_b32 m0, s48
	s_nop 0
	global_load_lds_dwordx4 v[218:219], off
	v_lshl_add_u64 v[218:219], s[46:47], 0, v[136:137]
	s_add_i32 m0, s48, 0x2000
	s_nop 0
	global_load_lds_dwordx4 v[218:219], off
	v_lshl_add_u64 v[218:219], v[222:223], 0, s[16:17]
	s_mov_b32 m0, s57
	s_nop 0
	global_load_lds_dwordx4 v[218:219], off
	v_lshl_add_u64 v[218:219], v[224:225], 0, s[16:17]
	s_mov_b32 m0, s58
	s_nop 0
	global_load_lds_dwordx4 v[218:219], off
	s_waitcnt vmcnt(8) lgkmcnt(0)
	s_barrier
	s_setprio 1
	v_mfma_f32_16x16x32_bf16 v[62:65], v[146:149], v[186:189], v[62:65]
	v_mfma_f32_16x16x32_bf16 v[58:61], v[160:163], v[186:189], v[58:61]
	v_mfma_f32_16x16x32_bf16 v[46:49], v[146:149], v[194:197], v[46:49]
	v_mfma_f32_16x16x32_bf16 v[42:45], v[160:163], v[194:197], v[42:45]
	v_mfma_f32_16x16x32_bf16 v[30:33], v[146:149], v[202:205], v[30:33]
	v_mfma_f32_16x16x32_bf16 v[26:29], v[160:163], v[202:205], v[26:29]
	v_mfma_f32_16x16x32_bf16 v[14:17], v[146:149], v[210:213], v[14:17]
	v_mfma_f32_16x16x32_bf16 v[10:13], v[160:163], v[210:213], v[10:13]
	v_mfma_f32_16x16x32_bf16 v[62:65], v[156:159], v[190:193], v[62:65]
	v_mfma_f32_16x16x32_bf16 v[58:61], v[164:167], v[190:193], v[58:61]
	v_mfma_f32_16x16x32_bf16 v[46:49], v[156:159], v[198:201], v[46:49]
	v_mfma_f32_16x16x32_bf16 v[42:45], v[164:167], v[198:201], v[42:45]
	v_mfma_f32_16x16x32_bf16 v[30:33], v[156:159], v[206:209], v[30:33]
	v_mfma_f32_16x16x32_bf16 v[26:29], v[164:167], v[206:209], v[26:29]
	v_mfma_f32_16x16x32_bf16 v[14:17], v[156:159], v[214:217], v[14:17]
	v_mfma_f32_16x16x32_bf16 v[10:13], v[164:167], v[214:217], v[10:13]
	v_mfma_f32_16x16x32_bf16 v[54:57], v[168:171], v[186:189], v[54:57]
	v_mfma_f32_16x16x32_bf16 v[50:53], v[176:179], v[186:189], v[50:53]
	v_mfma_f32_16x16x32_bf16 v[38:41], v[168:171], v[194:197], v[38:41]
	v_mfma_f32_16x16x32_bf16 v[34:37], v[176:179], v[194:197], v[34:37]
	v_mfma_f32_16x16x32_bf16 v[22:25], v[168:171], v[202:205], v[22:25]
	v_mfma_f32_16x16x32_bf16 v[18:21], v[176:179], v[202:205], v[18:21]
	v_mfma_f32_16x16x32_bf16 v[6:9], v[168:171], v[210:213], v[6:9]
	v_mfma_f32_16x16x32_bf16 v[2:5], v[176:179], v[210:213], v[2:5]
	v_mfma_f32_16x16x32_bf16 v[54:57], v[172:175], v[190:193], v[54:57]
	v_mfma_f32_16x16x32_bf16 v[50:53], v[180:183], v[190:193], v[50:53]
	v_mfma_f32_16x16x32_bf16 v[38:41], v[172:175], v[198:201], v[38:41]
	v_mfma_f32_16x16x32_bf16 v[34:37], v[180:183], v[198:201], v[34:37]
	v_mfma_f32_16x16x32_bf16 v[22:25], v[172:175], v[206:209], v[22:25]
	v_mfma_f32_16x16x32_bf16 v[18:21], v[180:183], v[206:209], v[18:21]
	v_mfma_f32_16x16x32_bf16 v[6:9], v[172:175], v[214:217], v[6:9]
	v_mfma_f32_16x16x32_bf16 v[2:5], v[180:183], v[214:217], v[2:5]
	s_setprio 0
	s_barrier
	s_add_i32 s66, s66, 2
	s_add_u32 s44, s44, 0x100
	s_addc_u32 s45, s45, 0
	s_add_u32 s64, s64, 0x100
	s_addc_u32 s65, s65, 0
	s_cmp_gt_u32 s66, 13
	s_cbranch_scc0 .LBB0_1133
	s_and_b64 vcc, exec, s[18:19]
	s_cbranch_vccz .LBB0_1136
	s_barrier

; #define PG8_STAGE(bufoff, gbase, voff) do { _Pragma("unroll") for (int _i = 0; _i < 2; ++_i) \
;         __builtin_amdgcn_global_load_lds((const unsigned*)((const char*)(gbase) + (voff)[_i]), (LAS unsigned*)(lds + (bufoff) + ldsw + _i * 8192), 16, 0, 0); } while (0)
; #define PG8_LDA(dst, b, h) do { _Pragma("unroll") for (int m = 0; m < 4; ++m) _Pragma("unroll") for (int k = 0; k < 2; ++k) dst[m][k] = *(const LAS bf16x8*)(lds + PG8_SA(b, h) + aoff + m * 2048 + k * 1024); } while (0)
; #define PG8_LDB(dst, b, h) do { _Pragma("unroll") for (int n = 0; n < 2; ++n) _Pragma("unroll") for (int k = 0; k < 2; ++k) dst[n][k] = *(const LAS bf16x8*)(lds + PG8_SB(b, h) + boff + n * 2048 + k * 1024); } while (0)
; #define PG8_MMA(ai, bj, At, Bt) do { __builtin_amdgcn_s_setprio(1); _Pragma("unroll") for (int m = 0; m < 4; ++m) _Pragma("unroll") for (int n = 0; n < 2; ++n) _Pragma("unroll") for (int k = 0; k < 2; ++k) \
;         acc[ai][bj][m][n] = __builtin_amdgcn_mfma_f32_16x16x32_bf16(Bt[n][k], At[m][k], acc[ai][bj][m][n], 0, 0, 0); __builtin_amdgcn_s_setprio(0); } while (0)
; #define PG8_WAIT_V(n) asm volatile("s_waitcnt vmcnt(" #n ")" ::: "memory")
; #define PG8_WAIT_L(n) asm volatile("s_waitcnt lgkmcnt(" #n ")" ::: "memory")
; #define PG8_BAR __builtin_amdgcn_s_barrier()
; #define PG8_SCHED __builtin_amdgcn_sched_barrier(0)
; template <class Epi, class Sched>
; DI void gemm_phase(LAS unsigned char* lds, const Gemm g, const Sched& S, const Epi& E) {
;     ...
;         for (int t = 0; t < nt; t += 2) {
;             const bool last = (t == nt - 2);
;             const char* a1 = cA + (size_t)(t + 1) * kstep;
;             const char* a2 = last ? nA : cA + (size_t)(t + 2) * kstep; const char* b2 = last ? nB : cB + (size_t)(t + 2) * kstep;
;             const char* a3 = a2 + kstep; const char* b3 = b2 + kstep;
;             PG8_LDB(B0, 0, 0); PG8_LDB(B1, 0, 1); PG8_SCHED; PG8_LDA(At, 0, 0); PG8_STAGE(PG8_SA(1, 1), a1 + hstepA, voffA);
;             PG8_WAIT_V(8); PG8_WAIT_L(0); PG8_BAR; PG8_MMA(0, 0, At, B0); PG8_MMA(0, 1, At, B1); PG8_BAR; PG8_SCHED;
.LBB0_1234:
	ds_read_b128 v[166:169], v160
	ds_read_b128 v[170:173], v160 offset:1024
	ds_read_b128 v[174:177], v160 offset:2048
	ds_read_b128 v[178:181], v160 offset:3072
	ds_read_b128 v[186:189], v161
	ds_read_b128 v[190:193], v161 offset:1024
	ds_read_b128 v[194:197], v161 offset:2048
	ds_read_b128 v[198:201], v161 offset:3072
	s_add_u32 s42, s40, 0xfffc0080
	s_addc_u32 s43, s41, -1
	s_cmp_eq_u32 s65, 12
	s_cselect_b32 s45, s35, s43
	s_cselect_b32 s44, s61, s42
	s_cselect_b32 s43, s21, s64
	s_cselect_b32 s42, s62, s63
	v_lshl_add_u64 v[182:183], s[40:41], 0, v[138:139]
	s_add_i32 m0, s49, 0xc000
	ds_read_b128 v[202:205], v158
	ds_read_b128 v[206:209], v158 offset:1024
	ds_read_b128 v[210:213], v158 offset:2048
	ds_read_b128 v[214:217], v158 offset:3072
	ds_read_b128 v[218:221], v158 offset:4096
	ds_read_b128 v[222:225], v158 offset:5120
	ds_read_b128 v[226:229], v158 offset:6144
	ds_read_b128 v[230:233], v158 offset:7168
	global_load_lds_dwordx4 v[182:183], off
	v_lshl_add_u64 v[182:183], s[40:41], 0, v[140:141]
	s_add_i32 m0, s49, 0xe000
	s_nop 0
	global_load_lds_dwordx4 v[182:183], off
	s_waitcnt vmcnt(8) lgkmcnt(0)
	s_barrier
	s_setprio 1
	v_mfma_f32_16x16x32_bf16 v[126:129], v[166:169], v[202:205], v[126:129]
	v_mfma_f32_16x16x32_bf16 v[118:121], v[174:177], v[202:205], v[118:121]
	v_mfma_f32_16x16x32_bf16 v[110:113], v[166:169], v[210:213], v[110:113]
	v_mfma_f32_16x16x32_bf16 v[102:105], v[174:177], v[210:213], v[102:105]
	v_mfma_f32_16x16x32_bf16 v[94:97], v[166:169], v[218:221], v[94:97]
	v_mfma_f32_16x16x32_bf16 v[86:89], v[174:177], v[218:221], v[86:89]
	v_mfma_f32_16x16x32_bf16 v[78:81], v[166:169], v[226:229], v[78:81]
	v_mfma_f32_16x16x32_bf16 v[70:73], v[174:177], v[226:229], v[70:73]
	v_mfma_f32_16x16x32_bf16 v[126:129], v[170:173], v[206:209], v[126:129]
	v_mfma_f32_16x16x32_bf16 v[118:121], v[178:181], v[206:209], v[118:121]
	v_mfma_f32_16x16x32_bf16 v[110:113], v[170:173], v[214:217], v[110:113]
	v_mfma_f32_16x16x32_bf16 v[102:105], v[178:181], v[214:217], v[102:105]
	v_mfma_f32_16x16x32_bf16 v[94:97], v[170:173], v[222:225], v[94:97]
	v_mfma_f32_16x16x32_bf16 v[86:89], v[178:181], v[222:225], v[86:89]
	v_mfma_f32_16x16x32_bf16 v[78:81], v[170:173], v[230:233], v[78:81]
	v_mfma_f32_16x16x32_bf16 v[70:73], v[178:181], v[230:233], v[70:73]
	v_mfma_f32_16x16x32_bf16 v[122:125], v[186:189], v[202:205], v[122:125]
	v_mfma_f32_16x16x32_bf16 v[114:117], v[194:197], v[202:205], v[114:117]
	v_mfma_f32_16x16x32_bf16 v[106:109], v[186:189], v[210:213], v[106:109]
	v_mfma_f32_16x16x32_bf16 v[98:101], v[194:197], v[210:213], v[98:101]
	v_mfma_f32_16x16x32_bf16 v[90:93], v[186:189], v[218:221], v[90:93]
	v_mfma_f32_16x16x32_bf16 v[82:85], v[194:197], v[218:221], v[82:85]
	v_mfma_f32_16x16x32_bf16 v[74:77], v[186:189], v[226:229], v[74:77]
	v_mfma_f32_16x16x32_bf16 v[66:69], v[194:197], v[226:229], v[66:69]
	v_mfma_f32_16x16x32_bf16 v[122:125], v[190:193], v[206:209], v[122:125]
	v_mfma_f32_16x16x32_bf16 v[114:117], v[198:201], v[206:209], v[114:117]
	v_mfma_f32_16x16x32_bf16 v[106:109], v[190:193], v[214:217], v[106:109]
	v_mfma_f32_16x16x32_bf16 v[98:101], v[198:201], v[214:217], v[98:101]
	v_mfma_f32_16x16x32_bf16 v[90:93], v[190:193], v[222:225], v[90:93]
	v_mfma_f32_16x16x32_bf16 v[82:85], v[198:201], v[222:225], v[82:85]
	v_mfma_f32_16x16x32_bf16 v[74:77], v[190:193], v[230:233], v[74:77]
	v_mfma_f32_16x16x32_bf16 v[66:69], v[198:201], v[230:233], v[66:69]
	s_setprio 0
	s_barrier
	s_add_i32 s66, s57, s46
	v_lshl_add_u64 v[182:183], s[42:43], 0, v[134:135]
	s_mov_b32 m0, s66
	ds_read_b128 v[202:205], v158 offset:16384
	ds_read_b128 v[206:209], v158 offset:17408
	ds_read_b128 v[210:213], v158 offset:18432
	ds_read_b128 v[214:217], v158 offset:19456
	ds_read_b128 v[218:221], v158 offset:20480
	ds_read_b128 v[222:225], v158 offset:21504
	ds_read_b128 v[226:229], v158 offset:22528
	ds_read_b128 v[230:233], v158 offset:23552
	global_load_lds_dwordx4 v[182:183], off
	s_add_i32 m0, s66, 0x2000
	s_add_u32 s66, s42, 0x40000
	v_lshl_add_u64 v[234:235], s[42:43], 0, v[130:131]
	s_addc_u32 s67, s43, 0
	s_add_i32 s68, s58, s46
	global_load_lds_dwordx4 v[234:235], off
	v_lshl_add_u64 v[236:237], s[66:67], 0, v[134:135]
	s_mov_b32 m0, s68
	v_lshl_add_u64 v[238:239], s[44:45], 0, v[132:133]
	global_load_lds_dwordx4 v[236:237], off
	v_lshl_add_u64 v[236:237], s[66:67], 0, v[130:131]
	s_add_i32 m0, s68, 0x2000
	s_nop 0
	global_load_lds_dwordx4 v[236:237], off
	v_lshl_add_u64 v[236:237], s[44:45], 0, v[136:137]
	s_mov_b32 m0, s49
	s_nop 0
	global_load_lds_dwordx4 v[236:237], off
	s_mov_b32 m0, s50
	s_nop 0
	global_load_lds_dwordx4 v[238:239], off
	s_waitcnt vmcnt(8) lgkmcnt(0)
	s_barrier
; #define PG8_STAGE(bufoff, gbase, voff) do { _Pragma("unroll") for (int _i = 0; _i < 2; ++_i) \
;         __builtin_amdgcn_global_load_lds((const unsigned*)((const char*)(gbase) + (voff)[_i]), (LAS unsigned*)(lds + (bufoff) + ldsw + _i * 8192), 16, 0, 0); } while (0)
; #define PG8_LDA(dst, b, h) do { _Pragma("unroll") for (int m = 0; m < 4; ++m) _Pragma("unroll") for (int k = 0; k < 2; ++k) dst[m][k] = *(const LAS bf16x8*)(lds + PG8_SA(b, h) + aoff + m * 2048 + k * 1024); } while (0)
; #define PG8_LDB(dst, b, h) do { _Pragma("unroll") for (int n = 0; n < 2; ++n) _Pragma("unroll") for (int k = 0; k < 2; ++k) dst[n][k] = *(const LAS bf16x8*)(lds + PG8_SB(b, h) + boff + n * 2048 + k * 1024); } while (0)
; #define PG8_MMA(ai, bj, At, Bt) do { __builtin_amdgcn_s_setprio(1); _Pragma("unroll") for (int m = 0; m < 4; ++m) _Pragma("unroll") for (int n = 0; n < 2; ++n) _Pragma("unroll") for (int k = 0; k < 2; ++k) \
;         acc[ai][bj][m][n] = __builtin_amdgcn_mfma_f32_16x16x32_bf16(Bt[n][k], At[m][k], acc[ai][bj][m][n], 0, 0, 0); __builtin_amdgcn_s_setprio(0); } while (0)
; #define PG8_WAIT_V(n) asm volatile("s_waitcnt vmcnt(" #n ")" ::: "memory")
; #define PG8_WAIT_L(n) asm volatile("s_waitcnt lgkmcnt(" #n ")" ::: "memory")
; #define PG8_BAR __builtin_amdgcn_s_barrier()
; #define PG8_SCHED __builtin_amdgcn_sched_barrier(0)
; template <class Epi, class Sched>
; DI void gemm_phase(LAS unsigned char* lds, const Gemm g, const Sched& S, const Epi& E) {
;     ...
;             PG8_WAIT_V(8); PG8_WAIT_L(0); PG8_BAR; PG8_MMA(0, 0, At, B0); PG8_MMA(0, 1, At, B1); PG8_BAR; PG8_SCHED;
;             PG8_LDA(At, 0, 1); PG8_STAGE(PG8_SB(0, 0), b2, voffB); PG8_STAGE(PG8_SB(0, 1), b2 + hstepB, voffB); PG8_STAGE(PG8_SA(0, 0), a2, voffA);
;             PG8_WAIT_V(8); PG8_WAIT_L(0); PG8_BAR; PG8_MMA(1, 0, At, B0); PG8_MMA(1, 1, At, B1); PG8_BAR; PG8_SCHED;
;             PG8_LDB(B0, 1, 0); PG8_LDB(B1, 1, 1); PG8_SCHED; PG8_LDA(At, 1, 0); PG8_STAGE(PG8_SA(0, 1), a2 + hstepA, voffA);
;             PG8_WAIT_V(8); PG8_WAIT_L(0); PG8_BAR; PG8_MMA(0, 0, At, B0); PG8_MMA(0, 1, At, B1); PG8_BAR; PG8_SCHED;
	s_setprio 1
	v_mfma_f32_16x16x32_bf16 v[62:65], v[166:169], v[202:205], v[62:65]
	v_mfma_f32_16x16x32_bf16 v[54:57], v[174:177], v[202:205], v[54:57]
	v_mfma_f32_16x16x32_bf16 v[46:49], v[166:169], v[210:213], v[46:49]
	v_mfma_f32_16x16x32_bf16 v[38:41], v[174:177], v[210:213], v[38:41]
	v_mfma_f32_16x16x32_bf16 v[30:33], v[166:169], v[218:221], v[30:33]
	v_mfma_f32_16x16x32_bf16 v[22:25], v[174:177], v[218:221], v[22:25]
	v_mfma_f32_16x16x32_bf16 v[14:17], v[166:169], v[226:229], v[14:17]
	v_mfma_f32_16x16x32_bf16 v[6:9], v[174:177], v[226:229], v[6:9]
	v_mfma_f32_16x16x32_bf16 v[62:65], v[170:173], v[206:209], v[62:65]
	v_mfma_f32_16x16x32_bf16 v[54:57], v[178:181], v[206:209], v[54:57]
	v_mfma_f32_16x16x32_bf16 v[46:49], v[170:173], v[214:217], v[46:49]
	v_mfma_f32_16x16x32_bf16 v[38:41], v[178:181], v[214:217], v[38:41]
	v_mfma_f32_16x16x32_bf16 v[30:33], v[170:173], v[222:225], v[30:33]
	v_mfma_f32_16x16x32_bf16 v[22:25], v[178:181], v[222:225], v[22:25]
	v_mfma_f32_16x16x32_bf16 v[14:17], v[170:173], v[230:233], v[14:17]
	v_mfma_f32_16x16x32_bf16 v[6:9], v[178:181], v[230:233], v[6:9]
	v_mfma_f32_16x16x32_bf16 v[58:61], v[186:189], v[202:205], v[58:61]
	v_mfma_f32_16x16x32_bf16 v[50:53], v[194:197], v[202:205], v[50:53]
	v_mfma_f32_16x16x32_bf16 v[42:45], v[186:189], v[210:213], v[42:45]
	v_mfma_f32_16x16x32_bf16 v[34:37], v[194:197], v[210:213], v[34:37]
	v_mfma_f32_16x16x32_bf16 v[26:29], v[186:189], v[218:221], v[26:29]
	v_mfma_f32_16x16x32_bf16 v[18:21], v[194:197], v[218:221], v[18:21]
	v_mfma_f32_16x16x32_bf16 v[10:13], v[186:189], v[226:229], v[10:13]
	v_mfma_f32_16x16x32_bf16 v[2:5], v[194:197], v[226:229], v[2:5]
	v_mfma_f32_16x16x32_bf16 v[58:61], v[190:193], v[206:209], v[58:61]
	v_mfma_f32_16x16x32_bf16 v[50:53], v[198:201], v[206:209], v[50:53]
	v_mfma_f32_16x16x32_bf16 v[42:45], v[190:193], v[214:217], v[42:45]
	v_mfma_f32_16x16x32_bf16 v[34:37], v[198:201], v[214:217], v[34:37]
	v_mfma_f32_16x16x32_bf16 v[26:29], v[190:193], v[222:225], v[26:29]
	v_mfma_f32_16x16x32_bf16 v[18:21], v[198:201], v[222:225], v[18:21]
	v_mfma_f32_16x16x32_bf16 v[10:13], v[190:193], v[230:233], v[10:13]
	v_mfma_f32_16x16x32_bf16 v[2:5], v[198:201], v[230:233], v[2:5]
	s_setprio 0
	s_barrier
	s_add_i32 s66, 0, 0x18000
	v_add_u32_e32 v165, s66, v156
	s_add_i32 s67, 0, 0x1c000
	ds_read_b128 v[166:169], v165
	ds_read_b128 v[170:173], v165 offset:1024
	ds_read_b128 v[174:177], v165 offset:2048
	ds_read_b128 v[178:181], v165 offset:3072
	v_add_u32_e32 v165, s67, v156
	ds_read_b128 v[186:189], v165
	ds_read_b128 v[190:193], v165 offset:1024
	ds_read_b128 v[194:197], v165 offset:2048
	ds_read_b128 v[198:201], v165 offset:3072
	s_add_u32 s44, s44, 0x40000
	s_addc_u32 s45, s45, 0
	s_mov_b32 m0, s51
	v_lshl_add_u64 v[240:241], s[44:45], 0, v[136:137]
	ds_read_b128 v[202:205], v158 offset:32768
	ds_read_b128 v[206:209], v158 offset:33792
	ds_read_b128 v[210:213], v158 offset:34816
	ds_read_b128 v[214:217], v158 offset:35840
	ds_read_b128 v[218:221], v158 offset:36864
	ds_read_b128 v[222:225], v158 offset:37888
	ds_read_b128 v[226:229], v158 offset:38912
	ds_read_b128 v[230:233], v158 offset:39936
	global_load_lds_dwordx4 v[240:241], off
	v_lshl_add_u64 v[240:241], s[44:45], 0, v[132:133]
	s_mov_b32 m0, s52
	s_nop 0
	global_load_lds_dwordx4 v[240:241], off
	s_waitcnt vmcnt(8) lgkmcnt(0)
	s_barrier
	s_setprio 1
	v_mfma_f32_16x16x32_bf16 v[126:129], v[166:169], v[202:205], v[126:129]
	v_mfma_f32_16x16x32_bf16 v[118:121], v[174:177], v[202:205], v[118:121]
	v_mfma_f32_16x16x32_bf16 v[110:113], v[166:169], v[210:213], v[110:113]
	v_mfma_f32_16x16x32_bf16 v[102:105], v[174:177], v[210:213], v[102:105]
	v_mfma_f32_16x16x32_bf16 v[94:97], v[166:169], v[218:221], v[94:97]
	v_mfma_f32_16x16x32_bf16 v[86:89], v[174:177], v[218:221], v[86:89]
	v_mfma_f32_16x16x32_bf16 v[78:81], v[166:169], v[226:229], v[78:81]
	v_mfma_f32_16x16x32_bf16 v[70:73], v[174:177], v[226:229], v[70:73]
	v_mfma_f32_16x16x32_bf16 v[126:129], v[170:173], v[206:209], v[126:129]
	v_mfma_f32_16x16x32_bf16 v[118:121], v[178:181], v[206:209], v[118:121]
	v_mfma_f32_16x16x32_bf16 v[110:113], v[170:173], v[214:217], v[110:113]
	v_mfma_f32_16x16x32_bf16 v[102:105], v[178:181], v[214:217], v[102:105]
	v_mfma_f32_16x16x32_bf16 v[94:97], v[170:173], v[222:225], v[94:97]
	v_mfma_f32_16x16x32_bf16 v[86:89], v[178:181], v[222:225], v[86:89]
	v_mfma_f32_16x16x32_bf16 v[78:81], v[170:173], v[230:233], v[78:81]
	v_mfma_f32_16x16x32_bf16 v[70:73], v[178:181], v[230:233], v[70:73]
	v_mfma_f32_16x16x32_bf16 v[122:125], v[186:189], v[202:205], v[122:125]
	v_mfma_f32_16x16x32_bf16 v[114:117], v[194:197], v[202:205], v[114:117]
	v_mfma_f32_16x16x32_bf16 v[106:109], v[186:189], v[210:213], v[106:109]
	v_mfma_f32_16x16x32_bf16 v[98:101], v[194:197], v[210:213], v[98:101]
	v_mfma_f32_16x16x32_bf16 v[90:93], v[186:189], v[218:221], v[90:93]
	v_mfma_f32_16x16x32_bf16 v[82:85], v[194:197], v[218:221], v[82:85]
	v_mfma_f32_16x16x32_bf16 v[74:77], v[186:189], v[226:229], v[74:77]
	v_mfma_f32_16x16x32_bf16 v[66:69], v[194:197], v[226:229], v[66:69]
	v_mfma_f32_16x16x32_bf16 v[122:125], v[190:193], v[206:209], v[122:125]
	v_mfma_f32_16x16x32_bf16 v[114:117], v[198:201], v[206:209], v[114:117]
	v_mfma_f32_16x16x32_bf16 v[106:109], v[190:193], v[214:217], v[106:109]
	v_mfma_f32_16x16x32_bf16 v[98:101], v[198:201], v[214:217], v[98:101]
	v_mfma_f32_16x16x32_bf16 v[90:93], v[190:193], v[222:225], v[90:93]
	v_mfma_f32_16x16x32_bf16 v[82:85], v[198:201], v[222:225], v[82:85]
	v_mfma_f32_16x16x32_bf16 v[74:77], v[190:193], v[230:233], v[74:77]
	v_mfma_f32_16x16x32_bf16 v[66:69], v[198:201], v[230:233], v[66:69]
	s_setprio 0
	s_barrier
; #define PG8_STAGE(bufoff, gbase, voff) do { _Pragma("unroll") for (int _i = 0; _i < 2; ++_i) \
;         __builtin_amdgcn_global_load_lds((const unsigned*)((const char*)(gbase) + (voff)[_i]), (LAS unsigned*)(lds + (bufoff) + ldsw + _i * 8192), 16, 0, 0); } while (0)
; #define PG8_LDA(dst, b, h) do { _Pragma("unroll") for (int m = 0; m < 4; ++m) _Pragma("unroll") for (int k = 0; k < 2; ++k) dst[m][k] = *(const LAS bf16x8*)(lds + PG8_SA(b, h) + aoff + m * 2048 + k * 1024); } while (0)
; #define PG8_MMA(ai, bj, At, Bt) do { __builtin_amdgcn_s_setprio(1); _Pragma("unroll") for (int m = 0; m < 4; ++m) _Pragma("unroll") for (int n = 0; n < 2; ++n) _Pragma("unroll") for (int k = 0; k < 2; ++k) \
;         acc[ai][bj][m][n] = __builtin_amdgcn_mfma_f32_16x16x32_bf16(Bt[n][k], At[m][k], acc[ai][bj][m][n], 0, 0, 0); __builtin_amdgcn_s_setprio(0); } while (0)
; #define PG8_WAIT_V(n) asm volatile("s_waitcnt vmcnt(" #n ")" ::: "memory")
; #define PG8_WAIT_L(n) asm volatile("s_waitcnt lgkmcnt(" #n ")" ::: "memory")
; #define PG8_BAR __builtin_amdgcn_s_barrier()
; #define PG8_SCHED __builtin_amdgcn_sched_barrier(0)
; template <class Epi, class Sched>
; DI void gemm_phase(LAS unsigned char* lds, const Gemm g, const Sched& S, const Epi& E) {
;     ...
;             PG8_LDA(At, 1, 1); PG8_STAGE(PG8_SB(1, 0), b3, voffB); PG8_STAGE(PG8_SB(1, 1), b3 + hstepB, voffB); PG8_STAGE(PG8_SA(1, 0), a3, voffA);
;             PG8_WAIT_V(8); PG8_WAIT_L(0); PG8_BAR; PG8_MMA(1, 0, At, B0); PG8_MMA(1, 1, At, B1); PG8_BAR; PG8_SCHED;
;         }
;         if (wr == 0) PG8_BAR;
	s_add_i32 s44, s66, s46
	v_lshl_add_u64 v[182:183], v[182:183], 0, s[16:17]
	s_mov_b32 m0, s44
	ds_read_b128 v[202:205], v158 offset:49152
	ds_read_b128 v[206:209], v158 offset:50176
	ds_read_b128 v[210:213], v158 offset:51200
	ds_read_b128 v[214:217], v158 offset:52224
	ds_read_b128 v[218:221], v158 offset:53248
	ds_read_b128 v[222:225], v158 offset:54272
	ds_read_b128 v[226:229], v158 offset:55296
	ds_read_b128 v[230:233], v158 offset:56320
	global_load_lds_dwordx4 v[182:183], off
	s_add_i32 m0, s44, 0x2000
	s_add_u32 s42, s42, 0x40080
	v_lshl_add_u64 v[182:183], v[234:235], 0, s[16:17]
	s_addc_u32 s43, s43, 0
	s_add_i32 s44, s67, s46
	global_load_lds_dwordx4 v[182:183], off
	v_lshl_add_u64 v[182:183], s[42:43], 0, v[134:135]
	s_mov_b32 m0, s44
	s_nop 0
	global_load_lds_dwordx4 v[182:183], off
	v_lshl_add_u64 v[182:183], s[42:43], 0, v[130:131]
	s_add_i32 m0, s44, 0x2000
	s_nop 0
	global_load_lds_dwordx4 v[182:183], off
	v_lshl_add_u64 v[182:183], v[236:237], 0, s[16:17]
	s_mov_b32 m0, s54
	s_nop 0
	global_load_lds_dwordx4 v[182:183], off
	v_lshl_add_u64 v[182:183], v[238:239], 0, s[16:17]
	s_mov_b32 m0, s55
	s_nop 0
	global_load_lds_dwordx4 v[182:183], off
	s_waitcnt vmcnt(8) lgkmcnt(0)
	s_barrier
	s_setprio 1
	v_mfma_f32_16x16x32_bf16 v[62:65], v[166:169], v[202:205], v[62:65]
	v_mfma_f32_16x16x32_bf16 v[54:57], v[174:177], v[202:205], v[54:57]
	v_mfma_f32_16x16x32_bf16 v[46:49], v[166:169], v[210:213], v[46:49]
	v_mfma_f32_16x16x32_bf16 v[38:41], v[174:177], v[210:213], v[38:41]
	v_mfma_f32_16x16x32_bf16 v[30:33], v[166:169], v[218:221], v[30:33]
	v_mfma_f32_16x16x32_bf16 v[22:25], v[174:177], v[218:221], v[22:25]
	v_mfma_f32_16x16x32_bf16 v[14:17], v[166:169], v[226:229], v[14:17]
	v_mfma_f32_16x16x32_bf16 v[6:9], v[174:177], v[226:229], v[6:9]
	v_mfma_f32_16x16x32_bf16 v[62:65], v[170:173], v[206:209], v[62:65]
	v_mfma_f32_16x16x32_bf16 v[54:57], v[178:181], v[206:209], v[54:57]
	v_mfma_f32_16x16x32_bf16 v[46:49], v[170:173], v[214:217], v[46:49]
	v_mfma_f32_16x16x32_bf16 v[38:41], v[178:181], v[214:217], v[38:41]
	v_mfma_f32_16x16x32_bf16 v[30:33], v[170:173], v[222:225], v[30:33]
	v_mfma_f32_16x16x32_bf16 v[22:25], v[178:181], v[222:225], v[22:25]
	v_mfma_f32_16x16x32_bf16 v[14:17], v[170:173], v[230:233], v[14:17]
	v_mfma_f32_16x16x32_bf16 v[6:9], v[178:181], v[230:233], v[6:9]
	v_mfma_f32_16x16x32_bf16 v[58:61], v[186:189], v[202:205], v[58:61]
	v_mfma_f32_16x16x32_bf16 v[50:53], v[194:197], v[202:205], v[50:53]
	v_mfma_f32_16x16x32_bf16 v[42:45], v[186:189], v[210:213], v[42:45]
	v_mfma_f32_16x16x32_bf16 v[34:37], v[194:197], v[210:213], v[34:37]
	v_mfma_f32_16x16x32_bf16 v[26:29], v[186:189], v[218:221], v[26:29]
	v_mfma_f32_16x16x32_bf16 v[18:21], v[194:197], v[218:221], v[18:21]
	v_mfma_f32_16x16x32_bf16 v[10:13], v[186:189], v[226:229], v[10:13]
	v_mfma_f32_16x16x32_bf16 v[2:5], v[194:197], v[226:229], v[2:5]
	v_mfma_f32_16x16x32_bf16 v[58:61], v[190:193], v[206:209], v[58:61]
	v_mfma_f32_16x16x32_bf16 v[50:53], v[198:201], v[206:209], v[50:53]
	v_mfma_f32_16x16x32_bf16 v[42:45], v[190:193], v[214:217], v[42:45]
	v_mfma_f32_16x16x32_bf16 v[34:37], v[198:201], v[214:217], v[34:37]
	v_mfma_f32_16x16x32_bf16 v[26:29], v[190:193], v[222:225], v[26:29]
	v_mfma_f32_16x16x32_bf16 v[18:21], v[198:201], v[222:225], v[18:21]
	v_mfma_f32_16x16x32_bf16 v[10:13], v[190:193], v[230:233], v[10:13]
	v_mfma_f32_16x16x32_bf16 v[2:5], v[198:201], v[230:233], v[2:5]
	s_setprio 0
	s_barrier
	s_add_i32 s65, s65, 2
	s_add_u32 s40, s40, 0x100
	s_addc_u32 s41, s41, 0
	s_add_u32 s63, s63, 0x100
	s_addc_u32 s64, s64, 0
	s_cmp_gt_u32 s65, 13
	s_cbranch_scc0 .LBB0_1234
	s_and_b64 vcc, exec, s[18:19]
	s_cbranch_vccz .LBB0_1237
	s_barrier

; #define PG8_STAGE(bufoff, gbase, voff) do { _Pragma("unroll") for (int _i = 0; _i < 2; ++_i) \
;         __builtin_amdgcn_global_load_lds((const unsigned*)((const char*)(gbase) + (voff)[_i]), (LAS unsigned*)(lds + (bufoff) + ldsw + _i * 8192), 16, 0, 0); } while (0)
; #define PG8_LDA(dst, b, h) do { _Pragma("unroll") for (int m = 0; m < 4; ++m) _Pragma("unroll") for (int k = 0; k < 2; ++k) dst[m][k] = *(const LAS bf16x8*)(lds + PG8_SA(b, h) + aoff + m * 2048 + k * 1024); } while (0)
; #define PG8_LDB(dst, b, h) do { _Pragma("unroll") for (int n = 0; n < 2; ++n) _Pragma("unroll") for (int k = 0; k < 2; ++k) dst[n][k] = *(const LAS bf16x8*)(lds + PG8_SB(b, h) + boff + n * 2048 + k * 1024); } while (0)
; #define PG8_MMA(ai, bj, At, Bt) do { __builtin_amdgcn_s_setprio(1); _Pragma("unroll") for (int m = 0; m < 4; ++m) _Pragma("unroll") for (int n = 0; n < 2; ++n) _Pragma("unroll") for (int k = 0; k < 2; ++k) \
;         acc[ai][bj][m][n] = __builtin_amdgcn_mfma_f32_16x16x32_bf16(Bt[n][k], At[m][k], acc[ai][bj][m][n], 0, 0, 0); __builtin_amdgcn_s_setprio(0); } while (0)
; #define PG8_WAIT_V(n) asm volatile("s_waitcnt vmcnt(" #n ")" ::: "memory")
; #define PG8_WAIT_L(n) asm volatile("s_waitcnt lgkmcnt(" #n ")" ::: "memory")
; #define PG8_BAR __builtin_amdgcn_s_barrier()
; #define PG8_SCHED __builtin_amdgcn_sched_barrier(0)
; template <class Epi, class Sched>
; DI void gemm_phase(LAS unsigned char* lds, const Gemm g, const Sched& S, const Epi& E) {
;     ...
;         for (int t = 0; t < nt; t += 2) {
;             const bool last = (t == nt - 2);
;             const char* a1 = cA + (size_t)(t + 1) * kstep;
;             const char* a2 = last ? nA : cA + (size_t)(t + 2) * kstep; const char* b2 = last ? nB : cB + (size_t)(t + 2) * kstep;
;             const char* a3 = a2 + kstep; const char* b3 = b2 + kstep;
;             PG8_LDB(B0, 0, 0); PG8_LDB(B1, 0, 1); PG8_SCHED; PG8_LDA(At, 0, 0); PG8_STAGE(PG8_SA(1, 1), a1 + hstepA, voffA);
;             PG8_WAIT_V(8); PG8_WAIT_L(0); PG8_BAR; PG8_MMA(0, 0, At, B0); PG8_MMA(0, 1, At, B1); PG8_BAR; PG8_SCHED;
.LBB0_1331:
	ds_read_b128 v[144:147], v151
	ds_read_b128 v[154:157], v151 offset:1024
	ds_read_b128 v[158:161], v151 offset:2048
	ds_read_b128 v[162:165], v151 offset:3072
	ds_read_b128 v[166:169], v152
	ds_read_b128 v[170:173], v152 offset:1024
	ds_read_b128 v[174:177], v152 offset:2048
	ds_read_b128 v[178:181], v152 offset:3072
	s_add_u32 s18, s16, 0xfff50080
	s_addc_u32 s19, s17, -1
	s_cmp_eq_u32 s47, 40
	s_cselect_b32 s21, s5, s19
	s_cselect_b32 s20, s4, s18
	s_cselect_b32 s19, s15, s46
	s_cselect_b32 s18, s14, s45
	v_lshl_add_u64 v[214:215], s[16:17], 0, v[136:137]
	s_add_i32 m0, s28, 0xc000
	ds_read_b128 v[182:185], v153
	ds_read_b128 v[186:189], v153 offset:1024
	ds_read_b128 v[190:193], v153 offset:2048
	ds_read_b128 v[194:197], v153 offset:3072
	ds_read_b128 v[198:201], v153 offset:4096
	ds_read_b128 v[202:205], v153 offset:5120
	ds_read_b128 v[206:209], v153 offset:6144
	ds_read_b128 v[210:213], v153 offset:7168
	global_load_lds_dwordx4 v[214:215], off
	v_lshl_add_u64 v[214:215], s[16:17], 0, v[138:139]
	s_add_i32 m0, s28, 0xe000
	s_nop 0
	global_load_lds_dwordx4 v[214:215], off
	s_waitcnt vmcnt(8) lgkmcnt(0)
	s_barrier
	s_setprio 1
	v_mfma_f32_16x16x32_bf16 v[124:127], v[144:147], v[182:185], v[124:127]
	v_mfma_f32_16x16x32_bf16 v[120:123], v[158:161], v[182:185], v[120:123]
	v_mfma_f32_16x16x32_bf16 v[108:111], v[144:147], v[190:193], v[108:111]
	v_mfma_f32_16x16x32_bf16 v[104:107], v[158:161], v[190:193], v[104:107]
	v_mfma_f32_16x16x32_bf16 v[92:95], v[144:147], v[198:201], v[92:95]
	v_mfma_f32_16x16x32_bf16 v[88:91], v[158:161], v[198:201], v[88:91]
	v_mfma_f32_16x16x32_bf16 v[76:79], v[144:147], v[206:209], v[76:79]
	v_mfma_f32_16x16x32_bf16 v[72:75], v[158:161], v[206:209], v[72:75]
	v_mfma_f32_16x16x32_bf16 v[124:127], v[154:157], v[186:189], v[124:127]
	v_mfma_f32_16x16x32_bf16 v[120:123], v[162:165], v[186:189], v[120:123]
	v_mfma_f32_16x16x32_bf16 v[108:111], v[154:157], v[194:197], v[108:111]
	v_mfma_f32_16x16x32_bf16 v[104:107], v[162:165], v[194:197], v[104:107]
	v_mfma_f32_16x16x32_bf16 v[92:95], v[154:157], v[202:205], v[92:95]
	v_mfma_f32_16x16x32_bf16 v[88:91], v[162:165], v[202:205], v[88:91]
	v_mfma_f32_16x16x32_bf16 v[76:79], v[154:157], v[210:213], v[76:79]
	v_mfma_f32_16x16x32_bf16 v[72:75], v[162:165], v[210:213], v[72:75]
	v_mfma_f32_16x16x32_bf16 v[116:119], v[166:169], v[182:185], v[116:119]
	v_mfma_f32_16x16x32_bf16 v[112:115], v[174:177], v[182:185], v[112:115]
	v_mfma_f32_16x16x32_bf16 v[100:103], v[166:169], v[190:193], v[100:103]
	v_mfma_f32_16x16x32_bf16 v[96:99], v[174:177], v[190:193], v[96:99]
	v_mfma_f32_16x16x32_bf16 v[84:87], v[166:169], v[198:201], v[84:87]
	v_mfma_f32_16x16x32_bf16 v[80:83], v[174:177], v[198:201], v[80:83]
	v_mfma_f32_16x16x32_bf16 v[68:71], v[166:169], v[206:209], v[68:71]
	v_mfma_f32_16x16x32_bf16 v[64:67], v[174:177], v[206:209], v[64:67]
	v_mfma_f32_16x16x32_bf16 v[116:119], v[170:173], v[186:189], v[116:119]
	v_mfma_f32_16x16x32_bf16 v[112:115], v[178:181], v[186:189], v[112:115]
	v_mfma_f32_16x16x32_bf16 v[100:103], v[170:173], v[194:197], v[100:103]
	v_mfma_f32_16x16x32_bf16 v[96:99], v[178:181], v[194:197], v[96:99]
	v_mfma_f32_16x16x32_bf16 v[84:87], v[170:173], v[202:205], v[84:87]
	v_mfma_f32_16x16x32_bf16 v[80:83], v[178:181], v[202:205], v[80:83]
	v_mfma_f32_16x16x32_bf16 v[68:71], v[170:173], v[210:213], v[68:71]
	v_mfma_f32_16x16x32_bf16 v[64:67], v[178:181], v[210:213], v[64:67]
	s_setprio 0
	s_barrier
	s_add_i32 s48, s39, s27
	v_lshl_add_u64 v[214:215], s[18:19], 0, v[130:131]
	s_mov_b32 m0, s48
	ds_read_b128 v[182:185], v153 offset:16384
	ds_read_b128 v[186:189], v153 offset:17408
	ds_read_b128 v[190:193], v153 offset:18432
	ds_read_b128 v[194:197], v153 offset:19456
	ds_read_b128 v[198:201], v153 offset:20480
	ds_read_b128 v[202:205], v153 offset:21504
	ds_read_b128 v[206:209], v153 offset:22528
	ds_read_b128 v[210:213], v153 offset:23552
	global_load_lds_dwordx4 v[214:215], off
	s_add_i32 m0, s48, 0x2000
	s_add_u32 s48, s18, 0xb0000
	v_lshl_add_u64 v[216:217], s[18:19], 0, v[134:135]
	s_addc_u32 s49, s19, 0
	s_add_i32 s50, s40, s27
	global_load_lds_dwordx4 v[216:217], off
	v_lshl_add_u64 v[218:219], s[48:49], 0, v[130:131]
	s_mov_b32 m0, s50
	v_lshl_add_u64 v[220:221], s[20:21], 0, v[132:133]
	global_load_lds_dwordx4 v[218:219], off
	v_lshl_add_u64 v[218:219], s[48:49], 0, v[134:135]
	s_add_i32 m0, s50, 0x2000
	s_nop 0
	global_load_lds_dwordx4 v[218:219], off
	v_lshl_add_u64 v[218:219], s[20:21], 0, v[128:129]
	s_mov_b32 m0, s28
	s_nop 0
	global_load_lds_dwordx4 v[218:219], off
	s_mov_b32 m0, s29
	s_nop 0
	global_load_lds_dwordx4 v[220:221], off
	s_waitcnt vmcnt(8) lgkmcnt(0)
	s_barrier
; #define PG8_STAGE(bufoff, gbase, voff) do { _Pragma("unroll") for (int _i = 0; _i < 2; ++_i) \
;         __builtin_amdgcn_global_load_lds((const unsigned*)((const char*)(gbase) + (voff)[_i]), (LAS unsigned*)(lds + (bufoff) + ldsw + _i * 8192), 16, 0, 0); } while (0)
; #define PG8_LDA(dst, b, h) do { _Pragma("unroll") for (int m = 0; m < 4; ++m) _Pragma("unroll") for (int k = 0; k < 2; ++k) dst[m][k] = *(const LAS bf16x8*)(lds + PG8_SA(b, h) + aoff + m * 2048 + k * 1024); } while (0)
; #define PG8_LDB(dst, b, h) do { _Pragma("unroll") for (int n = 0; n < 2; ++n) _Pragma("unroll") for (int k = 0; k < 2; ++k) dst[n][k] = *(const LAS bf16x8*)(lds + PG8_SB(b, h) + boff + n * 2048 + k * 1024); } while (0)
; #define PG8_MMA(ai, bj, At, Bt) do { __builtin_amdgcn_s_setprio(1); _Pragma("unroll") for (int m = 0; m < 4; ++m) _Pragma("unroll") for (int n = 0; n < 2; ++n) _Pragma("unroll") for (int k = 0; k < 2; ++k) \
;         acc[ai][bj][m][n] = __builtin_amdgcn_mfma_f32_16x16x32_bf16(Bt[n][k], At[m][k], acc[ai][bj][m][n], 0, 0, 0); __builtin_amdgcn_s_setprio(0); } while (0)
; #define PG8_WAIT_V(n) asm volatile("s_waitcnt vmcnt(" #n ")" ::: "memory")
; #define PG8_WAIT_L(n) asm volatile("s_waitcnt lgkmcnt(" #n ")" ::: "memory")
; #define PG8_BAR __builtin_amdgcn_s_barrier()
; #define PG8_SCHED __builtin_amdgcn_sched_barrier(0)
; template <class Epi, class Sched>
; DI void gemm_phase(LAS unsigned char* lds, const Gemm g, const Sched& S, const Epi& E) {
;     ...
;             PG8_WAIT_V(8); PG8_WAIT_L(0); PG8_BAR; PG8_MMA(0, 0, At, B0); PG8_MMA(0, 1, At, B1); PG8_BAR; PG8_SCHED;
;             PG8_LDA(At, 0, 1); PG8_STAGE(PG8_SB(0, 0), b2, voffB); PG8_STAGE(PG8_SB(0, 1), b2 + hstepB, voffB); PG8_STAGE(PG8_SA(0, 0), a2, voffA);
;             PG8_WAIT_V(8); PG8_WAIT_L(0); PG8_BAR; PG8_MMA(1, 0, At, B0); PG8_MMA(1, 1, At, B1); PG8_BAR; PG8_SCHED;
;             PG8_LDB(B0, 1, 0); PG8_LDB(B1, 1, 1); PG8_SCHED; PG8_LDA(At, 1, 0); PG8_STAGE(PG8_SA(0, 1), a2 + hstepA, voffA);
;             PG8_WAIT_V(8); PG8_WAIT_L(0); PG8_BAR; PG8_MMA(0, 0, At, B0); PG8_MMA(0, 1, At, B1); PG8_BAR; PG8_SCHED;
	s_setprio 1
	v_mfma_f32_16x16x32_bf16 v[60:63], v[144:147], v[182:185], v[60:63]
	v_mfma_f32_16x16x32_bf16 v[56:59], v[158:161], v[182:185], v[56:59]
	v_mfma_f32_16x16x32_bf16 v[44:47], v[144:147], v[190:193], v[44:47]
	v_mfma_f32_16x16x32_bf16 v[40:43], v[158:161], v[190:193], v[40:43]
	v_mfma_f32_16x16x32_bf16 v[28:31], v[144:147], v[198:201], v[28:31]
	v_mfma_f32_16x16x32_bf16 v[24:27], v[158:161], v[198:201], v[24:27]
	v_mfma_f32_16x16x32_bf16 v[12:15], v[144:147], v[206:209], v[12:15]
	v_mfma_f32_16x16x32_bf16 v[8:11], v[158:161], v[206:209], v[8:11]
	v_mfma_f32_16x16x32_bf16 v[60:63], v[154:157], v[186:189], v[60:63]
	v_mfma_f32_16x16x32_bf16 v[56:59], v[162:165], v[186:189], v[56:59]
	v_mfma_f32_16x16x32_bf16 v[44:47], v[154:157], v[194:197], v[44:47]
	v_mfma_f32_16x16x32_bf16 v[40:43], v[162:165], v[194:197], v[40:43]
	v_mfma_f32_16x16x32_bf16 v[28:31], v[154:157], v[202:205], v[28:31]
	v_mfma_f32_16x16x32_bf16 v[24:27], v[162:165], v[202:205], v[24:27]
	v_mfma_f32_16x16x32_bf16 v[12:15], v[154:157], v[210:213], v[12:15]
	v_mfma_f32_16x16x32_bf16 v[8:11], v[162:165], v[210:213], v[8:11]
	v_mfma_f32_16x16x32_bf16 v[52:55], v[166:169], v[182:185], v[52:55]
	v_mfma_f32_16x16x32_bf16 v[48:51], v[174:177], v[182:185], v[48:51]
	v_mfma_f32_16x16x32_bf16 v[36:39], v[166:169], v[190:193], v[36:39]
	v_mfma_f32_16x16x32_bf16 v[32:35], v[174:177], v[190:193], v[32:35]
	v_mfma_f32_16x16x32_bf16 v[20:23], v[166:169], v[198:201], v[20:23]
	v_mfma_f32_16x16x32_bf16 v[16:19], v[174:177], v[198:201], v[16:19]
	v_mfma_f32_16x16x32_bf16 v[4:7], v[166:169], v[206:209], v[4:7]
	v_mfma_f32_16x16x32_bf16 v[0:3], v[174:177], v[206:209], v[0:3]
	v_mfma_f32_16x16x32_bf16 v[52:55], v[170:173], v[186:189], v[52:55]
	v_mfma_f32_16x16x32_bf16 v[48:51], v[178:181], v[186:189], v[48:51]
	v_mfma_f32_16x16x32_bf16 v[36:39], v[170:173], v[194:197], v[36:39]
	v_mfma_f32_16x16x32_bf16 v[32:35], v[178:181], v[194:197], v[32:35]
	v_mfma_f32_16x16x32_bf16 v[20:23], v[170:173], v[202:205], v[20:23]
	v_mfma_f32_16x16x32_bf16 v[16:19], v[178:181], v[202:205], v[16:19]
	v_mfma_f32_16x16x32_bf16 v[4:7], v[170:173], v[210:213], v[4:7]
	v_mfma_f32_16x16x32_bf16 v[0:3], v[178:181], v[210:213], v[0:3]
	s_setprio 0
	s_barrier
	s_add_i32 s48, 0, 0x18000
	s_add_i32 s49, 0, 0x1c000
	v_add_u32_e32 v162, s48, v149
	v_add_u32_e32 v178, s49, v149
	ds_read_b128 v[144:147], v162
	ds_read_b128 v[154:157], v162 offset:1024
	ds_read_b128 v[158:161], v162 offset:2048
	ds_read_b128 v[162:165], v162 offset:3072
	ds_read_b128 v[166:169], v178
	ds_read_b128 v[170:173], v178 offset:1024
	ds_read_b128 v[174:177], v178 offset:2048
	ds_read_b128 v[178:181], v178 offset:3072
	s_add_u32 s20, s20, 0xb0000
	s_addc_u32 s21, s21, 0
	s_mov_b32 m0, s33
	v_lshl_add_u64 v[222:223], s[20:21], 0, v[128:129]
	ds_read_b128 v[182:185], v153 offset:32768
	ds_read_b128 v[186:189], v153 offset:33792
	ds_read_b128 v[190:193], v153 offset:34816
	ds_read_b128 v[194:197], v153 offset:35840
	ds_read_b128 v[198:201], v153 offset:36864
	ds_read_b128 v[202:205], v153 offset:37888
	ds_read_b128 v[206:209], v153 offset:38912
	ds_read_b128 v[210:213], v153 offset:39936
	global_load_lds_dwordx4 v[222:223], off
	v_lshl_add_u64 v[222:223], s[20:21], 0, v[132:133]
	s_mov_b32 m0, s34
	s_nop 0
	global_load_lds_dwordx4 v[222:223], off
	s_waitcnt vmcnt(8) lgkmcnt(0)
	s_barrier
	s_setprio 1
	v_mfma_f32_16x16x32_bf16 v[124:127], v[144:147], v[182:185], v[124:127]
	v_mfma_f32_16x16x32_bf16 v[120:123], v[158:161], v[182:185], v[120:123]
	v_mfma_f32_16x16x32_bf16 v[108:111], v[144:147], v[190:193], v[108:111]
	v_mfma_f32_16x16x32_bf16 v[104:107], v[158:161], v[190:193], v[104:107]
	v_mfma_f32_16x16x32_bf16 v[92:95], v[144:147], v[198:201], v[92:95]
	v_mfma_f32_16x16x32_bf16 v[88:91], v[158:161], v[198:201], v[88:91]
	v_mfma_f32_16x16x32_bf16 v[76:79], v[144:147], v[206:209], v[76:79]
	v_mfma_f32_16x16x32_bf16 v[72:75], v[158:161], v[206:209], v[72:75]
	v_mfma_f32_16x16x32_bf16 v[124:127], v[154:157], v[186:189], v[124:127]
	v_mfma_f32_16x16x32_bf16 v[120:123], v[162:165], v[186:189], v[120:123]
	v_mfma_f32_16x16x32_bf16 v[108:111], v[154:157], v[194:197], v[108:111]
	v_mfma_f32_16x16x32_bf16 v[104:107], v[162:165], v[194:197], v[104:107]
	v_mfma_f32_16x16x32_bf16 v[92:95], v[154:157], v[202:205], v[92:95]
	v_mfma_f32_16x16x32_bf16 v[88:91], v[162:165], v[202:205], v[88:91]
	v_mfma_f32_16x16x32_bf16 v[76:79], v[154:157], v[210:213], v[76:79]
	v_mfma_f32_16x16x32_bf16 v[72:75], v[162:165], v[210:213], v[72:75]
	v_mfma_f32_16x16x32_bf16 v[116:119], v[166:169], v[182:185], v[116:119]
	v_mfma_f32_16x16x32_bf16 v[112:115], v[174:177], v[182:185], v[112:115]
	v_mfma_f32_16x16x32_bf16 v[100:103], v[166:169], v[190:193], v[100:103]
	v_mfma_f32_16x16x32_bf16 v[96:99], v[174:177], v[190:193], v[96:99]
	v_mfma_f32_16x16x32_bf16 v[84:87], v[166:169], v[198:201], v[84:87]
	v_mfma_f32_16x16x32_bf16 v[80:83], v[174:177], v[198:201], v[80:83]
	v_mfma_f32_16x16x32_bf16 v[68:71], v[166:169], v[206:209], v[68:71]
	v_mfma_f32_16x16x32_bf16 v[64:67], v[174:177], v[206:209], v[64:67]
	v_mfma_f32_16x16x32_bf16 v[116:119], v[170:173], v[186:189], v[116:119]
	v_mfma_f32_16x16x32_bf16 v[112:115], v[178:181], v[186:189], v[112:115]
	v_mfma_f32_16x16x32_bf16 v[100:103], v[170:173], v[194:197], v[100:103]
	v_mfma_f32_16x16x32_bf16 v[96:99], v[178:181], v[194:197], v[96:99]
	v_mfma_f32_16x16x32_bf16 v[84:87], v[170:173], v[202:205], v[84:87]
	v_mfma_f32_16x16x32_bf16 v[80:83], v[178:181], v[202:205], v[80:83]
	v_mfma_f32_16x16x32_bf16 v[68:71], v[170:173], v[210:213], v[68:71]
	v_mfma_f32_16x16x32_bf16 v[64:67], v[178:181], v[210:213], v[64:67]
	s_setprio 0
	s_barrier
; #define PG8_STAGE(bufoff, gbase, voff) do { _Pragma("unroll") for (int _i = 0; _i < 2; ++_i) \
;         __builtin_amdgcn_global_load_lds((const unsigned*)((const char*)(gbase) + (voff)[_i]), (LAS unsigned*)(lds + (bufoff) + ldsw + _i * 8192), 16, 0, 0); } while (0)
; #define PG8_LDA(dst, b, h) do { _Pragma("unroll") for (int m = 0; m < 4; ++m) _Pragma("unroll") for (int k = 0; k < 2; ++k) dst[m][k] = *(const LAS bf16x8*)(lds + PG8_SA(b, h) + aoff + m * 2048 + k * 1024); } while (0)
; #define PG8_MMA(ai, bj, At, Bt) do { __builtin_amdgcn_s_setprio(1); _Pragma("unroll") for (int m = 0; m < 4; ++m) _Pragma("unroll") for (int n = 0; n < 2; ++n) _Pragma("unroll") for (int k = 0; k < 2; ++k) \
;         acc[ai][bj][m][n] = __builtin_amdgcn_mfma_f32_16x16x32_bf16(Bt[n][k], At[m][k], acc[ai][bj][m][n], 0, 0, 0); __builtin_amdgcn_s_setprio(0); } while (0)
; #define PG8_WAIT_V(n) asm volatile("s_waitcnt vmcnt(" #n ")" ::: "memory")
; #define PG8_WAIT_L(n) asm volatile("s_waitcnt lgkmcnt(" #n ")" ::: "memory")
; #define PG8_BAR __builtin_amdgcn_s_barrier()
; #define PG8_SCHED __builtin_amdgcn_sched_barrier(0)
; template <class Epi, class Sched>
; DI void gemm_phase(LAS unsigned char* lds, const Gemm g, const Sched& S, const Epi& E) {
;     ...
;             PG8_LDA(At, 1, 1); PG8_STAGE(PG8_SB(1, 0), b3, voffB); PG8_STAGE(PG8_SB(1, 1), b3 + hstepB, voffB); PG8_STAGE(PG8_SA(1, 0), a3, voffA);
;             PG8_WAIT_V(8); PG8_WAIT_L(0); PG8_BAR; PG8_MMA(1, 0, At, B0); PG8_MMA(1, 1, At, B1); PG8_BAR; PG8_SCHED;
;         }
;         if (wr == 0) PG8_BAR;
	s_add_i32 s20, s48, s27
	v_lshl_add_u64 v[214:215], v[214:215], 0, s[10:11]
	s_mov_b32 m0, s20
	ds_read_b128 v[182:185], v153 offset:49152
	ds_read_b128 v[186:189], v153 offset:50176
	ds_read_b128 v[190:193], v153 offset:51200
	ds_read_b128 v[194:197], v153 offset:52224
	ds_read_b128 v[198:201], v153 offset:53248
	ds_read_b128 v[202:205], v153 offset:54272
	ds_read_b128 v[206:209], v153 offset:55296
	ds_read_b128 v[210:213], v153 offset:56320
	global_load_lds_dwordx4 v[214:215], off
	s_add_i32 m0, s20, 0x2000
	s_add_u32 s18, s18, 0xb0080
	v_lshl_add_u64 v[214:215], v[216:217], 0, s[10:11]
	s_addc_u32 s19, s19, 0
	s_add_i32 s20, s49, s27
	global_load_lds_dwordx4 v[214:215], off
	v_lshl_add_u64 v[214:215], s[18:19], 0, v[130:131]
	s_mov_b32 m0, s20
	s_nop 0
	global_load_lds_dwordx4 v[214:215], off
	v_lshl_add_u64 v[214:215], s[18:19], 0, v[134:135]
	s_add_i32 m0, s20, 0x2000
	s_nop 0
	global_load_lds_dwordx4 v[214:215], off
	v_lshl_add_u64 v[214:215], v[218:219], 0, s[10:11]
	s_mov_b32 m0, s36
	s_nop 0
	global_load_lds_dwordx4 v[214:215], off
	v_lshl_add_u64 v[214:215], v[220:221], 0, s[10:11]
	s_mov_b32 m0, s37
	s_nop 0
	global_load_lds_dwordx4 v[214:215], off
	s_waitcnt vmcnt(8) lgkmcnt(0)
	s_barrier
	s_setprio 1
	v_mfma_f32_16x16x32_bf16 v[60:63], v[144:147], v[182:185], v[60:63]
	v_mfma_f32_16x16x32_bf16 v[56:59], v[158:161], v[182:185], v[56:59]
	v_mfma_f32_16x16x32_bf16 v[44:47], v[144:147], v[190:193], v[44:47]
	v_mfma_f32_16x16x32_bf16 v[40:43], v[158:161], v[190:193], v[40:43]
	v_mfma_f32_16x16x32_bf16 v[28:31], v[144:147], v[198:201], v[28:31]
	v_mfma_f32_16x16x32_bf16 v[24:27], v[158:161], v[198:201], v[24:27]
	v_mfma_f32_16x16x32_bf16 v[12:15], v[144:147], v[206:209], v[12:15]
	v_mfma_f32_16x16x32_bf16 v[8:11], v[158:161], v[206:209], v[8:11]
	v_mfma_f32_16x16x32_bf16 v[60:63], v[154:157], v[186:189], v[60:63]
	v_mfma_f32_16x16x32_bf16 v[56:59], v[162:165], v[186:189], v[56:59]
	v_mfma_f32_16x16x32_bf16 v[44:47], v[154:157], v[194:197], v[44:47]
	v_mfma_f32_16x16x32_bf16 v[40:43], v[162:165], v[194:197], v[40:43]
	v_mfma_f32_16x16x32_bf16 v[28:31], v[154:157], v[202:205], v[28:31]
	v_mfma_f32_16x16x32_bf16 v[24:27], v[162:165], v[202:205], v[24:27]
	v_mfma_f32_16x16x32_bf16 v[12:15], v[154:157], v[210:213], v[12:15]
	v_mfma_f32_16x16x32_bf16 v[8:11], v[162:165], v[210:213], v[8:11]
	v_mfma_f32_16x16x32_bf16 v[52:55], v[166:169], v[182:185], v[52:55]
	v_mfma_f32_16x16x32_bf16 v[48:51], v[174:177], v[182:185], v[48:51]
	v_mfma_f32_16x16x32_bf16 v[36:39], v[166:169], v[190:193], v[36:39]
	v_mfma_f32_16x16x32_bf16 v[32:35], v[174:177], v[190:193], v[32:35]
	v_mfma_f32_16x16x32_bf16 v[20:23], v[166:169], v[198:201], v[20:23]
	v_mfma_f32_16x16x32_bf16 v[16:19], v[174:177], v[198:201], v[16:19]
	v_mfma_f32_16x16x32_bf16 v[4:7], v[166:169], v[206:209], v[4:7]
	v_mfma_f32_16x16x32_bf16 v[0:3], v[174:177], v[206:209], v[0:3]
	v_mfma_f32_16x16x32_bf16 v[52:55], v[170:173], v[186:189], v[52:55]
	v_mfma_f32_16x16x32_bf16 v[48:51], v[178:181], v[186:189], v[48:51]
	v_mfma_f32_16x16x32_bf16 v[36:39], v[170:173], v[194:197], v[36:39]
	v_mfma_f32_16x16x32_bf16 v[32:35], v[178:181], v[194:197], v[32:35]
	v_mfma_f32_16x16x32_bf16 v[20:23], v[170:173], v[202:205], v[20:23]
	v_mfma_f32_16x16x32_bf16 v[16:19], v[178:181], v[202:205], v[16:19]
	v_mfma_f32_16x16x32_bf16 v[4:7], v[170:173], v[210:213], v[4:7]
	v_mfma_f32_16x16x32_bf16 v[0:3], v[178:181], v[210:213], v[0:3]
	s_setprio 0
	s_barrier
	s_add_i32 s47, s47, 2
	s_add_u32 s16, s16, 0x100
	s_addc_u32 s17, s17, 0
	s_add_u32 s45, s45, 0x100
	s_addc_u32 s46, s46, 0
	s_cmp_gt_u32 s47, 41
	s_cbranch_scc0 .LBB0_1331
	s_and_b64 vcc, exec, s[12:13]
	s_cbranch_vccz .LBB0_1334
	s_barrier
